# scan waves: y reductions batched (one 16-lane reduce-scatter per 16 steps instead of 16 all-reduces; same summation tree)
# speedup vs baseline: 1.0094x; 1.0094x over previous
; __device__ void phase_scan(int l, unsigned char* lds) {
;     ...
;             for (int t8 = 0; t8 < (jb.nsteps < 16 ? jb.nsteps : 16); t8 += 4) {
; #pragma unroll
;                 for (int u = 0; u < 4; ++u) {
;                     const int tt = t8 + u;
;                     const unsigned char* tb = buf + tt * SC_TOKB + c0 * 4;
;                     const f32x4 a = *(const f32x4*)(tb), w = *(const f32x4*)(tb + 256), b = *(const f32x4*)(tb + 512), k = *(const f32x4*)(tb + 768), r = *(const f32x4*)(tb + 1024);
;                     const float v = *(const float*)(buf + tt * SC_TOKB + 1280 + rl * 4);
;                     const f32x2 a01 = (f32x2){a[0], a[1]}, a23 = (f32x2){a[2], a[3]}, w01 = (f32x2){w[0], w[1]}, w23 = (f32x2){w[2], w[3]}, b01 = (f32x2){b[0], b[1]}, b23 = (f32x2){b[2], b[3]};
;                     const f32x2 k01 = (f32x2){k[0], k[1]}, k23 = (f32x2){k[2], k[3]}, r01 = (f32x2){r[0], r[1]}, r23 = (f32x2){r[2], r[3]};
;                     const f32x2 pa = s01 * a01 + s23 * a23;
;                     const float sa = allsum16(pa.x + pa.y);
;                     const f32x2 kv01 = k01 * v, kv23 = k23 * v;
;                     s01 = s01 * w01 + (b01 * sa + kv01); s23 = s23 * w23 + (b23 * sa + kv23);
;                     const f32x2 py = s01 * r01 + s23 * r23;
;                     const float y = allsum16(py.x + py.y);
;                     if ((lane & 15) == (tt & 15)) yreg0 = y;
;                 }
.LBB0_532:
	s_mul_hi_u32 s9, s83, 0xaaaaaaab
	s_lshr_b32 s9, s9, 1
	s_mul_i32 s9, s9, 0xfffe0800
	s_xor_b64 s[20:21], s[20:21], -1
	v_add_u32_e32 v217, s9, v110
	v_add_u32_e32 v218, s9, v111
	v_mov_b32_e32 v18, 0
	v_mov_b32_e32 v26, 0
	s_cmp_eq_u32 s8, 32
	s_cbranch_scc0 .Lscan0_n8
	ds_read_b128 v[120:123], v217 offset:0
	ds_read_b128 v[124:127], v217 offset:256
	ds_read_b128 v[128:131], v217 offset:512
	ds_read_b128 v[132:135], v217 offset:768
	ds_read_b128 v[136:139], v217 offset:1024
	ds_read_b32 v28, v218 offset:0
	ds_read_b128 v[146:149], v217 offset:1344
	ds_read_b128 v[150:153], v217 offset:1600
	ds_read_b128 v[154:157], v217 offset:1856
	ds_read_b128 v[158:161], v217 offset:2112
	ds_read_b128 v[162:165], v217 offset:2368
	ds_read_b32 v30, v218 offset:1344
	s_waitcnt lgkmcnt(6)
	ds_read_b128 v[32:35], v217 offset:2688
	ds_read_b128 v[36:39], v217 offset:2944
	ds_read_b128 v[40:43], v217 offset:3200
	ds_read_b128 v[44:47], v217 offset:3456
	ds_read_b128 v[48:51], v217 offset:3712
	ds_read_b32 v92, v218 offset:2688
	v_pk_mul_f32 v[206:207], v[24:25], v[122:123]
	v_pk_fma_f32 v[206:207], v[22:23], v[120:121], v[206:207]
	s_nop 0
	v_add_f32_e32 v214, v206, v207
	s_nop 0
	v_pk_mul_f32 v[210:211], v[132:133], v[28:29] op_sel_hi:[1,0]
	v_add_f32_dpp v214, v214, v214 quad_perm:[1,0,3,2] row_mask:0xf bank_mask:0xf bound_ctrl:1
	s_nop 0
	v_pk_mul_f32 v[212:213], v[134:135], v[28:29] op_sel_hi:[1,0]
	v_add_f32_dpp v214, v214, v214 quad_perm:[2,3,0,1] row_mask:0xf bank_mask:0xf bound_ctrl:1
	v_pk_fma_f32 v[210:211], v[22:23], v[124:125], v[210:211]
	v_pk_fma_f32 v[212:213], v[24:25], v[126:127], v[212:213]
	v_add_f32_dpp v214, v214, v214 row_half_mirror row_mask:0xf bank_mask:0xf bound_ctrl:1
	s_nop 1
	v_add_f32_dpp v214, v214, v214 row_mirror row_mask:0xf bank_mask:0xf bound_ctrl:1
	v_pk_fma_f32 v[22:23], v[128:129], v[214:215], v[210:211] op_sel_hi:[1,0,1]
	v_pk_fma_f32 v[24:25], v[130:131], v[214:215], v[212:213] op_sel_hi:[1,0,1]
	s_waitcnt lgkmcnt(6)
	ds_read_b128 v[186:189], v217 offset:4032
	ds_read_b128 v[190:193], v217 offset:4288
	ds_read_b128 v[194:197], v217 offset:4544
	ds_read_b128 v[198:201], v217 offset:4800
	ds_read_b128 v[202:205], v217 offset:5056
	ds_read_b32 v52, v218 offset:4032
	v_pk_mul_f32 v[206:207], v[24:25], v[148:149]
	v_pk_fma_f32 v[206:207], v[22:23], v[146:147], v[206:207]
	v_pk_mul_f32 v[208:209], v[24:25], v[138:139]
	v_add_f32_e32 v214, v206, v207
	v_pk_fma_f32 v[208:209], v[22:23], v[136:137], v[208:209]
	v_pk_mul_f32 v[210:211], v[158:159], v[30:31] op_sel_hi:[1,0]
	v_add_f32_dpp v214, v214, v214 quad_perm:[1,0,3,2] row_mask:0xf bank_mask:0xf bound_ctrl:1
	v_add_f32_e32 v232, v208, v209
	v_pk_mul_f32 v[212:213], v[160:161], v[30:31] op_sel_hi:[1,0]
	v_add_f32_dpp v214, v214, v214 quad_perm:[2,3,0,1] row_mask:0xf bank_mask:0xf bound_ctrl:1
	v_pk_fma_f32 v[210:211], v[22:23], v[150:151], v[210:211]
	v_pk_fma_f32 v[212:213], v[24:25], v[152:153], v[212:213]
	v_add_f32_dpp v214, v214, v214 row_half_mirror row_mask:0xf bank_mask:0xf bound_ctrl:1
	s_nop 1
	v_add_f32_dpp v214, v214, v214 row_mirror row_mask:0xf bank_mask:0xf bound_ctrl:1
	v_pk_fma_f32 v[22:23], v[154:155], v[214:215], v[210:211] op_sel_hi:[1,0,1]
	v_pk_fma_f32 v[24:25], v[156:157], v[214:215], v[212:213] op_sel_hi:[1,0,1]
	s_waitcnt lgkmcnt(6)
	ds_read_b128 v[120:123], v217 offset:5376
	ds_read_b128 v[124:127], v217 offset:5632
	ds_read_b128 v[128:131], v217 offset:5888
	ds_read_b128 v[132:135], v217 offset:6144
	ds_read_b128 v[136:139], v217 offset:6400
	ds_read_b32 v28, v218 offset:5376
	v_pk_mul_f32 v[206:207], v[24:25], v[34:35]
	v_pk_fma_f32 v[206:207], v[22:23], v[32:33], v[206:207]
	v_pk_mul_f32 v[208:209], v[24:25], v[164:165]
	v_add_f32_e32 v214, v206, v207
	v_pk_fma_f32 v[208:209], v[22:23], v[162:163], v[208:209]
	v_pk_mul_f32 v[210:211], v[44:45], v[92:93] op_sel_hi:[1,0]
	v_add_f32_dpp v214, v214, v214 quad_perm:[1,0,3,2] row_mask:0xf bank_mask:0xf bound_ctrl:1
	v_add_f32_e32 v233, v208, v209
	v_pk_mul_f32 v[212:213], v[46:47], v[92:93] op_sel_hi:[1,0]
	v_add_f32_dpp v214, v214, v214 quad_perm:[2,3,0,1] row_mask:0xf bank_mask:0xf bound_ctrl:1
	v_pk_fma_f32 v[210:211], v[22:23], v[36:37], v[210:211]
	v_pk_fma_f32 v[212:213], v[24:25], v[38:39], v[212:213]
	v_add_f32_dpp v214, v214, v214 row_half_mirror row_mask:0xf bank_mask:0xf bound_ctrl:1
	s_nop 1
	v_add_f32_dpp v214, v214, v214 row_mirror row_mask:0xf bank_mask:0xf bound_ctrl:1
	v_pk_fma_f32 v[22:23], v[40:41], v[214:215], v[210:211] op_sel_hi:[1,0,1]
	v_pk_fma_f32 v[24:25], v[42:43], v[214:215], v[212:213] op_sel_hi:[1,0,1]
	s_waitcnt lgkmcnt(6)
	ds_read_b128 v[146:149], v217 offset:6720
	ds_read_b128 v[150:153], v217 offset:6976
	ds_read_b128 v[154:157], v217 offset:7232
	ds_read_b128 v[158:161], v217 offset:7488
	ds_read_b128 v[162:165], v217 offset:7744
	ds_read_b32 v30, v218 offset:6720
	v_pk_mul_f32 v[206:207], v[24:25], v[188:189]
	v_pk_fma_f32 v[206:207], v[22:23], v[186:187], v[206:207]
	v_pk_mul_f32 v[208:209], v[24:25], v[50:51]
	v_add_f32_e32 v214, v206, v207
	v_pk_fma_f32 v[208:209], v[22:23], v[48:49], v[208:209]
	v_pk_mul_f32 v[210:211], v[198:199], v[52:53] op_sel_hi:[1,0]
	v_add_f32_dpp v214, v214, v214 quad_perm:[1,0,3,2] row_mask:0xf bank_mask:0xf bound_ctrl:1
	v_add_f32_e32 v234, v208, v209
	v_pk_mul_f32 v[212:213], v[200:201], v[52:53] op_sel_hi:[1,0]
	v_add_f32_dpp v214, v214, v214 quad_perm:[2,3,0,1] row_mask:0xf bank_mask:0xf bound_ctrl:1
	v_pk_fma_f32 v[210:211], v[22:23], v[190:191], v[210:211]
	v_pk_fma_f32 v[212:213], v[24:25], v[192:193], v[212:213]
	v_add_f32_dpp v214, v214, v214 row_half_mirror row_mask:0xf bank_mask:0xf bound_ctrl:1
	s_nop 1
	v_add_f32_dpp v214, v214, v214 row_mirror row_mask:0xf bank_mask:0xf bound_ctrl:1
	v_pk_fma_f32 v[22:23], v[194:195], v[214:215], v[210:211] op_sel_hi:[1,0,1]
	v_pk_fma_f32 v[24:25], v[196:197], v[214:215], v[212:213] op_sel_hi:[1,0,1]
	s_waitcnt lgkmcnt(6)
; __device__ void phase_scan(int l, unsigned char* lds) {
;     ...
;                     const f32x4 a = *(const f32x4*)(tb), w = *(const f32x4*)(tb + 256), b = *(const f32x4*)(tb + 512), k = *(const f32x4*)(tb + 768), r = *(const f32x4*)(tb + 1024);
;                     const float v = *(const float*)(buf + tt * SC_TOKB + 1280 + rl * 4);
;                     const f32x2 a01 = (f32x2){a[0], a[1]}, a23 = (f32x2){a[2], a[3]}, w01 = (f32x2){w[0], w[1]}, w23 = (f32x2){w[2], w[3]}, b01 = (f32x2){b[0], b[1]}, b23 = (f32x2){b[2], b[3]};
;                     const f32x2 k01 = (f32x2){k[0], k[1]}, k23 = (f32x2){k[2], k[3]}, r01 = (f32x2){r[0], r[1]}, r23 = (f32x2){r[2], r[3]};
;                     const f32x2 pa = s01 * a01 + s23 * a23;
;                     const float sa = allsum16(pa.x + pa.y);
;                     const f32x2 kv01 = k01 * v, kv23 = k23 * v;
;                     s01 = s01 * w01 + (b01 * sa + kv01); s23 = s23 * w23 + (b23 * sa + kv23);
;                     const f32x2 py = s01 * r01 + s23 * r23;
;                     const float y = allsum16(py.x + py.y);
;                     if ((lane & 15) == (tt & 15)) yreg0 = y;
	ds_read_b128 v[32:35], v217 offset:8064
	ds_read_b128 v[36:39], v217 offset:8320
	ds_read_b128 v[40:43], v217 offset:8576
	ds_read_b128 v[44:47], v217 offset:8832
	ds_read_b128 v[48:51], v217 offset:9088
	ds_read_b32 v92, v218 offset:8064
	v_pk_mul_f32 v[206:207], v[24:25], v[122:123]
	v_pk_fma_f32 v[206:207], v[22:23], v[120:121], v[206:207]
	v_pk_mul_f32 v[208:209], v[24:25], v[204:205]
	v_add_f32_e32 v214, v206, v207
	v_pk_fma_f32 v[208:209], v[22:23], v[202:203], v[208:209]
	v_pk_mul_f32 v[210:211], v[132:133], v[28:29] op_sel_hi:[1,0]
	v_add_f32_dpp v214, v214, v214 quad_perm:[1,0,3,2] row_mask:0xf bank_mask:0xf bound_ctrl:1
	v_add_f32_e32 v235, v208, v209
	v_pk_mul_f32 v[212:213], v[134:135], v[28:29] op_sel_hi:[1,0]
	v_add_f32_dpp v214, v214, v214 quad_perm:[2,3,0,1] row_mask:0xf bank_mask:0xf bound_ctrl:1
	v_pk_fma_f32 v[210:211], v[22:23], v[124:125], v[210:211]
	v_pk_fma_f32 v[212:213], v[24:25], v[126:127], v[212:213]
	v_add_f32_dpp v214, v214, v214 row_half_mirror row_mask:0xf bank_mask:0xf bound_ctrl:1
	s_nop 1
	v_add_f32_dpp v214, v214, v214 row_mirror row_mask:0xf bank_mask:0xf bound_ctrl:1
	v_pk_fma_f32 v[22:23], v[128:129], v[214:215], v[210:211] op_sel_hi:[1,0,1]
	v_pk_fma_f32 v[24:25], v[130:131], v[214:215], v[212:213] op_sel_hi:[1,0,1]
	s_waitcnt lgkmcnt(6)
	ds_read_b128 v[186:189], v217 offset:9408
	ds_read_b128 v[190:193], v217 offset:9664
	ds_read_b128 v[194:197], v217 offset:9920
	ds_read_b128 v[198:201], v217 offset:10176
	ds_read_b128 v[202:205], v217 offset:10432
	ds_read_b32 v52, v218 offset:9408
	v_pk_mul_f32 v[206:207], v[24:25], v[148:149]
	v_pk_fma_f32 v[206:207], v[22:23], v[146:147], v[206:207]
	v_pk_mul_f32 v[208:209], v[24:25], v[138:139]
	v_add_f32_e32 v214, v206, v207
	v_pk_fma_f32 v[208:209], v[22:23], v[136:137], v[208:209]
	v_pk_mul_f32 v[210:211], v[158:159], v[30:31] op_sel_hi:[1,0]
	v_add_f32_dpp v214, v214, v214 quad_perm:[1,0,3,2] row_mask:0xf bank_mask:0xf bound_ctrl:1
	v_add_f32_e32 v236, v208, v209
	v_pk_mul_f32 v[212:213], v[160:161], v[30:31] op_sel_hi:[1,0]
	v_add_f32_dpp v214, v214, v214 quad_perm:[2,3,0,1] row_mask:0xf bank_mask:0xf bound_ctrl:1
	v_pk_fma_f32 v[210:211], v[22:23], v[150:151], v[210:211]
	v_pk_fma_f32 v[212:213], v[24:25], v[152:153], v[212:213]
	v_add_f32_dpp v214, v214, v214 row_half_mirror row_mask:0xf bank_mask:0xf bound_ctrl:1
	s_nop 1
	v_add_f32_dpp v214, v214, v214 row_mirror row_mask:0xf bank_mask:0xf bound_ctrl:1
	v_pk_fma_f32 v[22:23], v[154:155], v[214:215], v[210:211] op_sel_hi:[1,0,1]
	v_pk_fma_f32 v[24:25], v[156:157], v[214:215], v[212:213] op_sel_hi:[1,0,1]
	s_waitcnt lgkmcnt(6)
	ds_read_b128 v[120:123], v217 offset:10752
	ds_read_b128 v[124:127], v217 offset:11008
	ds_read_b128 v[128:131], v217 offset:11264
	ds_read_b128 v[132:135], v217 offset:11520
	ds_read_b128 v[136:139], v217 offset:11776
	ds_read_b32 v28, v218 offset:10752
	v_pk_mul_f32 v[206:207], v[24:25], v[34:35]
	v_pk_fma_f32 v[206:207], v[22:23], v[32:33], v[206:207]
	v_pk_mul_f32 v[208:209], v[24:25], v[164:165]
	v_add_f32_e32 v214, v206, v207
	v_pk_fma_f32 v[208:209], v[22:23], v[162:163], v[208:209]
	v_pk_mul_f32 v[210:211], v[44:45], v[92:93] op_sel_hi:[1,0]
	v_add_f32_dpp v214, v214, v214 quad_perm:[1,0,3,2] row_mask:0xf bank_mask:0xf bound_ctrl:1
	v_add_f32_e32 v237, v208, v209
	v_pk_mul_f32 v[212:213], v[46:47], v[92:93] op_sel_hi:[1,0]
	v_add_f32_dpp v214, v214, v214 quad_perm:[2,3,0,1] row_mask:0xf bank_mask:0xf bound_ctrl:1
	v_pk_fma_f32 v[210:211], v[22:23], v[36:37], v[210:211]
	v_pk_fma_f32 v[212:213], v[24:25], v[38:39], v[212:213]
	v_add_f32_dpp v214, v214, v214 row_half_mirror row_mask:0xf bank_mask:0xf bound_ctrl:1
	s_nop 1
	v_add_f32_dpp v214, v214, v214 row_mirror row_mask:0xf bank_mask:0xf bound_ctrl:1
	v_pk_fma_f32 v[22:23], v[40:41], v[214:215], v[210:211] op_sel_hi:[1,0,1]
	v_pk_fma_f32 v[24:25], v[42:43], v[214:215], v[212:213] op_sel_hi:[1,0,1]
	s_waitcnt lgkmcnt(6)
	ds_read_b128 v[146:149], v217 offset:12096
	ds_read_b128 v[150:153], v217 offset:12352
	ds_read_b128 v[154:157], v217 offset:12608
	ds_read_b128 v[158:161], v217 offset:12864
	ds_read_b128 v[162:165], v217 offset:13120
	ds_read_b32 v30, v218 offset:12096
	v_pk_mul_f32 v[206:207], v[24:25], v[188:189]
	v_pk_fma_f32 v[206:207], v[22:23], v[186:187], v[206:207]
	v_pk_mul_f32 v[208:209], v[24:25], v[50:51]
	v_add_f32_e32 v214, v206, v207
	v_pk_fma_f32 v[208:209], v[22:23], v[48:49], v[208:209]
	v_pk_mul_f32 v[210:211], v[198:199], v[52:53] op_sel_hi:[1,0]
	v_add_f32_dpp v214, v214, v214 quad_perm:[1,0,3,2] row_mask:0xf bank_mask:0xf bound_ctrl:1
	v_add_f32_e32 v238, v208, v209
	v_pk_mul_f32 v[212:213], v[200:201], v[52:53] op_sel_hi:[1,0]
	v_add_f32_dpp v214, v214, v214 quad_perm:[2,3,0,1] row_mask:0xf bank_mask:0xf bound_ctrl:1
	v_pk_fma_f32 v[210:211], v[22:23], v[190:191], v[210:211]
	v_pk_fma_f32 v[212:213], v[24:25], v[192:193], v[212:213]
	v_add_f32_dpp v214, v214, v214 row_half_mirror row_mask:0xf bank_mask:0xf bound_ctrl:1
	s_nop 1
	v_add_f32_dpp v214, v214, v214 row_mirror row_mask:0xf bank_mask:0xf bound_ctrl:1
	v_pk_fma_f32 v[22:23], v[194:195], v[214:215], v[210:211] op_sel_hi:[1,0,1]
	v_pk_fma_f32 v[24:25], v[196:197], v[214:215], v[212:213] op_sel_hi:[1,0,1]
	s_waitcnt lgkmcnt(6)
; __device__ void phase_scan(int l, unsigned char* lds) {
;     ...
;                     const f32x4 a = *(const f32x4*)(tb), w = *(const f32x4*)(tb + 256), b = *(const f32x4*)(tb + 512), k = *(const f32x4*)(tb + 768), r = *(const f32x4*)(tb + 1024);
;                     const float v = *(const float*)(buf + tt * SC_TOKB + 1280 + rl * 4);
;                     const f32x2 a01 = (f32x2){a[0], a[1]}, a23 = (f32x2){a[2], a[3]}, w01 = (f32x2){w[0], w[1]}, w23 = (f32x2){w[2], w[3]}, b01 = (f32x2){b[0], b[1]}, b23 = (f32x2){b[2], b[3]};
;                     const f32x2 k01 = (f32x2){k[0], k[1]}, k23 = (f32x2){k[2], k[3]}, r01 = (f32x2){r[0], r[1]}, r23 = (f32x2){r[2], r[3]};
;                     const f32x2 pa = s01 * a01 + s23 * a23;
;                     const float sa = allsum16(pa.x + pa.y);
;                     const f32x2 kv01 = k01 * v, kv23 = k23 * v;
;                     s01 = s01 * w01 + (b01 * sa + kv01); s23 = s23 * w23 + (b23 * sa + kv23);
;                     const f32x2 py = s01 * r01 + s23 * r23;
;                     const float y = allsum16(py.x + py.y);
;                     if ((lane & 15) == (tt & 15)) yreg0 = y;
	ds_read_b128 v[32:35], v217 offset:13440
	ds_read_b128 v[36:39], v217 offset:13696
	ds_read_b128 v[40:43], v217 offset:13952
	ds_read_b128 v[44:47], v217 offset:14208
	ds_read_b128 v[48:51], v217 offset:14464
	ds_read_b32 v92, v218 offset:13440
	v_pk_mul_f32 v[206:207], v[24:25], v[122:123]
	v_pk_fma_f32 v[206:207], v[22:23], v[120:121], v[206:207]
	v_pk_mul_f32 v[208:209], v[24:25], v[204:205]
	v_add_f32_e32 v214, v206, v207
	v_pk_fma_f32 v[208:209], v[22:23], v[202:203], v[208:209]
	v_pk_mul_f32 v[210:211], v[132:133], v[28:29] op_sel_hi:[1,0]
	v_add_f32_dpp v214, v214, v214 quad_perm:[1,0,3,2] row_mask:0xf bank_mask:0xf bound_ctrl:1
	v_add_f32_e32 v239, v208, v209
	v_pk_mul_f32 v[212:213], v[134:135], v[28:29] op_sel_hi:[1,0]
	v_add_f32_dpp v214, v214, v214 quad_perm:[2,3,0,1] row_mask:0xf bank_mask:0xf bound_ctrl:1
	v_pk_fma_f32 v[210:211], v[22:23], v[124:125], v[210:211]
	v_pk_fma_f32 v[212:213], v[24:25], v[126:127], v[212:213]
	v_add_f32_dpp v214, v214, v214 row_half_mirror row_mask:0xf bank_mask:0xf bound_ctrl:1
	s_nop 1
	v_add_f32_dpp v214, v214, v214 row_mirror row_mask:0xf bank_mask:0xf bound_ctrl:1
	v_pk_fma_f32 v[22:23], v[128:129], v[214:215], v[210:211] op_sel_hi:[1,0,1]
	v_pk_fma_f32 v[24:25], v[130:131], v[214:215], v[212:213] op_sel_hi:[1,0,1]
	s_waitcnt lgkmcnt(6)
	ds_read_b128 v[186:189], v217 offset:14784
	ds_read_b128 v[190:193], v217 offset:15040
	ds_read_b128 v[194:197], v217 offset:15296
	ds_read_b128 v[198:201], v217 offset:15552
	ds_read_b128 v[202:205], v217 offset:15808
	ds_read_b32 v52, v218 offset:14784
	v_pk_mul_f32 v[206:207], v[24:25], v[148:149]
	v_pk_fma_f32 v[206:207], v[22:23], v[146:147], v[206:207]
	v_pk_mul_f32 v[208:209], v[24:25], v[138:139]
	v_add_f32_e32 v214, v206, v207
	v_pk_fma_f32 v[208:209], v[22:23], v[136:137], v[208:209]
	v_pk_mul_f32 v[210:211], v[158:159], v[30:31] op_sel_hi:[1,0]
	v_add_f32_dpp v214, v214, v214 quad_perm:[1,0,3,2] row_mask:0xf bank_mask:0xf bound_ctrl:1
	v_add_f32_e32 v240, v208, v209
	v_pk_mul_f32 v[212:213], v[160:161], v[30:31] op_sel_hi:[1,0]
	v_add_f32_dpp v214, v214, v214 quad_perm:[2,3,0,1] row_mask:0xf bank_mask:0xf bound_ctrl:1
	v_pk_fma_f32 v[210:211], v[22:23], v[150:151], v[210:211]
	v_pk_fma_f32 v[212:213], v[24:25], v[152:153], v[212:213]
	v_add_f32_dpp v214, v214, v214 row_half_mirror row_mask:0xf bank_mask:0xf bound_ctrl:1
	s_nop 1
	v_add_f32_dpp v214, v214, v214 row_mirror row_mask:0xf bank_mask:0xf bound_ctrl:1
	v_pk_fma_f32 v[22:23], v[154:155], v[214:215], v[210:211] op_sel_hi:[1,0,1]
	v_pk_fma_f32 v[24:25], v[156:157], v[214:215], v[212:213] op_sel_hi:[1,0,1]
	s_waitcnt lgkmcnt(6)
	ds_read_b128 v[120:123], v217 offset:16128
	ds_read_b128 v[124:127], v217 offset:16384
	ds_read_b128 v[128:131], v217 offset:16640
	ds_read_b128 v[132:135], v217 offset:16896
	ds_read_b128 v[136:139], v217 offset:17152
	ds_read_b32 v28, v218 offset:16128
	v_pk_mul_f32 v[206:207], v[24:25], v[34:35]
	v_pk_fma_f32 v[206:207], v[22:23], v[32:33], v[206:207]
	v_pk_mul_f32 v[208:209], v[24:25], v[164:165]
	v_add_f32_e32 v214, v206, v207
	v_pk_fma_f32 v[208:209], v[22:23], v[162:163], v[208:209]
	v_pk_mul_f32 v[210:211], v[44:45], v[92:93] op_sel_hi:[1,0]
	v_add_f32_dpp v214, v214, v214 quad_perm:[1,0,3,2] row_mask:0xf bank_mask:0xf bound_ctrl:1
	v_add_f32_e32 v241, v208, v209
	v_pk_mul_f32 v[212:213], v[46:47], v[92:93] op_sel_hi:[1,0]
	v_add_f32_dpp v214, v214, v214 quad_perm:[2,3,0,1] row_mask:0xf bank_mask:0xf bound_ctrl:1
	v_pk_fma_f32 v[210:211], v[22:23], v[36:37], v[210:211]
	v_pk_fma_f32 v[212:213], v[24:25], v[38:39], v[212:213]
	v_add_f32_dpp v214, v214, v214 row_half_mirror row_mask:0xf bank_mask:0xf bound_ctrl:1
	s_nop 1
	v_add_f32_dpp v214, v214, v214 row_mirror row_mask:0xf bank_mask:0xf bound_ctrl:1
	v_pk_fma_f32 v[22:23], v[40:41], v[214:215], v[210:211] op_sel_hi:[1,0,1]
	v_pk_fma_f32 v[24:25], v[42:43], v[214:215], v[212:213] op_sel_hi:[1,0,1]
	s_waitcnt lgkmcnt(6)
	ds_read_b128 v[146:149], v217 offset:17472
	ds_read_b128 v[150:153], v217 offset:17728
	ds_read_b128 v[154:157], v217 offset:17984
	ds_read_b128 v[158:161], v217 offset:18240
	ds_read_b128 v[162:165], v217 offset:18496
	ds_read_b32 v30, v218 offset:17472
	v_pk_mul_f32 v[206:207], v[24:25], v[188:189]
	v_pk_fma_f32 v[206:207], v[22:23], v[186:187], v[206:207]
	v_pk_mul_f32 v[208:209], v[24:25], v[50:51]
	v_add_f32_e32 v214, v206, v207
	v_pk_fma_f32 v[208:209], v[22:23], v[48:49], v[208:209]
	v_pk_mul_f32 v[210:211], v[198:199], v[52:53] op_sel_hi:[1,0]
	v_add_f32_dpp v214, v214, v214 quad_perm:[1,0,3,2] row_mask:0xf bank_mask:0xf bound_ctrl:1
	v_add_f32_e32 v242, v208, v209
	v_pk_mul_f32 v[212:213], v[200:201], v[52:53] op_sel_hi:[1,0]
	v_add_f32_dpp v214, v214, v214 quad_perm:[2,3,0,1] row_mask:0xf bank_mask:0xf bound_ctrl:1
	v_pk_fma_f32 v[210:211], v[22:23], v[190:191], v[210:211]
	v_pk_fma_f32 v[212:213], v[24:25], v[192:193], v[212:213]
	v_add_f32_dpp v214, v214, v214 row_half_mirror row_mask:0xf bank_mask:0xf bound_ctrl:1
	s_nop 1
	v_add_f32_dpp v214, v214, v214 row_mirror row_mask:0xf bank_mask:0xf bound_ctrl:1
	v_pk_fma_f32 v[22:23], v[194:195], v[214:215], v[210:211] op_sel_hi:[1,0,1]
	v_pk_fma_f32 v[24:25], v[196:197], v[214:215], v[212:213] op_sel_hi:[1,0,1]
	s_waitcnt lgkmcnt(6)
; __device__ void phase_scan(int l, unsigned char* lds) {
;     ...
;                     const f32x4 a = *(const f32x4*)(tb), w = *(const f32x4*)(tb + 256), b = *(const f32x4*)(tb + 512), k = *(const f32x4*)(tb + 768), r = *(const f32x4*)(tb + 1024);
;                     const float v = *(const float*)(buf + tt * SC_TOKB + 1280 + rl * 4);
;                     const f32x2 a01 = (f32x2){a[0], a[1]}, a23 = (f32x2){a[2], a[3]}, w01 = (f32x2){w[0], w[1]}, w23 = (f32x2){w[2], w[3]}, b01 = (f32x2){b[0], b[1]}, b23 = (f32x2){b[2], b[3]};
;                     const f32x2 k01 = (f32x2){k[0], k[1]}, k23 = (f32x2){k[2], k[3]}, r01 = (f32x2){r[0], r[1]}, r23 = (f32x2){r[2], r[3]};
;                     const f32x2 pa = s01 * a01 + s23 * a23;
;                     const float sa = allsum16(pa.x + pa.y);
;                     const f32x2 kv01 = k01 * v, kv23 = k23 * v;
;                     s01 = s01 * w01 + (b01 * sa + kv01); s23 = s23 * w23 + (b23 * sa + kv23);
;                     const f32x2 py = s01 * r01 + s23 * r23;
;                     const float y = allsum16(py.x + py.y);
;                     if ((lane & 15) == (tt & 15)) yreg0 = y;
	ds_read_b128 v[32:35], v217 offset:18816
	ds_read_b128 v[36:39], v217 offset:19072
	ds_read_b128 v[40:43], v217 offset:19328
	ds_read_b128 v[44:47], v217 offset:19584
	ds_read_b128 v[48:51], v217 offset:19840
	ds_read_b32 v92, v218 offset:18816
	v_pk_mul_f32 v[206:207], v[24:25], v[122:123]
	v_pk_fma_f32 v[206:207], v[22:23], v[120:121], v[206:207]
	v_pk_mul_f32 v[208:209], v[24:25], v[204:205]
	v_add_f32_e32 v214, v206, v207
	v_pk_fma_f32 v[208:209], v[22:23], v[202:203], v[208:209]
	v_pk_mul_f32 v[210:211], v[132:133], v[28:29] op_sel_hi:[1,0]
	v_add_f32_dpp v214, v214, v214 quad_perm:[1,0,3,2] row_mask:0xf bank_mask:0xf bound_ctrl:1
	v_add_f32_e32 v243, v208, v209
	v_pk_mul_f32 v[212:213], v[134:135], v[28:29] op_sel_hi:[1,0]
	v_add_f32_dpp v214, v214, v214 quad_perm:[2,3,0,1] row_mask:0xf bank_mask:0xf bound_ctrl:1
	v_pk_fma_f32 v[210:211], v[22:23], v[124:125], v[210:211]
	v_pk_fma_f32 v[212:213], v[24:25], v[126:127], v[212:213]
	v_add_f32_dpp v214, v214, v214 row_half_mirror row_mask:0xf bank_mask:0xf bound_ctrl:1
	s_nop 1
	v_add_f32_dpp v214, v214, v214 row_mirror row_mask:0xf bank_mask:0xf bound_ctrl:1
	v_pk_fma_f32 v[22:23], v[128:129], v[214:215], v[210:211] op_sel_hi:[1,0,1]
	v_pk_fma_f32 v[24:25], v[130:131], v[214:215], v[212:213] op_sel_hi:[1,0,1]
	s_waitcnt lgkmcnt(6)
	ds_read_b128 v[186:189], v217 offset:20160
	ds_read_b128 v[190:193], v217 offset:20416
	ds_read_b128 v[194:197], v217 offset:20672
	ds_read_b128 v[198:201], v217 offset:20928
	ds_read_b128 v[202:205], v217 offset:21184
	ds_read_b32 v52, v218 offset:20160
	v_pk_mul_f32 v[206:207], v[24:25], v[148:149]
	v_pk_fma_f32 v[206:207], v[22:23], v[146:147], v[206:207]
	v_pk_mul_f32 v[208:209], v[24:25], v[138:139]
	v_add_f32_e32 v214, v206, v207
	v_pk_fma_f32 v[208:209], v[22:23], v[136:137], v[208:209]
	v_pk_mul_f32 v[210:211], v[158:159], v[30:31] op_sel_hi:[1,0]
	v_add_f32_dpp v214, v214, v214 quad_perm:[1,0,3,2] row_mask:0xf bank_mask:0xf bound_ctrl:1
	v_add_f32_e32 v244, v208, v209
	v_pk_mul_f32 v[212:213], v[160:161], v[30:31] op_sel_hi:[1,0]
	v_add_f32_dpp v214, v214, v214 quad_perm:[2,3,0,1] row_mask:0xf bank_mask:0xf bound_ctrl:1
	v_pk_fma_f32 v[210:211], v[22:23], v[150:151], v[210:211]
	v_pk_fma_f32 v[212:213], v[24:25], v[152:153], v[212:213]
	v_add_f32_dpp v214, v214, v214 row_half_mirror row_mask:0xf bank_mask:0xf bound_ctrl:1
	s_nop 1
	v_add_f32_dpp v214, v214, v214 row_mirror row_mask:0xf bank_mask:0xf bound_ctrl:1
	v_pk_fma_f32 v[22:23], v[154:155], v[214:215], v[210:211] op_sel_hi:[1,0,1]
	v_pk_fma_f32 v[24:25], v[156:157], v[214:215], v[212:213] op_sel_hi:[1,0,1]
	s_waitcnt lgkmcnt(6)
	ds_read_b128 v[120:123], v217 offset:21504
	ds_read_b128 v[124:127], v217 offset:21760
	ds_read_b128 v[128:131], v217 offset:22016
	ds_read_b128 v[132:135], v217 offset:22272
	ds_read_b128 v[136:139], v217 offset:22528
	ds_read_b32 v28, v218 offset:21504
	v_pk_mul_f32 v[206:207], v[24:25], v[34:35]
	v_pk_fma_f32 v[206:207], v[22:23], v[32:33], v[206:207]
	v_pk_mul_f32 v[208:209], v[24:25], v[164:165]
	v_add_f32_e32 v214, v206, v207
	v_pk_fma_f32 v[208:209], v[22:23], v[162:163], v[208:209]
	v_pk_mul_f32 v[210:211], v[44:45], v[92:93] op_sel_hi:[1,0]
	v_add_f32_dpp v214, v214, v214 quad_perm:[1,0,3,2] row_mask:0xf bank_mask:0xf bound_ctrl:1
	v_add_f32_e32 v245, v208, v209
	v_pk_mul_f32 v[212:213], v[46:47], v[92:93] op_sel_hi:[1,0]
	v_add_f32_dpp v214, v214, v214 quad_perm:[2,3,0,1] row_mask:0xf bank_mask:0xf bound_ctrl:1
	v_pk_fma_f32 v[210:211], v[22:23], v[36:37], v[210:211]
	v_pk_fma_f32 v[212:213], v[24:25], v[38:39], v[212:213]
	v_add_f32_dpp v214, v214, v214 row_half_mirror row_mask:0xf bank_mask:0xf bound_ctrl:1
	s_nop 1
	v_add_f32_dpp v214, v214, v214 row_mirror row_mask:0xf bank_mask:0xf bound_ctrl:1
	v_pk_fma_f32 v[22:23], v[40:41], v[214:215], v[210:211] op_sel_hi:[1,0,1]
	v_pk_fma_f32 v[24:25], v[42:43], v[214:215], v[212:213] op_sel_hi:[1,0,1]
	s_waitcnt lgkmcnt(6)
	ds_read_b128 v[146:149], v217 offset:22848
	ds_read_b128 v[150:153], v217 offset:23104
	ds_read_b128 v[154:157], v217 offset:23360
	ds_read_b128 v[158:161], v217 offset:23616
	ds_read_b128 v[162:165], v217 offset:23872
	ds_read_b32 v30, v218 offset:22848
	v_pk_mul_f32 v[206:207], v[24:25], v[188:189]
	v_pk_fma_f32 v[206:207], v[22:23], v[186:187], v[206:207]
	v_pk_mul_f32 v[208:209], v[24:25], v[50:51]
	v_add_f32_e32 v214, v206, v207
	v_pk_fma_f32 v[208:209], v[22:23], v[48:49], v[208:209]
	v_pk_mul_f32 v[210:211], v[198:199], v[52:53] op_sel_hi:[1,0]
	v_add_f32_dpp v214, v214, v214 quad_perm:[1,0,3,2] row_mask:0xf bank_mask:0xf bound_ctrl:1
	v_add_f32_e32 v246, v208, v209
	v_pk_mul_f32 v[212:213], v[200:201], v[52:53] op_sel_hi:[1,0]
	v_add_f32_dpp v214, v214, v214 quad_perm:[2,3,0,1] row_mask:0xf bank_mask:0xf bound_ctrl:1
	v_pk_fma_f32 v[210:211], v[22:23], v[190:191], v[210:211]
	v_pk_fma_f32 v[212:213], v[24:25], v[192:193], v[212:213]
	v_add_f32_dpp v214, v214, v214 row_half_mirror row_mask:0xf bank_mask:0xf bound_ctrl:1
	s_nop 1
	v_add_f32_dpp v214, v214, v214 row_mirror row_mask:0xf bank_mask:0xf bound_ctrl:1
	v_pk_fma_f32 v[22:23], v[194:195], v[214:215], v[210:211] op_sel_hi:[1,0,1]
	v_pk_fma_f32 v[24:25], v[196:197], v[214:215], v[212:213] op_sel_hi:[1,0,1]
	s_waitcnt lgkmcnt(6)
; __device__ void phase_scan(int l, unsigned char* lds) {
;     ...
;                     const f32x4 a = *(const f32x4*)(tb), w = *(const f32x4*)(tb + 256), b = *(const f32x4*)(tb + 512), k = *(const f32x4*)(tb + 768), r = *(const f32x4*)(tb + 1024);
;                     const float v = *(const float*)(buf + tt * SC_TOKB + 1280 + rl * 4);
;                     const f32x2 a01 = (f32x2){a[0], a[1]}, a23 = (f32x2){a[2], a[3]}, w01 = (f32x2){w[0], w[1]}, w23 = (f32x2){w[2], w[3]}, b01 = (f32x2){b[0], b[1]}, b23 = (f32x2){b[2], b[3]};
;                     const f32x2 k01 = (f32x2){k[0], k[1]}, k23 = (f32x2){k[2], k[3]}, r01 = (f32x2){r[0], r[1]}, r23 = (f32x2){r[2], r[3]};
;                     const f32x2 pa = s01 * a01 + s23 * a23;
;                     const float sa = allsum16(pa.x + pa.y);
;                     const f32x2 kv01 = k01 * v, kv23 = k23 * v;
;                     s01 = s01 * w01 + (b01 * sa + kv01); s23 = s23 * w23 + (b23 * sa + kv23);
;                     const f32x2 py = s01 * r01 + s23 * r23;
;                     const float y = allsum16(py.x + py.y);
;                     if ((lane & 15) == (tt & 15)) yreg0 = y;
;                 }
;             }
;             for (int t8 = 16; t8 < (jb.nsteps < 32 ? jb.nsteps : 32); t8 += 4) {
; #pragma unroll
;                 for (int u = 0; u < 4; ++u) {
;                     const int tt = t8 + u;
;                     const unsigned char* tb = buf + tt * SC_TOKB + c0 * 4;
;                     const f32x4 a = *(const f32x4*)(tb), w = *(const f32x4*)(tb + 256), b = *(const f32x4*)(tb + 512), k = *(const f32x4*)(tb + 768), r = *(const f32x4*)(tb + 1024);
;                     const float v = *(const float*)(buf + tt * SC_TOKB + 1280 + rl * 4);
;                     const f32x2 a01 = (f32x2){a[0], a[1]}, a23 = (f32x2){a[2], a[3]}, w01 = (f32x2){w[0], w[1]}, w23 = (f32x2){w[2], w[3]}, b01 = (f32x2){b[0], b[1]}, b23 = (f32x2){b[2], b[3]};
;                     const f32x2 k01 = (f32x2){k[0], k[1]}, k23 = (f32x2){k[2], k[3]}, r01 = (f32x2){r[0], r[1]}, r23 = (f32x2){r[2], r[3]};
;                     const f32x2 pa = s01 * a01 + s23 * a23;
;                     const float sa = allsum16(pa.x + pa.y);
;                     const f32x2 kv01 = k01 * v, kv23 = k23 * v;
;                     s01 = s01 * w01 + (b01 * sa + kv01); s23 = s23 * w23 + (b23 * sa + kv23);
	ds_read_b128 v[32:35], v217 offset:24192
	ds_read_b128 v[36:39], v217 offset:24448
	ds_read_b128 v[40:43], v217 offset:24704
	ds_read_b128 v[44:47], v217 offset:24960
	ds_read_b128 v[48:51], v217 offset:25216
	ds_read_b32 v92, v218 offset:24192
	v_pk_mul_f32 v[206:207], v[24:25], v[122:123]
	v_pk_fma_f32 v[206:207], v[22:23], v[120:121], v[206:207]
	v_pk_mul_f32 v[208:209], v[24:25], v[204:205]
	v_add_f32_e32 v214, v206, v207
	v_pk_fma_f32 v[208:209], v[22:23], v[202:203], v[208:209]
	v_pk_mul_f32 v[210:211], v[132:133], v[28:29] op_sel_hi:[1,0]
	v_add_f32_dpp v214, v214, v214 quad_perm:[1,0,3,2] row_mask:0xf bank_mask:0xf bound_ctrl:1
	v_add_f32_e32 v247, v208, v209
	v_pk_mul_f32 v[212:213], v[134:135], v[28:29] op_sel_hi:[1,0]
	v_add_f32_dpp v214, v214, v214 quad_perm:[2,3,0,1] row_mask:0xf bank_mask:0xf bound_ctrl:1
	v_pk_fma_f32 v[210:211], v[22:23], v[124:125], v[210:211]
	v_pk_fma_f32 v[212:213], v[24:25], v[126:127], v[212:213]
	v_add_f32_dpp v214, v214, v214 row_half_mirror row_mask:0xf bank_mask:0xf bound_ctrl:1
	s_nop 1
	v_add_f32_dpp v214, v214, v214 row_mirror row_mask:0xf bank_mask:0xf bound_ctrl:1
	v_pk_fma_f32 v[22:23], v[128:129], v[214:215], v[210:211] op_sel_hi:[1,0,1]
	v_pk_fma_f32 v[24:25], v[130:131], v[214:215], v[212:213] op_sel_hi:[1,0,1]
	s_mov_b32 s98, 0xaaaaaaaa
	s_mov_b32 s99, 0xaaaaaaaa
	v_cndmask_b32_e64 v249, v233, v232, s[98:99]
	v_cndmask_b32_e64 v232, v232, v233, s[98:99]
	v_cndmask_b32_e64 v251, v235, v234, s[98:99]
	v_cndmask_b32_e64 v234, v234, v235, s[98:99]
	v_add_f32_dpp v232, v249, v232 quad_perm:[1,0,3,2] row_mask:0xf bank_mask:0xf bound_ctrl:1
	v_cndmask_b32_e64 v249, v237, v236, s[98:99]
	v_cndmask_b32_e64 v236, v236, v237, s[98:99]
	v_add_f32_dpp v234, v251, v234 quad_perm:[1,0,3,2] row_mask:0xf bank_mask:0xf bound_ctrl:1
	v_cndmask_b32_e64 v251, v239, v238, s[98:99]
	v_cndmask_b32_e64 v238, v238, v239, s[98:99]
	v_add_f32_dpp v236, v249, v236 quad_perm:[1,0,3,2] row_mask:0xf bank_mask:0xf bound_ctrl:1
	v_cndmask_b32_e64 v249, v241, v240, s[98:99]
	v_cndmask_b32_e64 v240, v240, v241, s[98:99]
	v_add_f32_dpp v238, v251, v238 quad_perm:[1,0,3,2] row_mask:0xf bank_mask:0xf bound_ctrl:1
	v_cndmask_b32_e64 v251, v243, v242, s[98:99]
	v_cndmask_b32_e64 v242, v242, v243, s[98:99]
	v_add_f32_dpp v240, v249, v240 quad_perm:[1,0,3,2] row_mask:0xf bank_mask:0xf bound_ctrl:1
	v_cndmask_b32_e64 v249, v245, v244, s[98:99]
	v_cndmask_b32_e64 v244, v244, v245, s[98:99]
	v_add_f32_dpp v242, v251, v242 quad_perm:[1,0,3,2] row_mask:0xf bank_mask:0xf bound_ctrl:1
	v_cndmask_b32_e64 v251, v247, v246, s[98:99]
	v_cndmask_b32_e64 v246, v246, v247, s[98:99]
	v_add_f32_dpp v244, v249, v244 quad_perm:[1,0,3,2] row_mask:0xf bank_mask:0xf bound_ctrl:1
	s_nop 1
	v_add_f32_dpp v246, v251, v246 quad_perm:[1,0,3,2] row_mask:0xf bank_mask:0xf bound_ctrl:1
	s_mov_b32 s98, 0xcccccccc
	s_mov_b32 s99, 0xcccccccc
	v_cndmask_b32_e64 v249, v234, v232, s[98:99]
	v_cndmask_b32_e64 v232, v232, v234, s[98:99]
	v_cndmask_b32_e64 v251, v238, v236, s[98:99]
	v_cndmask_b32_e64 v236, v236, v238, s[98:99]
	v_add_f32_dpp v232, v249, v232 quad_perm:[2,3,0,1] row_mask:0xf bank_mask:0xf bound_ctrl:1
	v_cndmask_b32_e64 v249, v242, v240, s[98:99]
	v_cndmask_b32_e64 v240, v240, v242, s[98:99]
	v_add_f32_dpp v236, v251, v236 quad_perm:[2,3,0,1] row_mask:0xf bank_mask:0xf bound_ctrl:1
	v_cndmask_b32_e64 v251, v246, v244, s[98:99]
	v_cndmask_b32_e64 v244, v244, v246, s[98:99]
	v_add_f32_dpp v240, v249, v240 quad_perm:[2,3,0,1] row_mask:0xf bank_mask:0xf bound_ctrl:1
	s_nop 1
	v_add_f32_dpp v244, v251, v244 quad_perm:[2,3,0,1] row_mask:0xf bank_mask:0xf bound_ctrl:1
	s_mov_b32 s98, 0xf0f0f0f0
	s_mov_b32 s99, 0xf0f0f0f0
	v_cndmask_b32_e64 v249, v236, v232, s[98:99]
	v_cndmask_b32_e64 v232, v232, v236, s[98:99]
	v_cndmask_b32_e64 v251, v244, v240, s[98:99]
	v_cndmask_b32_e64 v240, v240, v244, s[98:99]
	v_add_f32_dpp v232, v249, v232 row_shr:4 row_mask:0xf bank_mask:0xa
	v_add_f32_dpp v232, v249, v232 row_shl:4 row_mask:0xf bank_mask:0x5
	s_nop 1
	v_add_f32_dpp v240, v251, v240 row_shr:4 row_mask:0xf bank_mask:0xa
	v_add_f32_dpp v240, v251, v240 row_shl:4 row_mask:0xf bank_mask:0x5
	s_mov_b32 s98, 0xff00ff00
	s_mov_b32 s99, 0xff00ff00
	v_cndmask_b32_e64 v249, v240, v232, s[98:99]
	v_cndmask_b32_e64 v232, v232, v240, s[98:99]
	s_nop 1
	v_add_f32_dpp v232, v249, v232 row_ror:8 row_mask:0xf bank_mask:0xf bound_ctrl:1
	v_mov_b32_e32 v18, v232
	s_waitcnt lgkmcnt(6)
	ds_read_b128 v[186:189], v217 offset:25536
	ds_read_b128 v[190:193], v217 offset:25792
	ds_read_b128 v[194:197], v217 offset:26048
	ds_read_b128 v[198:201], v217 offset:26304
	ds_read_b128 v[202:205], v217 offset:26560
	ds_read_b32 v52, v218 offset:25536
	v_pk_mul_f32 v[206:207], v[24:25], v[148:149]
	v_pk_fma_f32 v[206:207], v[22:23], v[146:147], v[206:207]
	v_pk_mul_f32 v[208:209], v[24:25], v[138:139]
	v_add_f32_e32 v214, v206, v207
	v_pk_fma_f32 v[208:209], v[22:23], v[136:137], v[208:209]
	v_pk_mul_f32 v[210:211], v[158:159], v[30:31] op_sel_hi:[1,0]
	v_add_f32_dpp v214, v214, v214 quad_perm:[1,0,3,2] row_mask:0xf bank_mask:0xf bound_ctrl:1
	v_add_f32_e32 v232, v208, v209
	v_pk_mul_f32 v[212:213], v[160:161], v[30:31] op_sel_hi:[1,0]
	v_add_f32_dpp v214, v214, v214 quad_perm:[2,3,0,1] row_mask:0xf bank_mask:0xf bound_ctrl:1
	v_pk_fma_f32 v[210:211], v[22:23], v[150:151], v[210:211]
	v_pk_fma_f32 v[212:213], v[24:25], v[152:153], v[212:213]
	v_add_f32_dpp v214, v214, v214 row_half_mirror row_mask:0xf bank_mask:0xf bound_ctrl:1
	s_nop 1
	v_add_f32_dpp v214, v214, v214 row_mirror row_mask:0xf bank_mask:0xf bound_ctrl:1
	v_pk_fma_f32 v[22:23], v[154:155], v[214:215], v[210:211] op_sel_hi:[1,0,1]
	v_pk_fma_f32 v[24:25], v[156:157], v[214:215], v[212:213] op_sel_hi:[1,0,1]
	s_waitcnt lgkmcnt(6)
; __device__ void phase_scan(int l, unsigned char* lds) {
;     ...
;             for (int t8 = 16; t8 < (jb.nsteps < 32 ? jb.nsteps : 32); t8 += 4) {
; #pragma unroll
;                 for (int u = 0; u < 4; ++u) {
;                     const int tt = t8 + u;
;                     const unsigned char* tb = buf + tt * SC_TOKB + c0 * 4;
;                     const f32x4 a = *(const f32x4*)(tb), w = *(const f32x4*)(tb + 256), b = *(const f32x4*)(tb + 512), k = *(const f32x4*)(tb + 768), r = *(const f32x4*)(tb + 1024);
;                     const float v = *(const float*)(buf + tt * SC_TOKB + 1280 + rl * 4);
;                     const f32x2 a01 = (f32x2){a[0], a[1]}, a23 = (f32x2){a[2], a[3]}, w01 = (f32x2){w[0], w[1]}, w23 = (f32x2){w[2], w[3]}, b01 = (f32x2){b[0], b[1]}, b23 = (f32x2){b[2], b[3]};
;                     const f32x2 k01 = (f32x2){k[0], k[1]}, k23 = (f32x2){k[2], k[3]}, r01 = (f32x2){r[0], r[1]}, r23 = (f32x2){r[2], r[3]};
;                     const f32x2 pa = s01 * a01 + s23 * a23;
;                     const float sa = allsum16(pa.x + pa.y);
;                     const f32x2 kv01 = k01 * v, kv23 = k23 * v;
;                     s01 = s01 * w01 + (b01 * sa + kv01); s23 = s23 * w23 + (b23 * sa + kv23);
;                     const f32x2 py = s01 * r01 + s23 * r23;
;                     const float y = allsum16(py.x + py.y);
;                     if ((lane & 15) == (tt & 15)) yreg1 = y;
	ds_read_b128 v[120:123], v217 offset:26880
	ds_read_b128 v[124:127], v217 offset:27136
	ds_read_b128 v[128:131], v217 offset:27392
	ds_read_b128 v[132:135], v217 offset:27648
	ds_read_b128 v[136:139], v217 offset:27904
	ds_read_b32 v28, v218 offset:26880
	v_pk_mul_f32 v[206:207], v[24:25], v[34:35]
	v_pk_fma_f32 v[206:207], v[22:23], v[32:33], v[206:207]
	v_pk_mul_f32 v[208:209], v[24:25], v[164:165]
	v_add_f32_e32 v214, v206, v207
	v_pk_fma_f32 v[208:209], v[22:23], v[162:163], v[208:209]
	v_pk_mul_f32 v[210:211], v[44:45], v[92:93] op_sel_hi:[1,0]
	v_add_f32_dpp v214, v214, v214 quad_perm:[1,0,3,2] row_mask:0xf bank_mask:0xf bound_ctrl:1
	v_add_f32_e32 v233, v208, v209
	v_pk_mul_f32 v[212:213], v[46:47], v[92:93] op_sel_hi:[1,0]
	v_add_f32_dpp v214, v214, v214 quad_perm:[2,3,0,1] row_mask:0xf bank_mask:0xf bound_ctrl:1
	v_pk_fma_f32 v[210:211], v[22:23], v[36:37], v[210:211]
	v_pk_fma_f32 v[212:213], v[24:25], v[38:39], v[212:213]
	v_add_f32_dpp v214, v214, v214 row_half_mirror row_mask:0xf bank_mask:0xf bound_ctrl:1
	s_nop 1
	v_add_f32_dpp v214, v214, v214 row_mirror row_mask:0xf bank_mask:0xf bound_ctrl:1
	v_pk_fma_f32 v[22:23], v[40:41], v[214:215], v[210:211] op_sel_hi:[1,0,1]
	v_pk_fma_f32 v[24:25], v[42:43], v[214:215], v[212:213] op_sel_hi:[1,0,1]
	s_waitcnt lgkmcnt(6)
	ds_read_b128 v[146:149], v217 offset:28224
	ds_read_b128 v[150:153], v217 offset:28480
	ds_read_b128 v[154:157], v217 offset:28736
	ds_read_b128 v[158:161], v217 offset:28992
	ds_read_b128 v[162:165], v217 offset:29248
	ds_read_b32 v30, v218 offset:28224
	v_pk_mul_f32 v[206:207], v[24:25], v[188:189]
	v_pk_fma_f32 v[206:207], v[22:23], v[186:187], v[206:207]
	v_pk_mul_f32 v[208:209], v[24:25], v[50:51]
	v_add_f32_e32 v214, v206, v207
	v_pk_fma_f32 v[208:209], v[22:23], v[48:49], v[208:209]
	v_pk_mul_f32 v[210:211], v[198:199], v[52:53] op_sel_hi:[1,0]
	v_add_f32_dpp v214, v214, v214 quad_perm:[1,0,3,2] row_mask:0xf bank_mask:0xf bound_ctrl:1
	v_add_f32_e32 v234, v208, v209
	v_pk_mul_f32 v[212:213], v[200:201], v[52:53] op_sel_hi:[1,0]
	v_add_f32_dpp v214, v214, v214 quad_perm:[2,3,0,1] row_mask:0xf bank_mask:0xf bound_ctrl:1
	v_pk_fma_f32 v[210:211], v[22:23], v[190:191], v[210:211]
	v_pk_fma_f32 v[212:213], v[24:25], v[192:193], v[212:213]
	v_add_f32_dpp v214, v214, v214 row_half_mirror row_mask:0xf bank_mask:0xf bound_ctrl:1
	s_nop 1
	v_add_f32_dpp v214, v214, v214 row_mirror row_mask:0xf bank_mask:0xf bound_ctrl:1
	v_pk_fma_f32 v[22:23], v[194:195], v[214:215], v[210:211] op_sel_hi:[1,0,1]
	v_pk_fma_f32 v[24:25], v[196:197], v[214:215], v[212:213] op_sel_hi:[1,0,1]
	s_waitcnt lgkmcnt(6)
	ds_read_b128 v[32:35], v217 offset:29568
	ds_read_b128 v[36:39], v217 offset:29824
	ds_read_b128 v[40:43], v217 offset:30080
	ds_read_b128 v[44:47], v217 offset:30336
	ds_read_b128 v[48:51], v217 offset:30592
	ds_read_b32 v92, v218 offset:29568
	v_pk_mul_f32 v[206:207], v[24:25], v[122:123]
	v_pk_fma_f32 v[206:207], v[22:23], v[120:121], v[206:207]
	v_pk_mul_f32 v[208:209], v[24:25], v[204:205]
	v_add_f32_e32 v214, v206, v207
	v_pk_fma_f32 v[208:209], v[22:23], v[202:203], v[208:209]
	v_pk_mul_f32 v[210:211], v[132:133], v[28:29] op_sel_hi:[1,0]
	v_add_f32_dpp v214, v214, v214 quad_perm:[1,0,3,2] row_mask:0xf bank_mask:0xf bound_ctrl:1
	v_add_f32_e32 v235, v208, v209
	v_pk_mul_f32 v[212:213], v[134:135], v[28:29] op_sel_hi:[1,0]
	v_add_f32_dpp v214, v214, v214 quad_perm:[2,3,0,1] row_mask:0xf bank_mask:0xf bound_ctrl:1
	v_pk_fma_f32 v[210:211], v[22:23], v[124:125], v[210:211]
	v_pk_fma_f32 v[212:213], v[24:25], v[126:127], v[212:213]
	v_add_f32_dpp v214, v214, v214 row_half_mirror row_mask:0xf bank_mask:0xf bound_ctrl:1
	s_nop 1
	v_add_f32_dpp v214, v214, v214 row_mirror row_mask:0xf bank_mask:0xf bound_ctrl:1
	v_pk_fma_f32 v[22:23], v[128:129], v[214:215], v[210:211] op_sel_hi:[1,0,1]
	v_pk_fma_f32 v[24:25], v[130:131], v[214:215], v[212:213] op_sel_hi:[1,0,1]
	s_waitcnt lgkmcnt(6)
	ds_read_b128 v[186:189], v217 offset:30912
	ds_read_b128 v[190:193], v217 offset:31168
	ds_read_b128 v[194:197], v217 offset:31424
	ds_read_b128 v[198:201], v217 offset:31680
	ds_read_b128 v[202:205], v217 offset:31936
	ds_read_b32 v52, v218 offset:30912
	v_pk_mul_f32 v[206:207], v[24:25], v[148:149]
	v_pk_fma_f32 v[206:207], v[22:23], v[146:147], v[206:207]
	v_pk_mul_f32 v[208:209], v[24:25], v[138:139]
	v_add_f32_e32 v214, v206, v207
	v_pk_fma_f32 v[208:209], v[22:23], v[136:137], v[208:209]
	v_pk_mul_f32 v[210:211], v[158:159], v[30:31] op_sel_hi:[1,0]
	v_add_f32_dpp v214, v214, v214 quad_perm:[1,0,3,2] row_mask:0xf bank_mask:0xf bound_ctrl:1
	v_add_f32_e32 v236, v208, v209
	v_pk_mul_f32 v[212:213], v[160:161], v[30:31] op_sel_hi:[1,0]
	v_add_f32_dpp v214, v214, v214 quad_perm:[2,3,0,1] row_mask:0xf bank_mask:0xf bound_ctrl:1
	v_pk_fma_f32 v[210:211], v[22:23], v[150:151], v[210:211]
	v_pk_fma_f32 v[212:213], v[24:25], v[152:153], v[212:213]
	v_add_f32_dpp v214, v214, v214 row_half_mirror row_mask:0xf bank_mask:0xf bound_ctrl:1
	s_nop 1
	v_add_f32_dpp v214, v214, v214 row_mirror row_mask:0xf bank_mask:0xf bound_ctrl:1
	v_pk_fma_f32 v[22:23], v[154:155], v[214:215], v[210:211] op_sel_hi:[1,0,1]
	v_pk_fma_f32 v[24:25], v[156:157], v[214:215], v[212:213] op_sel_hi:[1,0,1]
	s_waitcnt lgkmcnt(6)
; __device__ void phase_scan(int l, unsigned char* lds) {
;     ...
;             for (int t8 = 16; t8 < (jb.nsteps < 32 ? jb.nsteps : 32); t8 += 4) {
; #pragma unroll
;                 for (int u = 0; u < 4; ++u) {
;                     const int tt = t8 + u;
;                     const unsigned char* tb = buf + tt * SC_TOKB + c0 * 4;
;                     const f32x4 a = *(const f32x4*)(tb), w = *(const f32x4*)(tb + 256), b = *(const f32x4*)(tb + 512), k = *(const f32x4*)(tb + 768), r = *(const f32x4*)(tb + 1024);
;                     const float v = *(const float*)(buf + tt * SC_TOKB + 1280 + rl * 4);
;                     const f32x2 a01 = (f32x2){a[0], a[1]}, a23 = (f32x2){a[2], a[3]}, w01 = (f32x2){w[0], w[1]}, w23 = (f32x2){w[2], w[3]}, b01 = (f32x2){b[0], b[1]}, b23 = (f32x2){b[2], b[3]};
;                     const f32x2 k01 = (f32x2){k[0], k[1]}, k23 = (f32x2){k[2], k[3]}, r01 = (f32x2){r[0], r[1]}, r23 = (f32x2){r[2], r[3]};
;                     const f32x2 pa = s01 * a01 + s23 * a23;
;                     const float sa = allsum16(pa.x + pa.y);
;                     const f32x2 kv01 = k01 * v, kv23 = k23 * v;
;                     s01 = s01 * w01 + (b01 * sa + kv01); s23 = s23 * w23 + (b23 * sa + kv23);
;                     const f32x2 py = s01 * r01 + s23 * r23;
;                     const float y = allsum16(py.x + py.y);
;                     if ((lane & 15) == (tt & 15)) yreg1 = y;
	ds_read_b128 v[120:123], v217 offset:32256
	ds_read_b128 v[124:127], v217 offset:32512
	ds_read_b128 v[128:131], v217 offset:32768
	ds_read_b128 v[132:135], v217 offset:33024
	ds_read_b128 v[136:139], v217 offset:33280
	ds_read_b32 v28, v218 offset:32256
	v_pk_mul_f32 v[206:207], v[24:25], v[34:35]
	v_pk_fma_f32 v[206:207], v[22:23], v[32:33], v[206:207]
	v_pk_mul_f32 v[208:209], v[24:25], v[164:165]
	v_add_f32_e32 v214, v206, v207
	v_pk_fma_f32 v[208:209], v[22:23], v[162:163], v[208:209]
	v_pk_mul_f32 v[210:211], v[44:45], v[92:93] op_sel_hi:[1,0]
	v_add_f32_dpp v214, v214, v214 quad_perm:[1,0,3,2] row_mask:0xf bank_mask:0xf bound_ctrl:1
	v_add_f32_e32 v237, v208, v209
	v_pk_mul_f32 v[212:213], v[46:47], v[92:93] op_sel_hi:[1,0]
	v_add_f32_dpp v214, v214, v214 quad_perm:[2,3,0,1] row_mask:0xf bank_mask:0xf bound_ctrl:1
	v_pk_fma_f32 v[210:211], v[22:23], v[36:37], v[210:211]
	v_pk_fma_f32 v[212:213], v[24:25], v[38:39], v[212:213]
	v_add_f32_dpp v214, v214, v214 row_half_mirror row_mask:0xf bank_mask:0xf bound_ctrl:1
	s_nop 1
	v_add_f32_dpp v214, v214, v214 row_mirror row_mask:0xf bank_mask:0xf bound_ctrl:1
	v_pk_fma_f32 v[22:23], v[40:41], v[214:215], v[210:211] op_sel_hi:[1,0,1]
	v_pk_fma_f32 v[24:25], v[42:43], v[214:215], v[212:213] op_sel_hi:[1,0,1]
	s_waitcnt lgkmcnt(6)
	ds_read_b128 v[146:149], v217 offset:33600
	ds_read_b128 v[150:153], v217 offset:33856
	ds_read_b128 v[154:157], v217 offset:34112
	ds_read_b128 v[158:161], v217 offset:34368
	ds_read_b128 v[162:165], v217 offset:34624
	ds_read_b32 v30, v218 offset:33600
	v_pk_mul_f32 v[206:207], v[24:25], v[188:189]
	v_pk_fma_f32 v[206:207], v[22:23], v[186:187], v[206:207]
	v_pk_mul_f32 v[208:209], v[24:25], v[50:51]
	v_add_f32_e32 v214, v206, v207
	v_pk_fma_f32 v[208:209], v[22:23], v[48:49], v[208:209]
	v_pk_mul_f32 v[210:211], v[198:199], v[52:53] op_sel_hi:[1,0]
	v_add_f32_dpp v214, v214, v214 quad_perm:[1,0,3,2] row_mask:0xf bank_mask:0xf bound_ctrl:1
	v_add_f32_e32 v238, v208, v209
	v_pk_mul_f32 v[212:213], v[200:201], v[52:53] op_sel_hi:[1,0]
	v_add_f32_dpp v214, v214, v214 quad_perm:[2,3,0,1] row_mask:0xf bank_mask:0xf bound_ctrl:1
	v_pk_fma_f32 v[210:211], v[22:23], v[190:191], v[210:211]
	v_pk_fma_f32 v[212:213], v[24:25], v[192:193], v[212:213]
	v_add_f32_dpp v214, v214, v214 row_half_mirror row_mask:0xf bank_mask:0xf bound_ctrl:1
	s_nop 1
	v_add_f32_dpp v214, v214, v214 row_mirror row_mask:0xf bank_mask:0xf bound_ctrl:1
	v_pk_fma_f32 v[22:23], v[194:195], v[214:215], v[210:211] op_sel_hi:[1,0,1]
	v_pk_fma_f32 v[24:25], v[196:197], v[214:215], v[212:213] op_sel_hi:[1,0,1]
	s_waitcnt lgkmcnt(6)
	ds_read_b128 v[32:35], v217 offset:34944
	ds_read_b128 v[36:39], v217 offset:35200
	ds_read_b128 v[40:43], v217 offset:35456
	ds_read_b128 v[44:47], v217 offset:35712
	ds_read_b128 v[48:51], v217 offset:35968
	ds_read_b32 v92, v218 offset:34944
	v_pk_mul_f32 v[206:207], v[24:25], v[122:123]
	v_pk_fma_f32 v[206:207], v[22:23], v[120:121], v[206:207]
	v_pk_mul_f32 v[208:209], v[24:25], v[204:205]
	v_add_f32_e32 v214, v206, v207
	v_pk_fma_f32 v[208:209], v[22:23], v[202:203], v[208:209]
	v_pk_mul_f32 v[210:211], v[132:133], v[28:29] op_sel_hi:[1,0]
	v_add_f32_dpp v214, v214, v214 quad_perm:[1,0,3,2] row_mask:0xf bank_mask:0xf bound_ctrl:1
	v_add_f32_e32 v239, v208, v209
	v_pk_mul_f32 v[212:213], v[134:135], v[28:29] op_sel_hi:[1,0]
	v_add_f32_dpp v214, v214, v214 quad_perm:[2,3,0,1] row_mask:0xf bank_mask:0xf bound_ctrl:1
	v_pk_fma_f32 v[210:211], v[22:23], v[124:125], v[210:211]
	v_pk_fma_f32 v[212:213], v[24:25], v[126:127], v[212:213]
	v_add_f32_dpp v214, v214, v214 row_half_mirror row_mask:0xf bank_mask:0xf bound_ctrl:1
	s_nop 1
	v_add_f32_dpp v214, v214, v214 row_mirror row_mask:0xf bank_mask:0xf bound_ctrl:1
	v_pk_fma_f32 v[22:23], v[128:129], v[214:215], v[210:211] op_sel_hi:[1,0,1]
	v_pk_fma_f32 v[24:25], v[130:131], v[214:215], v[212:213] op_sel_hi:[1,0,1]
	s_waitcnt lgkmcnt(6)
	ds_read_b128 v[186:189], v217 offset:36288
	ds_read_b128 v[190:193], v217 offset:36544
	ds_read_b128 v[194:197], v217 offset:36800
	ds_read_b128 v[198:201], v217 offset:37056
	ds_read_b128 v[202:205], v217 offset:37312
	ds_read_b32 v52, v218 offset:36288
	v_pk_mul_f32 v[206:207], v[24:25], v[148:149]
	v_pk_fma_f32 v[206:207], v[22:23], v[146:147], v[206:207]
	v_pk_mul_f32 v[208:209], v[24:25], v[138:139]
	v_add_f32_e32 v214, v206, v207
	v_pk_fma_f32 v[208:209], v[22:23], v[136:137], v[208:209]
	v_pk_mul_f32 v[210:211], v[158:159], v[30:31] op_sel_hi:[1,0]
	v_add_f32_dpp v214, v214, v214 quad_perm:[1,0,3,2] row_mask:0xf bank_mask:0xf bound_ctrl:1
	v_add_f32_e32 v240, v208, v209
	v_pk_mul_f32 v[212:213], v[160:161], v[30:31] op_sel_hi:[1,0]
	v_add_f32_dpp v214, v214, v214 quad_perm:[2,3,0,1] row_mask:0xf bank_mask:0xf bound_ctrl:1
	v_pk_fma_f32 v[210:211], v[22:23], v[150:151], v[210:211]
	v_pk_fma_f32 v[212:213], v[24:25], v[152:153], v[212:213]
	v_add_f32_dpp v214, v214, v214 row_half_mirror row_mask:0xf bank_mask:0xf bound_ctrl:1
	s_nop 1
	v_add_f32_dpp v214, v214, v214 row_mirror row_mask:0xf bank_mask:0xf bound_ctrl:1
	v_pk_fma_f32 v[22:23], v[154:155], v[214:215], v[210:211] op_sel_hi:[1,0,1]
	v_pk_fma_f32 v[24:25], v[156:157], v[214:215], v[212:213] op_sel_hi:[1,0,1]
	s_waitcnt lgkmcnt(6)
; __device__ void phase_scan(int l, unsigned char* lds) {
;     ...
;             for (int t8 = 16; t8 < (jb.nsteps < 32 ? jb.nsteps : 32); t8 += 4) {
; #pragma unroll
;                 for (int u = 0; u < 4; ++u) {
;                     const int tt = t8 + u;
;                     const unsigned char* tb = buf + tt * SC_TOKB + c0 * 4;
;                     const f32x4 a = *(const f32x4*)(tb), w = *(const f32x4*)(tb + 256), b = *(const f32x4*)(tb + 512), k = *(const f32x4*)(tb + 768), r = *(const f32x4*)(tb + 1024);
;                     const float v = *(const float*)(buf + tt * SC_TOKB + 1280 + rl * 4);
;                     const f32x2 a01 = (f32x2){a[0], a[1]}, a23 = (f32x2){a[2], a[3]}, w01 = (f32x2){w[0], w[1]}, w23 = (f32x2){w[2], w[3]}, b01 = (f32x2){b[0], b[1]}, b23 = (f32x2){b[2], b[3]};
;                     const f32x2 k01 = (f32x2){k[0], k[1]}, k23 = (f32x2){k[2], k[3]}, r01 = (f32x2){r[0], r[1]}, r23 = (f32x2){r[2], r[3]};
;                     const f32x2 pa = s01 * a01 + s23 * a23;
;                     const float sa = allsum16(pa.x + pa.y);
;                     const f32x2 kv01 = k01 * v, kv23 = k23 * v;
;                     s01 = s01 * w01 + (b01 * sa + kv01); s23 = s23 * w23 + (b23 * sa + kv23);
;                     const f32x2 py = s01 * r01 + s23 * r23;
;                     const float y = allsum16(py.x + py.y);
;                     if ((lane & 15) == (tt & 15)) yreg1 = y;
	ds_read_b128 v[120:123], v217 offset:37632
	ds_read_b128 v[124:127], v217 offset:37888
	ds_read_b128 v[128:131], v217 offset:38144
	ds_read_b128 v[132:135], v217 offset:38400
	ds_read_b128 v[136:139], v217 offset:38656
	ds_read_b32 v28, v218 offset:37632
	v_pk_mul_f32 v[206:207], v[24:25], v[34:35]
	v_pk_fma_f32 v[206:207], v[22:23], v[32:33], v[206:207]
	v_pk_mul_f32 v[208:209], v[24:25], v[164:165]
	v_add_f32_e32 v214, v206, v207
	v_pk_fma_f32 v[208:209], v[22:23], v[162:163], v[208:209]
	v_pk_mul_f32 v[210:211], v[44:45], v[92:93] op_sel_hi:[1,0]
	v_add_f32_dpp v214, v214, v214 quad_perm:[1,0,3,2] row_mask:0xf bank_mask:0xf bound_ctrl:1
	v_add_f32_e32 v241, v208, v209
	v_pk_mul_f32 v[212:213], v[46:47], v[92:93] op_sel_hi:[1,0]
	v_add_f32_dpp v214, v214, v214 quad_perm:[2,3,0,1] row_mask:0xf bank_mask:0xf bound_ctrl:1
	v_pk_fma_f32 v[210:211], v[22:23], v[36:37], v[210:211]
	v_pk_fma_f32 v[212:213], v[24:25], v[38:39], v[212:213]
	v_add_f32_dpp v214, v214, v214 row_half_mirror row_mask:0xf bank_mask:0xf bound_ctrl:1
	s_nop 1
	v_add_f32_dpp v214, v214, v214 row_mirror row_mask:0xf bank_mask:0xf bound_ctrl:1
	v_pk_fma_f32 v[22:23], v[40:41], v[214:215], v[210:211] op_sel_hi:[1,0,1]
	v_pk_fma_f32 v[24:25], v[42:43], v[214:215], v[212:213] op_sel_hi:[1,0,1]
	s_waitcnt lgkmcnt(6)
	ds_read_b128 v[146:149], v217 offset:38976
	ds_read_b128 v[150:153], v217 offset:39232
	ds_read_b128 v[154:157], v217 offset:39488
	ds_read_b128 v[158:161], v217 offset:39744
	ds_read_b128 v[162:165], v217 offset:40000
	ds_read_b32 v30, v218 offset:38976
	v_pk_mul_f32 v[206:207], v[24:25], v[188:189]
	v_pk_fma_f32 v[206:207], v[22:23], v[186:187], v[206:207]
	v_pk_mul_f32 v[208:209], v[24:25], v[50:51]
	v_add_f32_e32 v214, v206, v207
	v_pk_fma_f32 v[208:209], v[22:23], v[48:49], v[208:209]
	v_pk_mul_f32 v[210:211], v[198:199], v[52:53] op_sel_hi:[1,0]
	v_add_f32_dpp v214, v214, v214 quad_perm:[1,0,3,2] row_mask:0xf bank_mask:0xf bound_ctrl:1
	v_add_f32_e32 v242, v208, v209
	v_pk_mul_f32 v[212:213], v[200:201], v[52:53] op_sel_hi:[1,0]
	v_add_f32_dpp v214, v214, v214 quad_perm:[2,3,0,1] row_mask:0xf bank_mask:0xf bound_ctrl:1
	v_pk_fma_f32 v[210:211], v[22:23], v[190:191], v[210:211]
	v_pk_fma_f32 v[212:213], v[24:25], v[192:193], v[212:213]
	v_add_f32_dpp v214, v214, v214 row_half_mirror row_mask:0xf bank_mask:0xf bound_ctrl:1
	s_nop 1
	v_add_f32_dpp v214, v214, v214 row_mirror row_mask:0xf bank_mask:0xf bound_ctrl:1
	v_pk_fma_f32 v[22:23], v[194:195], v[214:215], v[210:211] op_sel_hi:[1,0,1]
	v_pk_fma_f32 v[24:25], v[196:197], v[214:215], v[212:213] op_sel_hi:[1,0,1]
	s_waitcnt lgkmcnt(6)
	ds_read_b128 v[32:35], v217 offset:40320
	ds_read_b128 v[36:39], v217 offset:40576
	ds_read_b128 v[40:43], v217 offset:40832
	ds_read_b128 v[44:47], v217 offset:41088
	ds_read_b128 v[48:51], v217 offset:41344
	ds_read_b32 v92, v218 offset:40320
	v_pk_mul_f32 v[206:207], v[24:25], v[122:123]
	v_pk_fma_f32 v[206:207], v[22:23], v[120:121], v[206:207]
	v_pk_mul_f32 v[208:209], v[24:25], v[204:205]
	v_add_f32_e32 v214, v206, v207
	v_pk_fma_f32 v[208:209], v[22:23], v[202:203], v[208:209]
	v_pk_mul_f32 v[210:211], v[132:133], v[28:29] op_sel_hi:[1,0]
	v_add_f32_dpp v214, v214, v214 quad_perm:[1,0,3,2] row_mask:0xf bank_mask:0xf bound_ctrl:1
	v_add_f32_e32 v243, v208, v209
	v_pk_mul_f32 v[212:213], v[134:135], v[28:29] op_sel_hi:[1,0]
	v_add_f32_dpp v214, v214, v214 quad_perm:[2,3,0,1] row_mask:0xf bank_mask:0xf bound_ctrl:1
	v_pk_fma_f32 v[210:211], v[22:23], v[124:125], v[210:211]
	v_pk_fma_f32 v[212:213], v[24:25], v[126:127], v[212:213]
	v_add_f32_dpp v214, v214, v214 row_half_mirror row_mask:0xf bank_mask:0xf bound_ctrl:1
	s_nop 1
	v_add_f32_dpp v214, v214, v214 row_mirror row_mask:0xf bank_mask:0xf bound_ctrl:1
	v_pk_fma_f32 v[22:23], v[128:129], v[214:215], v[210:211] op_sel_hi:[1,0,1]
	v_pk_fma_f32 v[24:25], v[130:131], v[214:215], v[212:213] op_sel_hi:[1,0,1]
	s_waitcnt lgkmcnt(6)
	ds_read_b128 v[186:189], v217 offset:41664
	ds_read_b128 v[190:193], v217 offset:41920
	ds_read_b128 v[194:197], v217 offset:42176
	ds_read_b128 v[198:201], v217 offset:42432
	ds_read_b128 v[202:205], v217 offset:42688
	ds_read_b32 v52, v218 offset:41664
	v_pk_mul_f32 v[206:207], v[24:25], v[148:149]
	v_pk_fma_f32 v[206:207], v[22:23], v[146:147], v[206:207]
	v_pk_mul_f32 v[208:209], v[24:25], v[138:139]
	v_add_f32_e32 v214, v206, v207
	v_pk_fma_f32 v[208:209], v[22:23], v[136:137], v[208:209]
	v_pk_mul_f32 v[210:211], v[158:159], v[30:31] op_sel_hi:[1,0]
	v_add_f32_dpp v214, v214, v214 quad_perm:[1,0,3,2] row_mask:0xf bank_mask:0xf bound_ctrl:1
	v_add_f32_e32 v244, v208, v209
	v_pk_mul_f32 v[212:213], v[160:161], v[30:31] op_sel_hi:[1,0]
	v_add_f32_dpp v214, v214, v214 quad_perm:[2,3,0,1] row_mask:0xf bank_mask:0xf bound_ctrl:1
	v_pk_fma_f32 v[210:211], v[22:23], v[150:151], v[210:211]
	v_pk_fma_f32 v[212:213], v[24:25], v[152:153], v[212:213]
	v_add_f32_dpp v214, v214, v214 row_half_mirror row_mask:0xf bank_mask:0xf bound_ctrl:1
	s_nop 1
	v_add_f32_dpp v214, v214, v214 row_mirror row_mask:0xf bank_mask:0xf bound_ctrl:1
	v_pk_fma_f32 v[22:23], v[154:155], v[214:215], v[210:211] op_sel_hi:[1,0,1]
	v_pk_fma_f32 v[24:25], v[156:157], v[214:215], v[212:213] op_sel_hi:[1,0,1]
	s_waitcnt lgkmcnt(6)
; __device__ __forceinline__ bf16_t f2bf(float f) { return (bf16_t)(pk2(f, 0.f) & 0xffffu); }
; __device__ void phase_scan(int l, unsigned char* lds) {
;     ...
;             for (int t8 = 16; t8 < (jb.nsteps < 32 ? jb.nsteps : 32); t8 += 4) {
; #pragma unroll
;                 for (int u = 0; u < 4; ++u) {
;                     const int tt = t8 + u;
;                     const unsigned char* tb = buf + tt * SC_TOKB + c0 * 4;
;                     const f32x4 a = *(const f32x4*)(tb), w = *(const f32x4*)(tb + 256), b = *(const f32x4*)(tb + 512), k = *(const f32x4*)(tb + 768), r = *(const f32x4*)(tb + 1024);
;                     const float v = *(const float*)(buf + tt * SC_TOKB + 1280 + rl * 4);
;                     const f32x2 a01 = (f32x2){a[0], a[1]}, a23 = (f32x2){a[2], a[3]}, w01 = (f32x2){w[0], w[1]}, w23 = (f32x2){w[2], w[3]}, b01 = (f32x2){b[0], b[1]}, b23 = (f32x2){b[2], b[3]};
;                     const f32x2 k01 = (f32x2){k[0], k[1]}, k23 = (f32x2){k[2], k[3]}, r01 = (f32x2){r[0], r[1]}, r23 = (f32x2){r[2], r[3]};
;                     const f32x2 pa = s01 * a01 + s23 * a23;
;                     const float sa = allsum16(pa.x + pa.y);
;                     const f32x2 kv01 = k01 * v, kv23 = k23 * v;
;                     s01 = s01 * w01 + (b01 * sa + kv01); s23 = s23 * w23 + (b23 * sa + kv23);
;                     const f32x2 py = s01 * r01 + s23 * r23;
;                     const float y = allsum16(py.x + py.y);
;                     if ((lane & 15) == (tt & 15)) yreg1 = y;
;                 }
;             }
;             if ((lane & 15) < jb.nsteps) ybuf[(size_t)(jb.tok0 + (lane & 15)) * 512 + jb.h * 64 + row] = f2bf(yreg0);
	v_pk_mul_f32 v[206:207], v[24:25], v[34:35]
	v_pk_fma_f32 v[206:207], v[22:23], v[32:33], v[206:207]
	v_pk_mul_f32 v[208:209], v[24:25], v[164:165]
	v_add_f32_e32 v214, v206, v207
	v_pk_fma_f32 v[208:209], v[22:23], v[162:163], v[208:209]
	v_pk_mul_f32 v[210:211], v[44:45], v[92:93] op_sel_hi:[1,0]
	v_add_f32_dpp v214, v214, v214 quad_perm:[1,0,3,2] row_mask:0xf bank_mask:0xf bound_ctrl:1
	v_add_f32_e32 v245, v208, v209
	v_pk_mul_f32 v[212:213], v[46:47], v[92:93] op_sel_hi:[1,0]
	v_add_f32_dpp v214, v214, v214 quad_perm:[2,3,0,1] row_mask:0xf bank_mask:0xf bound_ctrl:1
	v_pk_fma_f32 v[210:211], v[22:23], v[36:37], v[210:211]
	v_pk_fma_f32 v[212:213], v[24:25], v[38:39], v[212:213]
	v_add_f32_dpp v214, v214, v214 row_half_mirror row_mask:0xf bank_mask:0xf bound_ctrl:1
	s_nop 1
	v_add_f32_dpp v214, v214, v214 row_mirror row_mask:0xf bank_mask:0xf bound_ctrl:1
	v_pk_fma_f32 v[22:23], v[40:41], v[214:215], v[210:211] op_sel_hi:[1,0,1]
	v_pk_fma_f32 v[24:25], v[42:43], v[214:215], v[212:213] op_sel_hi:[1,0,1]
	s_waitcnt lgkmcnt(0)
	v_pk_mul_f32 v[206:207], v[24:25], v[188:189]
	v_pk_fma_f32 v[206:207], v[22:23], v[186:187], v[206:207]
	v_pk_mul_f32 v[208:209], v[24:25], v[50:51]
	v_add_f32_e32 v214, v206, v207
	v_pk_fma_f32 v[208:209], v[22:23], v[48:49], v[208:209]
	v_pk_mul_f32 v[210:211], v[198:199], v[52:53] op_sel_hi:[1,0]
	v_add_f32_dpp v214, v214, v214 quad_perm:[1,0,3,2] row_mask:0xf bank_mask:0xf bound_ctrl:1
	v_add_f32_e32 v246, v208, v209
	v_pk_mul_f32 v[212:213], v[200:201], v[52:53] op_sel_hi:[1,0]
	v_add_f32_dpp v214, v214, v214 quad_perm:[2,3,0,1] row_mask:0xf bank_mask:0xf bound_ctrl:1
	v_pk_fma_f32 v[210:211], v[22:23], v[190:191], v[210:211]
	v_pk_fma_f32 v[212:213], v[24:25], v[192:193], v[212:213]
	v_add_f32_dpp v214, v214, v214 row_half_mirror row_mask:0xf bank_mask:0xf bound_ctrl:1
	s_nop 1
	v_add_f32_dpp v214, v214, v214 row_mirror row_mask:0xf bank_mask:0xf bound_ctrl:1
	v_pk_fma_f32 v[22:23], v[194:195], v[214:215], v[210:211] op_sel_hi:[1,0,1]
	v_pk_fma_f32 v[24:25], v[196:197], v[214:215], v[212:213] op_sel_hi:[1,0,1]
	v_pk_mul_f32 v[208:209], v[24:25], v[204:205]
	v_pk_fma_f32 v[208:209], v[22:23], v[202:203], v[208:209]
	v_add_f32_e32 v247, v208, v209
	s_mov_b32 s98, 0xaaaaaaaa
	s_mov_b32 s99, 0xaaaaaaaa
	v_cndmask_b32_e64 v249, v233, v232, s[98:99]
	v_cndmask_b32_e64 v232, v232, v233, s[98:99]
	v_cndmask_b32_e64 v251, v235, v234, s[98:99]
	v_cndmask_b32_e64 v234, v234, v235, s[98:99]
	v_add_f32_dpp v232, v249, v232 quad_perm:[1,0,3,2] row_mask:0xf bank_mask:0xf bound_ctrl:1
	v_cndmask_b32_e64 v249, v237, v236, s[98:99]
	v_cndmask_b32_e64 v236, v236, v237, s[98:99]
	v_add_f32_dpp v234, v251, v234 quad_perm:[1,0,3,2] row_mask:0xf bank_mask:0xf bound_ctrl:1
	v_cndmask_b32_e64 v251, v239, v238, s[98:99]
	v_cndmask_b32_e64 v238, v238, v239, s[98:99]
	v_add_f32_dpp v236, v249, v236 quad_perm:[1,0,3,2] row_mask:0xf bank_mask:0xf bound_ctrl:1
	v_cndmask_b32_e64 v249, v241, v240, s[98:99]
	v_cndmask_b32_e64 v240, v240, v241, s[98:99]
	v_add_f32_dpp v238, v251, v238 quad_perm:[1,0,3,2] row_mask:0xf bank_mask:0xf bound_ctrl:1
	v_cndmask_b32_e64 v251, v243, v242, s[98:99]
	v_cndmask_b32_e64 v242, v242, v243, s[98:99]
	v_add_f32_dpp v240, v249, v240 quad_perm:[1,0,3,2] row_mask:0xf bank_mask:0xf bound_ctrl:1
	v_cndmask_b32_e64 v249, v245, v244, s[98:99]
	v_cndmask_b32_e64 v244, v244, v245, s[98:99]
	v_add_f32_dpp v242, v251, v242 quad_perm:[1,0,3,2] row_mask:0xf bank_mask:0xf bound_ctrl:1
	v_cndmask_b32_e64 v251, v247, v246, s[98:99]
	v_cndmask_b32_e64 v246, v246, v247, s[98:99]
	v_add_f32_dpp v244, v249, v244 quad_perm:[1,0,3,2] row_mask:0xf bank_mask:0xf bound_ctrl:1
	s_nop 1
	v_add_f32_dpp v246, v251, v246 quad_perm:[1,0,3,2] row_mask:0xf bank_mask:0xf bound_ctrl:1
	s_mov_b32 s98, 0xcccccccc
	s_mov_b32 s99, 0xcccccccc
	v_cndmask_b32_e64 v249, v234, v232, s[98:99]
	v_cndmask_b32_e64 v232, v232, v234, s[98:99]
	v_cndmask_b32_e64 v251, v238, v236, s[98:99]
	v_cndmask_b32_e64 v236, v236, v238, s[98:99]
	v_add_f32_dpp v232, v249, v232 quad_perm:[2,3,0,1] row_mask:0xf bank_mask:0xf bound_ctrl:1
	v_cndmask_b32_e64 v249, v242, v240, s[98:99]
	v_cndmask_b32_e64 v240, v240, v242, s[98:99]
	v_add_f32_dpp v236, v251, v236 quad_perm:[2,3,0,1] row_mask:0xf bank_mask:0xf bound_ctrl:1
	v_cndmask_b32_e64 v251, v246, v244, s[98:99]
	v_cndmask_b32_e64 v244, v244, v246, s[98:99]
	v_add_f32_dpp v240, v249, v240 quad_perm:[2,3,0,1] row_mask:0xf bank_mask:0xf bound_ctrl:1
	s_nop 1
	v_add_f32_dpp v244, v251, v244 quad_perm:[2,3,0,1] row_mask:0xf bank_mask:0xf bound_ctrl:1
	s_mov_b32 s98, 0xf0f0f0f0
	s_mov_b32 s99, 0xf0f0f0f0
	v_cndmask_b32_e64 v249, v236, v232, s[98:99]
	v_cndmask_b32_e64 v232, v232, v236, s[98:99]
	v_cndmask_b32_e64 v251, v244, v240, s[98:99]
	v_cndmask_b32_e64 v240, v240, v244, s[98:99]
	v_add_f32_dpp v232, v249, v232 row_shr:4 row_mask:0xf bank_mask:0xa
	v_add_f32_dpp v232, v249, v232 row_shl:4 row_mask:0xf bank_mask:0x5
	s_nop 1
	v_add_f32_dpp v240, v251, v240 row_shr:4 row_mask:0xf bank_mask:0xa
	v_add_f32_dpp v240, v251, v240 row_shl:4 row_mask:0xf bank_mask:0x5
	s_mov_b32 s98, 0xff00ff00
	s_mov_b32 s99, 0xff00ff00
	v_cndmask_b32_e64 v249, v240, v232, s[98:99]
	v_cndmask_b32_e64 v232, v232, v240, s[98:99]
	s_nop 1
	v_add_f32_dpp v232, v249, v232 row_ror:8 row_mask:0xf bank_mask:0xf bound_ctrl:1
	v_mov_b32_e32 v26, v232
	s_branch .LBB0_537
; __device__ void phase_scan(int l, unsigned char* lds) {
;     ...
;             for (int t8 = 0; t8 < (jb.nsteps < 16 ? jb.nsteps : 16); t8 += 4) {
; #pragma unroll
;                 for (int u = 0; u < 4; ++u) {
;                     const int tt = t8 + u;
;                     const unsigned char* tb = buf + tt * SC_TOKB + c0 * 4;
;                     const f32x4 a = *(const f32x4*)(tb), w = *(const f32x4*)(tb + 256), b = *(const f32x4*)(tb + 512), k = *(const f32x4*)(tb + 768), r = *(const f32x4*)(tb + 1024);
;                     const float v = *(const float*)(buf + tt * SC_TOKB + 1280 + rl * 4);
;                     const f32x2 a01 = (f32x2){a[0], a[1]}, a23 = (f32x2){a[2], a[3]}, w01 = (f32x2){w[0], w[1]}, w23 = (f32x2){w[2], w[3]}, b01 = (f32x2){b[0], b[1]}, b23 = (f32x2){b[2], b[3]};
;                     const f32x2 k01 = (f32x2){k[0], k[1]}, k23 = (f32x2){k[2], k[3]}, r01 = (f32x2){r[0], r[1]}, r23 = (f32x2){r[2], r[3]};
;                     const f32x2 pa = s01 * a01 + s23 * a23;
;                     const float sa = allsum16(pa.x + pa.y);
;                     const f32x2 kv01 = k01 * v, kv23 = k23 * v;
;                     s01 = s01 * w01 + (b01 * sa + kv01); s23 = s23 * w23 + (b23 * sa + kv23);
;                     const f32x2 py = s01 * r01 + s23 * r23;
;                     const float y = allsum16(py.x + py.y);
;                     if ((lane & 15) == (tt & 15)) yreg0 = y;
.Lscan0_n8:
	ds_read_b128 v[120:123], v217 offset:0
	ds_read_b128 v[124:127], v217 offset:256
	ds_read_b128 v[128:131], v217 offset:512
	ds_read_b128 v[132:135], v217 offset:768
	ds_read_b128 v[136:139], v217 offset:1024
	ds_read_b32 v28, v218 offset:0
	ds_read_b128 v[146:149], v217 offset:1344
	ds_read_b128 v[150:153], v217 offset:1600
	ds_read_b128 v[154:157], v217 offset:1856
	ds_read_b128 v[158:161], v217 offset:2112
	ds_read_b128 v[162:165], v217 offset:2368
	ds_read_b32 v30, v218 offset:1344
	s_waitcnt lgkmcnt(6)
	ds_read_b128 v[32:35], v217 offset:2688
	ds_read_b128 v[36:39], v217 offset:2944
	ds_read_b128 v[40:43], v217 offset:3200
	ds_read_b128 v[44:47], v217 offset:3456
	ds_read_b128 v[48:51], v217 offset:3712
	ds_read_b32 v92, v218 offset:2688
	v_pk_mul_f32 v[206:207], v[24:25], v[122:123]
	v_pk_fma_f32 v[206:207], v[22:23], v[120:121], v[206:207]
	s_nop 0
	v_add_f32_e32 v214, v206, v207
	s_nop 0
	v_pk_mul_f32 v[210:211], v[132:133], v[28:29] op_sel_hi:[1,0]
	v_add_f32_dpp v214, v214, v214 quad_perm:[1,0,3,2] row_mask:0xf bank_mask:0xf bound_ctrl:1
	s_nop 0
	v_pk_mul_f32 v[212:213], v[134:135], v[28:29] op_sel_hi:[1,0]
	v_add_f32_dpp v214, v214, v214 quad_perm:[2,3,0,1] row_mask:0xf bank_mask:0xf bound_ctrl:1
	v_pk_fma_f32 v[210:211], v[22:23], v[124:125], v[210:211]
	v_pk_fma_f32 v[212:213], v[24:25], v[126:127], v[212:213]
	v_add_f32_dpp v214, v214, v214 row_half_mirror row_mask:0xf bank_mask:0xf bound_ctrl:1
	s_nop 1
	v_add_f32_dpp v214, v214, v214 row_mirror row_mask:0xf bank_mask:0xf bound_ctrl:1
	v_pk_fma_f32 v[22:23], v[128:129], v[214:215], v[210:211] op_sel_hi:[1,0,1]
	v_pk_fma_f32 v[24:25], v[130:131], v[214:215], v[212:213] op_sel_hi:[1,0,1]
	s_waitcnt lgkmcnt(6)
	ds_read_b128 v[186:189], v217 offset:4032
	ds_read_b128 v[190:193], v217 offset:4288
	ds_read_b128 v[194:197], v217 offset:4544
	ds_read_b128 v[198:201], v217 offset:4800
	ds_read_b128 v[202:205], v217 offset:5056
	ds_read_b32 v52, v218 offset:4032
	v_pk_mul_f32 v[206:207], v[24:25], v[148:149]
	v_pk_fma_f32 v[206:207], v[22:23], v[146:147], v[206:207]
	v_pk_mul_f32 v[208:209], v[24:25], v[138:139]
	v_add_f32_e32 v214, v206, v207
	v_pk_fma_f32 v[208:209], v[22:23], v[136:137], v[208:209]
	v_pk_mul_f32 v[210:211], v[158:159], v[30:31] op_sel_hi:[1,0]
	v_add_f32_dpp v214, v214, v214 quad_perm:[1,0,3,2] row_mask:0xf bank_mask:0xf bound_ctrl:1
	v_add_f32_e32 v232, v208, v209
	v_pk_mul_f32 v[212:213], v[160:161], v[30:31] op_sel_hi:[1,0]
	v_add_f32_dpp v214, v214, v214 quad_perm:[2,3,0,1] row_mask:0xf bank_mask:0xf bound_ctrl:1
	v_pk_fma_f32 v[210:211], v[22:23], v[150:151], v[210:211]
	v_pk_fma_f32 v[212:213], v[24:25], v[152:153], v[212:213]
	v_add_f32_dpp v214, v214, v214 row_half_mirror row_mask:0xf bank_mask:0xf bound_ctrl:1
	s_nop 1
	v_add_f32_dpp v214, v214, v214 row_mirror row_mask:0xf bank_mask:0xf bound_ctrl:1
	v_pk_fma_f32 v[22:23], v[154:155], v[214:215], v[210:211] op_sel_hi:[1,0,1]
	v_pk_fma_f32 v[24:25], v[156:157], v[214:215], v[212:213] op_sel_hi:[1,0,1]
	s_waitcnt lgkmcnt(6)
	ds_read_b128 v[120:123], v217 offset:5376
	ds_read_b128 v[124:127], v217 offset:5632
	ds_read_b128 v[128:131], v217 offset:5888
	ds_read_b128 v[132:135], v217 offset:6144
	ds_read_b128 v[136:139], v217 offset:6400
	ds_read_b32 v28, v218 offset:5376
	v_pk_mul_f32 v[206:207], v[24:25], v[34:35]
	v_pk_fma_f32 v[206:207], v[22:23], v[32:33], v[206:207]
	v_pk_mul_f32 v[208:209], v[24:25], v[164:165]
	v_add_f32_e32 v214, v206, v207
	v_pk_fma_f32 v[208:209], v[22:23], v[162:163], v[208:209]
	v_pk_mul_f32 v[210:211], v[44:45], v[92:93] op_sel_hi:[1,0]
	v_add_f32_dpp v214, v214, v214 quad_perm:[1,0,3,2] row_mask:0xf bank_mask:0xf bound_ctrl:1
	v_add_f32_e32 v233, v208, v209
	v_pk_mul_f32 v[212:213], v[46:47], v[92:93] op_sel_hi:[1,0]
	v_add_f32_dpp v214, v214, v214 quad_perm:[2,3,0,1] row_mask:0xf bank_mask:0xf bound_ctrl:1
	v_pk_fma_f32 v[210:211], v[22:23], v[36:37], v[210:211]
	v_pk_fma_f32 v[212:213], v[24:25], v[38:39], v[212:213]
	v_add_f32_dpp v214, v214, v214 row_half_mirror row_mask:0xf bank_mask:0xf bound_ctrl:1
	s_nop 1
	v_add_f32_dpp v214, v214, v214 row_mirror row_mask:0xf bank_mask:0xf bound_ctrl:1
	v_pk_fma_f32 v[22:23], v[40:41], v[214:215], v[210:211] op_sel_hi:[1,0,1]
	v_pk_fma_f32 v[24:25], v[42:43], v[214:215], v[212:213] op_sel_hi:[1,0,1]
	s_waitcnt lgkmcnt(6)
	ds_read_b128 v[146:149], v217 offset:6720
	ds_read_b128 v[150:153], v217 offset:6976
	ds_read_b128 v[154:157], v217 offset:7232
	ds_read_b128 v[158:161], v217 offset:7488
	ds_read_b128 v[162:165], v217 offset:7744
	ds_read_b32 v30, v218 offset:6720
	v_pk_mul_f32 v[206:207], v[24:25], v[188:189]
	v_pk_fma_f32 v[206:207], v[22:23], v[186:187], v[206:207]
	v_pk_mul_f32 v[208:209], v[24:25], v[50:51]
	v_add_f32_e32 v214, v206, v207
	v_pk_fma_f32 v[208:209], v[22:23], v[48:49], v[208:209]
	v_pk_mul_f32 v[210:211], v[198:199], v[52:53] op_sel_hi:[1,0]
	v_add_f32_dpp v214, v214, v214 quad_perm:[1,0,3,2] row_mask:0xf bank_mask:0xf bound_ctrl:1
	v_add_f32_e32 v234, v208, v209
	v_pk_mul_f32 v[212:213], v[200:201], v[52:53] op_sel_hi:[1,0]
	v_add_f32_dpp v214, v214, v214 quad_perm:[2,3,0,1] row_mask:0xf bank_mask:0xf bound_ctrl:1
	v_pk_fma_f32 v[210:211], v[22:23], v[190:191], v[210:211]
	v_pk_fma_f32 v[212:213], v[24:25], v[192:193], v[212:213]
	v_add_f32_dpp v214, v214, v214 row_half_mirror row_mask:0xf bank_mask:0xf bound_ctrl:1
	s_nop 1
	v_add_f32_dpp v214, v214, v214 row_mirror row_mask:0xf bank_mask:0xf bound_ctrl:1
	v_pk_fma_f32 v[22:23], v[194:195], v[214:215], v[210:211] op_sel_hi:[1,0,1]
	v_pk_fma_f32 v[24:25], v[196:197], v[214:215], v[212:213] op_sel_hi:[1,0,1]
	s_waitcnt lgkmcnt(6)
; __device__ void phase_scan(int l, unsigned char* lds) {
;     ...
;             for (int t8 = 0; t8 < (jb.nsteps < 16 ? jb.nsteps : 16); t8 += 4) {
; #pragma unroll
;                 for (int u = 0; u < 4; ++u) {
;                     const int tt = t8 + u;
;                     const unsigned char* tb = buf + tt * SC_TOKB + c0 * 4;
;                     const f32x4 a = *(const f32x4*)(tb), w = *(const f32x4*)(tb + 256), b = *(const f32x4*)(tb + 512), k = *(const f32x4*)(tb + 768), r = *(const f32x4*)(tb + 1024);
;                     const float v = *(const float*)(buf + tt * SC_TOKB + 1280 + rl * 4);
;                     const f32x2 a01 = (f32x2){a[0], a[1]}, a23 = (f32x2){a[2], a[3]}, w01 = (f32x2){w[0], w[1]}, w23 = (f32x2){w[2], w[3]}, b01 = (f32x2){b[0], b[1]}, b23 = (f32x2){b[2], b[3]};
;                     const f32x2 k01 = (f32x2){k[0], k[1]}, k23 = (f32x2){k[2], k[3]}, r01 = (f32x2){r[0], r[1]}, r23 = (f32x2){r[2], r[3]};
;                     const f32x2 pa = s01 * a01 + s23 * a23;
;                     const float sa = allsum16(pa.x + pa.y);
;                     const f32x2 kv01 = k01 * v, kv23 = k23 * v;
;                     s01 = s01 * w01 + (b01 * sa + kv01); s23 = s23 * w23 + (b23 * sa + kv23);
;                     const f32x2 py = s01 * r01 + s23 * r23;
;                     const float y = allsum16(py.x + py.y);
;                     if ((lane & 15) == (tt & 15)) yreg0 = y;
	ds_read_b128 v[32:35], v217 offset:8064
	ds_read_b128 v[36:39], v217 offset:8320
	ds_read_b128 v[40:43], v217 offset:8576
	ds_read_b128 v[44:47], v217 offset:8832
	ds_read_b128 v[48:51], v217 offset:9088
	ds_read_b32 v92, v218 offset:8064
	v_pk_mul_f32 v[206:207], v[24:25], v[122:123]
	v_pk_fma_f32 v[206:207], v[22:23], v[120:121], v[206:207]
	v_pk_mul_f32 v[208:209], v[24:25], v[204:205]
	v_add_f32_e32 v214, v206, v207
	v_pk_fma_f32 v[208:209], v[22:23], v[202:203], v[208:209]
	v_pk_mul_f32 v[210:211], v[132:133], v[28:29] op_sel_hi:[1,0]
	v_add_f32_dpp v214, v214, v214 quad_perm:[1,0,3,2] row_mask:0xf bank_mask:0xf bound_ctrl:1
	v_add_f32_e32 v235, v208, v209
	v_pk_mul_f32 v[212:213], v[134:135], v[28:29] op_sel_hi:[1,0]
	v_add_f32_dpp v214, v214, v214 quad_perm:[2,3,0,1] row_mask:0xf bank_mask:0xf bound_ctrl:1
	v_pk_fma_f32 v[210:211], v[22:23], v[124:125], v[210:211]
	v_pk_fma_f32 v[212:213], v[24:25], v[126:127], v[212:213]
	v_add_f32_dpp v214, v214, v214 row_half_mirror row_mask:0xf bank_mask:0xf bound_ctrl:1
	s_nop 1
	v_add_f32_dpp v214, v214, v214 row_mirror row_mask:0xf bank_mask:0xf bound_ctrl:1
	v_pk_fma_f32 v[22:23], v[128:129], v[214:215], v[210:211] op_sel_hi:[1,0,1]
	v_pk_fma_f32 v[24:25], v[130:131], v[214:215], v[212:213] op_sel_hi:[1,0,1]
	s_waitcnt lgkmcnt(6)
	ds_read_b128 v[186:189], v217 offset:9408
	ds_read_b128 v[190:193], v217 offset:9664
	ds_read_b128 v[194:197], v217 offset:9920
	ds_read_b128 v[198:201], v217 offset:10176
	ds_read_b128 v[202:205], v217 offset:10432
	ds_read_b32 v52, v218 offset:9408
	v_pk_mul_f32 v[206:207], v[24:25], v[148:149]
	v_pk_fma_f32 v[206:207], v[22:23], v[146:147], v[206:207]
	v_pk_mul_f32 v[208:209], v[24:25], v[138:139]
	v_add_f32_e32 v214, v206, v207
	v_pk_fma_f32 v[208:209], v[22:23], v[136:137], v[208:209]
	v_pk_mul_f32 v[210:211], v[158:159], v[30:31] op_sel_hi:[1,0]
	v_add_f32_dpp v214, v214, v214 quad_perm:[1,0,3,2] row_mask:0xf bank_mask:0xf bound_ctrl:1
	v_add_f32_e32 v236, v208, v209
	v_pk_mul_f32 v[212:213], v[160:161], v[30:31] op_sel_hi:[1,0]
	v_add_f32_dpp v214, v214, v214 quad_perm:[2,3,0,1] row_mask:0xf bank_mask:0xf bound_ctrl:1
	v_pk_fma_f32 v[210:211], v[22:23], v[150:151], v[210:211]
	v_pk_fma_f32 v[212:213], v[24:25], v[152:153], v[212:213]
	v_add_f32_dpp v214, v214, v214 row_half_mirror row_mask:0xf bank_mask:0xf bound_ctrl:1
	s_nop 1
	v_add_f32_dpp v214, v214, v214 row_mirror row_mask:0xf bank_mask:0xf bound_ctrl:1
	v_pk_fma_f32 v[22:23], v[154:155], v[214:215], v[210:211] op_sel_hi:[1,0,1]
	v_pk_fma_f32 v[24:25], v[156:157], v[214:215], v[212:213] op_sel_hi:[1,0,1]
	s_waitcnt lgkmcnt(6)
	v_pk_mul_f32 v[206:207], v[24:25], v[34:35]
	v_pk_fma_f32 v[206:207], v[22:23], v[32:33], v[206:207]
	v_pk_mul_f32 v[208:209], v[24:25], v[164:165]
	v_add_f32_e32 v214, v206, v207
	v_pk_fma_f32 v[208:209], v[22:23], v[162:163], v[208:209]
	v_pk_mul_f32 v[210:211], v[44:45], v[92:93] op_sel_hi:[1,0]
	v_add_f32_dpp v214, v214, v214 quad_perm:[1,0,3,2] row_mask:0xf bank_mask:0xf bound_ctrl:1
	v_add_f32_e32 v237, v208, v209
	v_pk_mul_f32 v[212:213], v[46:47], v[92:93] op_sel_hi:[1,0]
	v_add_f32_dpp v214, v214, v214 quad_perm:[2,3,0,1] row_mask:0xf bank_mask:0xf bound_ctrl:1
	v_pk_fma_f32 v[210:211], v[22:23], v[36:37], v[210:211]
	v_pk_fma_f32 v[212:213], v[24:25], v[38:39], v[212:213]
	v_add_f32_dpp v214, v214, v214 row_half_mirror row_mask:0xf bank_mask:0xf bound_ctrl:1
	s_nop 1
	v_add_f32_dpp v214, v214, v214 row_mirror row_mask:0xf bank_mask:0xf bound_ctrl:1
	v_pk_fma_f32 v[22:23], v[40:41], v[214:215], v[210:211] op_sel_hi:[1,0,1]
	v_pk_fma_f32 v[24:25], v[42:43], v[214:215], v[212:213] op_sel_hi:[1,0,1]
	s_waitcnt lgkmcnt(0)
; __device__ void phase_scan(int l, unsigned char* lds) {
;     ...
;             for (int t8 = 0; t8 < (jb.nsteps < 16 ? jb.nsteps : 16); t8 += 4) {
; #pragma unroll
;                 for (int u = 0; u < 4; ++u) {
;                     const int tt = t8 + u;
;                     const unsigned char* tb = buf + tt * SC_TOKB + c0 * 4;
;                     const f32x4 a = *(const f32x4*)(tb), w = *(const f32x4*)(tb + 256), b = *(const f32x4*)(tb + 512), k = *(const f32x4*)(tb + 768), r = *(const f32x4*)(tb + 1024);
;                     const float v = *(const float*)(buf + tt * SC_TOKB + 1280 + rl * 4);
;                     const f32x2 a01 = (f32x2){a[0], a[1]}, a23 = (f32x2){a[2], a[3]}, w01 = (f32x2){w[0], w[1]}, w23 = (f32x2){w[2], w[3]}, b01 = (f32x2){b[0], b[1]}, b23 = (f32x2){b[2], b[3]};
;                     const f32x2 k01 = (f32x2){k[0], k[1]}, k23 = (f32x2){k[2], k[3]}, r01 = (f32x2){r[0], r[1]}, r23 = (f32x2){r[2], r[3]};
;                     const f32x2 pa = s01 * a01 + s23 * a23;
;                     const float sa = allsum16(pa.x + pa.y);
;                     const f32x2 kv01 = k01 * v, kv23 = k23 * v;
;                     s01 = s01 * w01 + (b01 * sa + kv01); s23 = s23 * w23 + (b23 * sa + kv23);
;                     const f32x2 py = s01 * r01 + s23 * r23;
;                     const float y = allsum16(py.x + py.y);
;                     if ((lane & 15) == (tt & 15)) yreg0 = y;
;                 }
;             }
	v_pk_mul_f32 v[206:207], v[24:25], v[188:189]
	v_pk_fma_f32 v[206:207], v[22:23], v[186:187], v[206:207]
	v_pk_mul_f32 v[208:209], v[24:25], v[50:51]
	v_add_f32_e32 v214, v206, v207
	v_pk_fma_f32 v[208:209], v[22:23], v[48:49], v[208:209]
	v_pk_mul_f32 v[210:211], v[198:199], v[52:53] op_sel_hi:[1,0]
	v_add_f32_dpp v214, v214, v214 quad_perm:[1,0,3,2] row_mask:0xf bank_mask:0xf bound_ctrl:1
	v_add_f32_e32 v238, v208, v209
	v_pk_mul_f32 v[212:213], v[200:201], v[52:53] op_sel_hi:[1,0]
	v_add_f32_dpp v214, v214, v214 quad_perm:[2,3,0,1] row_mask:0xf bank_mask:0xf bound_ctrl:1
	v_pk_fma_f32 v[210:211], v[22:23], v[190:191], v[210:211]
	v_pk_fma_f32 v[212:213], v[24:25], v[192:193], v[212:213]
	v_add_f32_dpp v214, v214, v214 row_half_mirror row_mask:0xf bank_mask:0xf bound_ctrl:1
	s_nop 1
	v_add_f32_dpp v214, v214, v214 row_mirror row_mask:0xf bank_mask:0xf bound_ctrl:1
	v_pk_fma_f32 v[22:23], v[194:195], v[214:215], v[210:211] op_sel_hi:[1,0,1]
	v_pk_fma_f32 v[24:25], v[196:197], v[214:215], v[212:213] op_sel_hi:[1,0,1]
	v_pk_mul_f32 v[208:209], v[24:25], v[204:205]
	v_pk_fma_f32 v[208:209], v[22:23], v[202:203], v[208:209]
	v_add_f32_e32 v239, v208, v209
	s_mov_b32 s98, 0xaaaaaaaa
	s_mov_b32 s99, 0xaaaaaaaa
	v_cndmask_b32_e64 v249, v233, v232, s[98:99]
	v_cndmask_b32_e64 v232, v232, v233, s[98:99]
	v_cndmask_b32_e64 v251, v235, v234, s[98:99]
	v_cndmask_b32_e64 v234, v234, v235, s[98:99]
	v_add_f32_dpp v232, v249, v232 quad_perm:[1,0,3,2] row_mask:0xf bank_mask:0xf bound_ctrl:1
	v_cndmask_b32_e64 v249, v237, v236, s[98:99]
	v_cndmask_b32_e64 v236, v236, v237, s[98:99]
	v_add_f32_dpp v234, v251, v234 quad_perm:[1,0,3,2] row_mask:0xf bank_mask:0xf bound_ctrl:1
	v_cndmask_b32_e64 v251, v239, v238, s[98:99]
	v_cndmask_b32_e64 v238, v238, v239, s[98:99]
	v_add_f32_dpp v236, v249, v236 quad_perm:[1,0,3,2] row_mask:0xf bank_mask:0xf bound_ctrl:1
	v_cndmask_b32_e64 v249, v241, v240, s[98:99]
	v_cndmask_b32_e64 v240, v240, v241, s[98:99]
	v_add_f32_dpp v238, v251, v238 quad_perm:[1,0,3,2] row_mask:0xf bank_mask:0xf bound_ctrl:1
	v_cndmask_b32_e64 v251, v243, v242, s[98:99]
	v_cndmask_b32_e64 v242, v242, v243, s[98:99]
	v_add_f32_dpp v240, v249, v240 quad_perm:[1,0,3,2] row_mask:0xf bank_mask:0xf bound_ctrl:1
	v_cndmask_b32_e64 v249, v245, v244, s[98:99]
	v_cndmask_b32_e64 v244, v244, v245, s[98:99]
	v_add_f32_dpp v242, v251, v242 quad_perm:[1,0,3,2] row_mask:0xf bank_mask:0xf bound_ctrl:1
	v_cndmask_b32_e64 v251, v247, v246, s[98:99]
	v_cndmask_b32_e64 v246, v246, v247, s[98:99]
	v_add_f32_dpp v244, v249, v244 quad_perm:[1,0,3,2] row_mask:0xf bank_mask:0xf bound_ctrl:1
	s_nop 1
	v_add_f32_dpp v246, v251, v246 quad_perm:[1,0,3,2] row_mask:0xf bank_mask:0xf bound_ctrl:1
	s_mov_b32 s98, 0xcccccccc
	s_mov_b32 s99, 0xcccccccc
	v_cndmask_b32_e64 v249, v234, v232, s[98:99]
	v_cndmask_b32_e64 v232, v232, v234, s[98:99]
	v_cndmask_b32_e64 v251, v238, v236, s[98:99]
	v_cndmask_b32_e64 v236, v236, v238, s[98:99]
	v_add_f32_dpp v232, v249, v232 quad_perm:[2,3,0,1] row_mask:0xf bank_mask:0xf bound_ctrl:1
	v_cndmask_b32_e64 v249, v242, v240, s[98:99]
	v_cndmask_b32_e64 v240, v240, v242, s[98:99]
	v_add_f32_dpp v236, v251, v236 quad_perm:[2,3,0,1] row_mask:0xf bank_mask:0xf bound_ctrl:1
	v_cndmask_b32_e64 v251, v246, v244, s[98:99]
	v_cndmask_b32_e64 v244, v244, v246, s[98:99]
	v_add_f32_dpp v240, v249, v240 quad_perm:[2,3,0,1] row_mask:0xf bank_mask:0xf bound_ctrl:1
	s_nop 1
	v_add_f32_dpp v244, v251, v244 quad_perm:[2,3,0,1] row_mask:0xf bank_mask:0xf bound_ctrl:1
	s_mov_b32 s98, 0xf0f0f0f0
	s_mov_b32 s99, 0xf0f0f0f0
	v_cndmask_b32_e64 v249, v236, v232, s[98:99]
	v_cndmask_b32_e64 v232, v232, v236, s[98:99]
	v_cndmask_b32_e64 v251, v244, v240, s[98:99]
	v_cndmask_b32_e64 v240, v240, v244, s[98:99]
	v_add_f32_dpp v232, v249, v232 row_shr:4 row_mask:0xf bank_mask:0xa
	v_add_f32_dpp v232, v249, v232 row_shl:4 row_mask:0xf bank_mask:0x5
	s_nop 1
	v_add_f32_dpp v240, v251, v240 row_shr:4 row_mask:0xf bank_mask:0xa
	v_add_f32_dpp v240, v251, v240 row_shl:4 row_mask:0xf bank_mask:0x5
	s_mov_b32 s98, 0xff00ff00
	s_mov_b32 s99, 0xff00ff00
	v_cndmask_b32_e64 v249, v240, v232, s[98:99]
	v_cndmask_b32_e64 v232, v232, v240, s[98:99]
	s_nop 1
	v_add_f32_dpp v232, v249, v232 row_ror:8 row_mask:0xf bank_mask:0xf bound_ctrl:1
	v_mov_b32_e32 v18, v232

; __device__ void phase_scan(int l, unsigned char* lds) {
;     ...
;         const unsigned char* buf = lds + (it % 3) * SC_BUFB;
;     ...
;             float yreg0 = 0.f, yreg1 = 0.f;
;             for (int t8 = 0; t8 < (jb.nsteps < 16 ? jb.nsteps : 16); t8 += 4) {
; #pragma unroll
;                 for (int u = 0; u < 4; ++u) {
;                     const int tt = t8 + u;
;                     const unsigned char* tb = buf + tt * SC_TOKB + c0 * 4;
;                     const f32x4 a = *(const f32x4*)(tb), w = *(const f32x4*)(tb + 256), b = *(const f32x4*)(tb + 512), k = *(const f32x4*)(tb + 768), r = *(const f32x4*)(tb + 1024);
;                     const float v = *(const float*)(buf + tt * SC_TOKB + 1280 + rl * 4);
;                     const f32x2 a01 = (f32x2){a[0], a[1]}, a23 = (f32x2){a[2], a[3]}, w01 = (f32x2){w[0], w[1]}, w23 = (f32x2){w[2], w[3]}, b01 = (f32x2){b[0], b[1]}, b23 = (f32x2){b[2], b[3]};
;                     const f32x2 k01 = (f32x2){k[0], k[1]}, k23 = (f32x2){k[2], k[3]}, r01 = (f32x2){r[0], r[1]}, r23 = (f32x2){r[2], r[3]};
;                     const f32x2 pa = s01 * a01 + s23 * a23;
;                     const float sa = allsum16(pa.x + pa.y);
;                     const f32x2 kv01 = k01 * v, kv23 = k23 * v;
;                     s01 = s01 * w01 + (b01 * sa + kv01); s23 = s23 * w23 + (b23 * sa + kv23);
;                     const f32x2 py = s01 * r01 + s23 * r23;
;                     const float y = allsum16(py.x + py.y);
;                     if ((lane & 15) == (tt & 15)) yreg0 = y;
.LBB0_1673:
	s_mul_hi_u32 s17, s84, 0xaaaaaaab
	s_lshr_b32 s17, s17, 1
	s_mul_i32 s17, s17, 0xfffe0800
	s_xor_b64 s[18:19], s[18:19], -1
	v_add_u32_e32 v217, s17, v110
	v_add_u32_e32 v218, s17, v111
	v_mov_b32_e32 v18, 0
	v_mov_b32_e32 v26, 0
	s_cmp_eq_u32 s44, 32
	s_cbranch_scc0 .Lscan1_n8
	ds_read_b128 v[120:123], v217 offset:0
	ds_read_b128 v[124:127], v217 offset:256
	ds_read_b128 v[128:131], v217 offset:512
	ds_read_b128 v[132:135], v217 offset:768
	ds_read_b128 v[136:139], v217 offset:1024
	ds_read_b32 v28, v218 offset:0
	ds_read_b128 v[146:149], v217 offset:1344
	ds_read_b128 v[150:153], v217 offset:1600
	ds_read_b128 v[154:157], v217 offset:1856
	ds_read_b128 v[158:161], v217 offset:2112
	ds_read_b128 v[162:165], v217 offset:2368
	ds_read_b32 v30, v218 offset:1344
	s_waitcnt lgkmcnt(6)
	ds_read_b128 v[32:35], v217 offset:2688
	ds_read_b128 v[36:39], v217 offset:2944
	ds_read_b128 v[40:43], v217 offset:3200
	ds_read_b128 v[44:47], v217 offset:3456
	ds_read_b128 v[48:51], v217 offset:3712
	ds_read_b32 v92, v218 offset:2688
	v_pk_mul_f32 v[206:207], v[24:25], v[122:123]
	v_pk_fma_f32 v[206:207], v[22:23], v[120:121], v[206:207]
	s_nop 0
	v_add_f32_e32 v214, v206, v207
	s_nop 0
	v_pk_mul_f32 v[210:211], v[132:133], v[28:29] op_sel_hi:[1,0]
	v_add_f32_dpp v214, v214, v214 quad_perm:[1,0,3,2] row_mask:0xf bank_mask:0xf bound_ctrl:1
	s_nop 0
	v_pk_mul_f32 v[212:213], v[134:135], v[28:29] op_sel_hi:[1,0]
	v_add_f32_dpp v214, v214, v214 quad_perm:[2,3,0,1] row_mask:0xf bank_mask:0xf bound_ctrl:1
	v_pk_fma_f32 v[210:211], v[22:23], v[124:125], v[210:211]
	v_pk_fma_f32 v[212:213], v[24:25], v[126:127], v[212:213]
	v_add_f32_dpp v214, v214, v214 row_half_mirror row_mask:0xf bank_mask:0xf bound_ctrl:1
	s_nop 1
	v_add_f32_dpp v214, v214, v214 row_mirror row_mask:0xf bank_mask:0xf bound_ctrl:1
	v_pk_fma_f32 v[22:23], v[128:129], v[214:215], v[210:211] op_sel_hi:[1,0,1]
	v_pk_fma_f32 v[24:25], v[130:131], v[214:215], v[212:213] op_sel_hi:[1,0,1]
	s_waitcnt lgkmcnt(6)
	ds_read_b128 v[186:189], v217 offset:4032
	ds_read_b128 v[190:193], v217 offset:4288
	ds_read_b128 v[194:197], v217 offset:4544
	ds_read_b128 v[198:201], v217 offset:4800
	ds_read_b128 v[202:205], v217 offset:5056
	ds_read_b32 v52, v218 offset:4032
	v_pk_mul_f32 v[206:207], v[24:25], v[148:149]
	v_pk_fma_f32 v[206:207], v[22:23], v[146:147], v[206:207]
	v_pk_mul_f32 v[208:209], v[24:25], v[138:139]
	v_add_f32_e32 v214, v206, v207
	v_pk_fma_f32 v[208:209], v[22:23], v[136:137], v[208:209]
	v_pk_mul_f32 v[210:211], v[158:159], v[30:31] op_sel_hi:[1,0]
	v_add_f32_dpp v214, v214, v214 quad_perm:[1,0,3,2] row_mask:0xf bank_mask:0xf bound_ctrl:1
	v_add_f32_e32 v232, v208, v209
	v_pk_mul_f32 v[212:213], v[160:161], v[30:31] op_sel_hi:[1,0]
	v_add_f32_dpp v214, v214, v214 quad_perm:[2,3,0,1] row_mask:0xf bank_mask:0xf bound_ctrl:1
	v_pk_fma_f32 v[210:211], v[22:23], v[150:151], v[210:211]
	v_pk_fma_f32 v[212:213], v[24:25], v[152:153], v[212:213]
	v_add_f32_dpp v214, v214, v214 row_half_mirror row_mask:0xf bank_mask:0xf bound_ctrl:1
	s_nop 1
	v_add_f32_dpp v214, v214, v214 row_mirror row_mask:0xf bank_mask:0xf bound_ctrl:1
	v_pk_fma_f32 v[22:23], v[154:155], v[214:215], v[210:211] op_sel_hi:[1,0,1]
	v_pk_fma_f32 v[24:25], v[156:157], v[214:215], v[212:213] op_sel_hi:[1,0,1]
	s_waitcnt lgkmcnt(6)
	ds_read_b128 v[120:123], v217 offset:5376
	ds_read_b128 v[124:127], v217 offset:5632
	ds_read_b128 v[128:131], v217 offset:5888
	ds_read_b128 v[132:135], v217 offset:6144
	ds_read_b128 v[136:139], v217 offset:6400
	ds_read_b32 v28, v218 offset:5376
	v_pk_mul_f32 v[206:207], v[24:25], v[34:35]
	v_pk_fma_f32 v[206:207], v[22:23], v[32:33], v[206:207]
	v_pk_mul_f32 v[208:209], v[24:25], v[164:165]
	v_add_f32_e32 v214, v206, v207
	v_pk_fma_f32 v[208:209], v[22:23], v[162:163], v[208:209]
	v_pk_mul_f32 v[210:211], v[44:45], v[92:93] op_sel_hi:[1,0]
	v_add_f32_dpp v214, v214, v214 quad_perm:[1,0,3,2] row_mask:0xf bank_mask:0xf bound_ctrl:1
	v_add_f32_e32 v233, v208, v209
	v_pk_mul_f32 v[212:213], v[46:47], v[92:93] op_sel_hi:[1,0]
	v_add_f32_dpp v214, v214, v214 quad_perm:[2,3,0,1] row_mask:0xf bank_mask:0xf bound_ctrl:1
	v_pk_fma_f32 v[210:211], v[22:23], v[36:37], v[210:211]
	v_pk_fma_f32 v[212:213], v[24:25], v[38:39], v[212:213]
	v_add_f32_dpp v214, v214, v214 row_half_mirror row_mask:0xf bank_mask:0xf bound_ctrl:1
	s_nop 1
	v_add_f32_dpp v214, v214, v214 row_mirror row_mask:0xf bank_mask:0xf bound_ctrl:1
	v_pk_fma_f32 v[22:23], v[40:41], v[214:215], v[210:211] op_sel_hi:[1,0,1]
	v_pk_fma_f32 v[24:25], v[42:43], v[214:215], v[212:213] op_sel_hi:[1,0,1]
	s_waitcnt lgkmcnt(6)
	ds_read_b128 v[146:149], v217 offset:6720
	ds_read_b128 v[150:153], v217 offset:6976
	ds_read_b128 v[154:157], v217 offset:7232
	ds_read_b128 v[158:161], v217 offset:7488
	ds_read_b128 v[162:165], v217 offset:7744
	ds_read_b32 v30, v218 offset:6720
	v_pk_mul_f32 v[206:207], v[24:25], v[188:189]
	v_pk_fma_f32 v[206:207], v[22:23], v[186:187], v[206:207]
	v_pk_mul_f32 v[208:209], v[24:25], v[50:51]
	v_add_f32_e32 v214, v206, v207
	v_pk_fma_f32 v[208:209], v[22:23], v[48:49], v[208:209]
	v_pk_mul_f32 v[210:211], v[198:199], v[52:53] op_sel_hi:[1,0]
	v_add_f32_dpp v214, v214, v214 quad_perm:[1,0,3,2] row_mask:0xf bank_mask:0xf bound_ctrl:1
	v_add_f32_e32 v234, v208, v209
	v_pk_mul_f32 v[212:213], v[200:201], v[52:53] op_sel_hi:[1,0]
	v_add_f32_dpp v214, v214, v214 quad_perm:[2,3,0,1] row_mask:0xf bank_mask:0xf bound_ctrl:1
	v_pk_fma_f32 v[210:211], v[22:23], v[190:191], v[210:211]
	v_pk_fma_f32 v[212:213], v[24:25], v[192:193], v[212:213]
	v_add_f32_dpp v214, v214, v214 row_half_mirror row_mask:0xf bank_mask:0xf bound_ctrl:1
	s_nop 1
	v_add_f32_dpp v214, v214, v214 row_mirror row_mask:0xf bank_mask:0xf bound_ctrl:1
	v_pk_fma_f32 v[22:23], v[194:195], v[214:215], v[210:211] op_sel_hi:[1,0,1]
	v_pk_fma_f32 v[24:25], v[196:197], v[214:215], v[212:213] op_sel_hi:[1,0,1]
	s_waitcnt lgkmcnt(6)
; __device__ void phase_scan(int l, unsigned char* lds) {
;     ...
;                     const f32x4 a = *(const f32x4*)(tb), w = *(const f32x4*)(tb + 256), b = *(const f32x4*)(tb + 512), k = *(const f32x4*)(tb + 768), r = *(const f32x4*)(tb + 1024);
;                     const float v = *(const float*)(buf + tt * SC_TOKB + 1280 + rl * 4);
;                     const f32x2 a01 = (f32x2){a[0], a[1]}, a23 = (f32x2){a[2], a[3]}, w01 = (f32x2){w[0], w[1]}, w23 = (f32x2){w[2], w[3]}, b01 = (f32x2){b[0], b[1]}, b23 = (f32x2){b[2], b[3]};
;                     const f32x2 k01 = (f32x2){k[0], k[1]}, k23 = (f32x2){k[2], k[3]}, r01 = (f32x2){r[0], r[1]}, r23 = (f32x2){r[2], r[3]};
;                     const f32x2 pa = s01 * a01 + s23 * a23;
;                     const float sa = allsum16(pa.x + pa.y);
;                     const f32x2 kv01 = k01 * v, kv23 = k23 * v;
;                     s01 = s01 * w01 + (b01 * sa + kv01); s23 = s23 * w23 + (b23 * sa + kv23);
;                     const f32x2 py = s01 * r01 + s23 * r23;
;                     const float y = allsum16(py.x + py.y);
;                     if ((lane & 15) == (tt & 15)) yreg0 = y;
	ds_read_b128 v[32:35], v217 offset:8064
	ds_read_b128 v[36:39], v217 offset:8320
	ds_read_b128 v[40:43], v217 offset:8576
	ds_read_b128 v[44:47], v217 offset:8832
	ds_read_b128 v[48:51], v217 offset:9088
	ds_read_b32 v92, v218 offset:8064
	v_pk_mul_f32 v[206:207], v[24:25], v[122:123]
	v_pk_fma_f32 v[206:207], v[22:23], v[120:121], v[206:207]
	v_pk_mul_f32 v[208:209], v[24:25], v[204:205]
	v_add_f32_e32 v214, v206, v207
	v_pk_fma_f32 v[208:209], v[22:23], v[202:203], v[208:209]
	v_pk_mul_f32 v[210:211], v[132:133], v[28:29] op_sel_hi:[1,0]
	v_add_f32_dpp v214, v214, v214 quad_perm:[1,0,3,2] row_mask:0xf bank_mask:0xf bound_ctrl:1
	v_add_f32_e32 v235, v208, v209
	v_pk_mul_f32 v[212:213], v[134:135], v[28:29] op_sel_hi:[1,0]
	v_add_f32_dpp v214, v214, v214 quad_perm:[2,3,0,1] row_mask:0xf bank_mask:0xf bound_ctrl:1
	v_pk_fma_f32 v[210:211], v[22:23], v[124:125], v[210:211]
	v_pk_fma_f32 v[212:213], v[24:25], v[126:127], v[212:213]
	v_add_f32_dpp v214, v214, v214 row_half_mirror row_mask:0xf bank_mask:0xf bound_ctrl:1
	s_nop 1
	v_add_f32_dpp v214, v214, v214 row_mirror row_mask:0xf bank_mask:0xf bound_ctrl:1
	v_pk_fma_f32 v[22:23], v[128:129], v[214:215], v[210:211] op_sel_hi:[1,0,1]
	v_pk_fma_f32 v[24:25], v[130:131], v[214:215], v[212:213] op_sel_hi:[1,0,1]
	s_waitcnt lgkmcnt(6)
	ds_read_b128 v[186:189], v217 offset:9408
	ds_read_b128 v[190:193], v217 offset:9664
	ds_read_b128 v[194:197], v217 offset:9920
	ds_read_b128 v[198:201], v217 offset:10176
	ds_read_b128 v[202:205], v217 offset:10432
	ds_read_b32 v52, v218 offset:9408
	v_pk_mul_f32 v[206:207], v[24:25], v[148:149]
	v_pk_fma_f32 v[206:207], v[22:23], v[146:147], v[206:207]
	v_pk_mul_f32 v[208:209], v[24:25], v[138:139]
	v_add_f32_e32 v214, v206, v207
	v_pk_fma_f32 v[208:209], v[22:23], v[136:137], v[208:209]
	v_pk_mul_f32 v[210:211], v[158:159], v[30:31] op_sel_hi:[1,0]
	v_add_f32_dpp v214, v214, v214 quad_perm:[1,0,3,2] row_mask:0xf bank_mask:0xf bound_ctrl:1
	v_add_f32_e32 v236, v208, v209
	v_pk_mul_f32 v[212:213], v[160:161], v[30:31] op_sel_hi:[1,0]
	v_add_f32_dpp v214, v214, v214 quad_perm:[2,3,0,1] row_mask:0xf bank_mask:0xf bound_ctrl:1
	v_pk_fma_f32 v[210:211], v[22:23], v[150:151], v[210:211]
	v_pk_fma_f32 v[212:213], v[24:25], v[152:153], v[212:213]
	v_add_f32_dpp v214, v214, v214 row_half_mirror row_mask:0xf bank_mask:0xf bound_ctrl:1
	s_nop 1
	v_add_f32_dpp v214, v214, v214 row_mirror row_mask:0xf bank_mask:0xf bound_ctrl:1
	v_pk_fma_f32 v[22:23], v[154:155], v[214:215], v[210:211] op_sel_hi:[1,0,1]
	v_pk_fma_f32 v[24:25], v[156:157], v[214:215], v[212:213] op_sel_hi:[1,0,1]
	s_waitcnt lgkmcnt(6)
	ds_read_b128 v[120:123], v217 offset:10752
	ds_read_b128 v[124:127], v217 offset:11008
	ds_read_b128 v[128:131], v217 offset:11264
	ds_read_b128 v[132:135], v217 offset:11520
	ds_read_b128 v[136:139], v217 offset:11776
	ds_read_b32 v28, v218 offset:10752
	v_pk_mul_f32 v[206:207], v[24:25], v[34:35]
	v_pk_fma_f32 v[206:207], v[22:23], v[32:33], v[206:207]
	v_pk_mul_f32 v[208:209], v[24:25], v[164:165]
	v_add_f32_e32 v214, v206, v207
	v_pk_fma_f32 v[208:209], v[22:23], v[162:163], v[208:209]
	v_pk_mul_f32 v[210:211], v[44:45], v[92:93] op_sel_hi:[1,0]
	v_add_f32_dpp v214, v214, v214 quad_perm:[1,0,3,2] row_mask:0xf bank_mask:0xf bound_ctrl:1
	v_add_f32_e32 v237, v208, v209
	v_pk_mul_f32 v[212:213], v[46:47], v[92:93] op_sel_hi:[1,0]
	v_add_f32_dpp v214, v214, v214 quad_perm:[2,3,0,1] row_mask:0xf bank_mask:0xf bound_ctrl:1
	v_pk_fma_f32 v[210:211], v[22:23], v[36:37], v[210:211]
	v_pk_fma_f32 v[212:213], v[24:25], v[38:39], v[212:213]
	v_add_f32_dpp v214, v214, v214 row_half_mirror row_mask:0xf bank_mask:0xf bound_ctrl:1
	s_nop 1
	v_add_f32_dpp v214, v214, v214 row_mirror row_mask:0xf bank_mask:0xf bound_ctrl:1
	v_pk_fma_f32 v[22:23], v[40:41], v[214:215], v[210:211] op_sel_hi:[1,0,1]
	v_pk_fma_f32 v[24:25], v[42:43], v[214:215], v[212:213] op_sel_hi:[1,0,1]
	s_waitcnt lgkmcnt(6)
	ds_read_b128 v[146:149], v217 offset:12096
	ds_read_b128 v[150:153], v217 offset:12352
	ds_read_b128 v[154:157], v217 offset:12608
	ds_read_b128 v[158:161], v217 offset:12864
	ds_read_b128 v[162:165], v217 offset:13120
	ds_read_b32 v30, v218 offset:12096
	v_pk_mul_f32 v[206:207], v[24:25], v[188:189]
	v_pk_fma_f32 v[206:207], v[22:23], v[186:187], v[206:207]
	v_pk_mul_f32 v[208:209], v[24:25], v[50:51]
	v_add_f32_e32 v214, v206, v207
	v_pk_fma_f32 v[208:209], v[22:23], v[48:49], v[208:209]
	v_pk_mul_f32 v[210:211], v[198:199], v[52:53] op_sel_hi:[1,0]
	v_add_f32_dpp v214, v214, v214 quad_perm:[1,0,3,2] row_mask:0xf bank_mask:0xf bound_ctrl:1
	v_add_f32_e32 v238, v208, v209
	v_pk_mul_f32 v[212:213], v[200:201], v[52:53] op_sel_hi:[1,0]
	v_add_f32_dpp v214, v214, v214 quad_perm:[2,3,0,1] row_mask:0xf bank_mask:0xf bound_ctrl:1
	v_pk_fma_f32 v[210:211], v[22:23], v[190:191], v[210:211]
	v_pk_fma_f32 v[212:213], v[24:25], v[192:193], v[212:213]
	v_add_f32_dpp v214, v214, v214 row_half_mirror row_mask:0xf bank_mask:0xf bound_ctrl:1
	s_nop 1
	v_add_f32_dpp v214, v214, v214 row_mirror row_mask:0xf bank_mask:0xf bound_ctrl:1
	v_pk_fma_f32 v[22:23], v[194:195], v[214:215], v[210:211] op_sel_hi:[1,0,1]
	v_pk_fma_f32 v[24:25], v[196:197], v[214:215], v[212:213] op_sel_hi:[1,0,1]
	s_waitcnt lgkmcnt(6)
; __device__ void phase_scan(int l, unsigned char* lds) {
;     ...
;                     const f32x4 a = *(const f32x4*)(tb), w = *(const f32x4*)(tb + 256), b = *(const f32x4*)(tb + 512), k = *(const f32x4*)(tb + 768), r = *(const f32x4*)(tb + 1024);
;                     const float v = *(const float*)(buf + tt * SC_TOKB + 1280 + rl * 4);
;                     const f32x2 a01 = (f32x2){a[0], a[1]}, a23 = (f32x2){a[2], a[3]}, w01 = (f32x2){w[0], w[1]}, w23 = (f32x2){w[2], w[3]}, b01 = (f32x2){b[0], b[1]}, b23 = (f32x2){b[2], b[3]};
;                     const f32x2 k01 = (f32x2){k[0], k[1]}, k23 = (f32x2){k[2], k[3]}, r01 = (f32x2){r[0], r[1]}, r23 = (f32x2){r[2], r[3]};
;                     const f32x2 pa = s01 * a01 + s23 * a23;
;                     const float sa = allsum16(pa.x + pa.y);
;                     const f32x2 kv01 = k01 * v, kv23 = k23 * v;
;                     s01 = s01 * w01 + (b01 * sa + kv01); s23 = s23 * w23 + (b23 * sa + kv23);
;                     const f32x2 py = s01 * r01 + s23 * r23;
;                     const float y = allsum16(py.x + py.y);
;                     if ((lane & 15) == (tt & 15)) yreg0 = y;
	ds_read_b128 v[32:35], v217 offset:13440
	ds_read_b128 v[36:39], v217 offset:13696
	ds_read_b128 v[40:43], v217 offset:13952
	ds_read_b128 v[44:47], v217 offset:14208
	ds_read_b128 v[48:51], v217 offset:14464
	ds_read_b32 v92, v218 offset:13440
	v_pk_mul_f32 v[206:207], v[24:25], v[122:123]
	v_pk_fma_f32 v[206:207], v[22:23], v[120:121], v[206:207]
	v_pk_mul_f32 v[208:209], v[24:25], v[204:205]
	v_add_f32_e32 v214, v206, v207
	v_pk_fma_f32 v[208:209], v[22:23], v[202:203], v[208:209]
	v_pk_mul_f32 v[210:211], v[132:133], v[28:29] op_sel_hi:[1,0]
	v_add_f32_dpp v214, v214, v214 quad_perm:[1,0,3,2] row_mask:0xf bank_mask:0xf bound_ctrl:1
	v_add_f32_e32 v239, v208, v209
	v_pk_mul_f32 v[212:213], v[134:135], v[28:29] op_sel_hi:[1,0]
	v_add_f32_dpp v214, v214, v214 quad_perm:[2,3,0,1] row_mask:0xf bank_mask:0xf bound_ctrl:1
	v_pk_fma_f32 v[210:211], v[22:23], v[124:125], v[210:211]
	v_pk_fma_f32 v[212:213], v[24:25], v[126:127], v[212:213]
	v_add_f32_dpp v214, v214, v214 row_half_mirror row_mask:0xf bank_mask:0xf bound_ctrl:1
	s_nop 1
	v_add_f32_dpp v214, v214, v214 row_mirror row_mask:0xf bank_mask:0xf bound_ctrl:1
	v_pk_fma_f32 v[22:23], v[128:129], v[214:215], v[210:211] op_sel_hi:[1,0,1]
	v_pk_fma_f32 v[24:25], v[130:131], v[214:215], v[212:213] op_sel_hi:[1,0,1]
	s_waitcnt lgkmcnt(6)
	ds_read_b128 v[186:189], v217 offset:14784
	ds_read_b128 v[190:193], v217 offset:15040
	ds_read_b128 v[194:197], v217 offset:15296
	ds_read_b128 v[198:201], v217 offset:15552
	ds_read_b128 v[202:205], v217 offset:15808
	ds_read_b32 v52, v218 offset:14784
	v_pk_mul_f32 v[206:207], v[24:25], v[148:149]
	v_pk_fma_f32 v[206:207], v[22:23], v[146:147], v[206:207]
	v_pk_mul_f32 v[208:209], v[24:25], v[138:139]
	v_add_f32_e32 v214, v206, v207
	v_pk_fma_f32 v[208:209], v[22:23], v[136:137], v[208:209]
	v_pk_mul_f32 v[210:211], v[158:159], v[30:31] op_sel_hi:[1,0]
	v_add_f32_dpp v214, v214, v214 quad_perm:[1,0,3,2] row_mask:0xf bank_mask:0xf bound_ctrl:1
	v_add_f32_e32 v240, v208, v209
	v_pk_mul_f32 v[212:213], v[160:161], v[30:31] op_sel_hi:[1,0]
	v_add_f32_dpp v214, v214, v214 quad_perm:[2,3,0,1] row_mask:0xf bank_mask:0xf bound_ctrl:1
	v_pk_fma_f32 v[210:211], v[22:23], v[150:151], v[210:211]
	v_pk_fma_f32 v[212:213], v[24:25], v[152:153], v[212:213]
	v_add_f32_dpp v214, v214, v214 row_half_mirror row_mask:0xf bank_mask:0xf bound_ctrl:1
	s_nop 1
	v_add_f32_dpp v214, v214, v214 row_mirror row_mask:0xf bank_mask:0xf bound_ctrl:1
	v_pk_fma_f32 v[22:23], v[154:155], v[214:215], v[210:211] op_sel_hi:[1,0,1]
	v_pk_fma_f32 v[24:25], v[156:157], v[214:215], v[212:213] op_sel_hi:[1,0,1]
	s_waitcnt lgkmcnt(6)
	ds_read_b128 v[120:123], v217 offset:16128
	ds_read_b128 v[124:127], v217 offset:16384
	ds_read_b128 v[128:131], v217 offset:16640
	ds_read_b128 v[132:135], v217 offset:16896
	ds_read_b128 v[136:139], v217 offset:17152
	ds_read_b32 v28, v218 offset:16128
	v_pk_mul_f32 v[206:207], v[24:25], v[34:35]
	v_pk_fma_f32 v[206:207], v[22:23], v[32:33], v[206:207]
	v_pk_mul_f32 v[208:209], v[24:25], v[164:165]
	v_add_f32_e32 v214, v206, v207
	v_pk_fma_f32 v[208:209], v[22:23], v[162:163], v[208:209]
	v_pk_mul_f32 v[210:211], v[44:45], v[92:93] op_sel_hi:[1,0]
	v_add_f32_dpp v214, v214, v214 quad_perm:[1,0,3,2] row_mask:0xf bank_mask:0xf bound_ctrl:1
	v_add_f32_e32 v241, v208, v209
	v_pk_mul_f32 v[212:213], v[46:47], v[92:93] op_sel_hi:[1,0]
	v_add_f32_dpp v214, v214, v214 quad_perm:[2,3,0,1] row_mask:0xf bank_mask:0xf bound_ctrl:1
	v_pk_fma_f32 v[210:211], v[22:23], v[36:37], v[210:211]
	v_pk_fma_f32 v[212:213], v[24:25], v[38:39], v[212:213]
	v_add_f32_dpp v214, v214, v214 row_half_mirror row_mask:0xf bank_mask:0xf bound_ctrl:1
	s_nop 1
	v_add_f32_dpp v214, v214, v214 row_mirror row_mask:0xf bank_mask:0xf bound_ctrl:1
	v_pk_fma_f32 v[22:23], v[40:41], v[214:215], v[210:211] op_sel_hi:[1,0,1]
	v_pk_fma_f32 v[24:25], v[42:43], v[214:215], v[212:213] op_sel_hi:[1,0,1]
	s_waitcnt lgkmcnt(6)
	ds_read_b128 v[146:149], v217 offset:17472
	ds_read_b128 v[150:153], v217 offset:17728
	ds_read_b128 v[154:157], v217 offset:17984
	ds_read_b128 v[158:161], v217 offset:18240
	ds_read_b128 v[162:165], v217 offset:18496
	ds_read_b32 v30, v218 offset:17472
	v_pk_mul_f32 v[206:207], v[24:25], v[188:189]
	v_pk_fma_f32 v[206:207], v[22:23], v[186:187], v[206:207]
	v_pk_mul_f32 v[208:209], v[24:25], v[50:51]
	v_add_f32_e32 v214, v206, v207
	v_pk_fma_f32 v[208:209], v[22:23], v[48:49], v[208:209]
	v_pk_mul_f32 v[210:211], v[198:199], v[52:53] op_sel_hi:[1,0]
	v_add_f32_dpp v214, v214, v214 quad_perm:[1,0,3,2] row_mask:0xf bank_mask:0xf bound_ctrl:1
	v_add_f32_e32 v242, v208, v209
	v_pk_mul_f32 v[212:213], v[200:201], v[52:53] op_sel_hi:[1,0]
	v_add_f32_dpp v214, v214, v214 quad_perm:[2,3,0,1] row_mask:0xf bank_mask:0xf bound_ctrl:1
	v_pk_fma_f32 v[210:211], v[22:23], v[190:191], v[210:211]
	v_pk_fma_f32 v[212:213], v[24:25], v[192:193], v[212:213]
	v_add_f32_dpp v214, v214, v214 row_half_mirror row_mask:0xf bank_mask:0xf bound_ctrl:1
	s_nop 1
	v_add_f32_dpp v214, v214, v214 row_mirror row_mask:0xf bank_mask:0xf bound_ctrl:1
	v_pk_fma_f32 v[22:23], v[194:195], v[214:215], v[210:211] op_sel_hi:[1,0,1]
	v_pk_fma_f32 v[24:25], v[196:197], v[214:215], v[212:213] op_sel_hi:[1,0,1]
	s_waitcnt lgkmcnt(6)
; __device__ void phase_scan(int l, unsigned char* lds) {
;     ...
;                     const f32x4 a = *(const f32x4*)(tb), w = *(const f32x4*)(tb + 256), b = *(const f32x4*)(tb + 512), k = *(const f32x4*)(tb + 768), r = *(const f32x4*)(tb + 1024);
;                     const float v = *(const float*)(buf + tt * SC_TOKB + 1280 + rl * 4);
;                     const f32x2 a01 = (f32x2){a[0], a[1]}, a23 = (f32x2){a[2], a[3]}, w01 = (f32x2){w[0], w[1]}, w23 = (f32x2){w[2], w[3]}, b01 = (f32x2){b[0], b[1]}, b23 = (f32x2){b[2], b[3]};
;                     const f32x2 k01 = (f32x2){k[0], k[1]}, k23 = (f32x2){k[2], k[3]}, r01 = (f32x2){r[0], r[1]}, r23 = (f32x2){r[2], r[3]};
;                     const f32x2 pa = s01 * a01 + s23 * a23;
;                     const float sa = allsum16(pa.x + pa.y);
;                     const f32x2 kv01 = k01 * v, kv23 = k23 * v;
;                     s01 = s01 * w01 + (b01 * sa + kv01); s23 = s23 * w23 + (b23 * sa + kv23);
;                     const f32x2 py = s01 * r01 + s23 * r23;
;                     const float y = allsum16(py.x + py.y);
;                     if ((lane & 15) == (tt & 15)) yreg0 = y;
	ds_read_b128 v[32:35], v217 offset:18816
	ds_read_b128 v[36:39], v217 offset:19072
	ds_read_b128 v[40:43], v217 offset:19328
	ds_read_b128 v[44:47], v217 offset:19584
	ds_read_b128 v[48:51], v217 offset:19840
	ds_read_b32 v92, v218 offset:18816
	v_pk_mul_f32 v[206:207], v[24:25], v[122:123]
	v_pk_fma_f32 v[206:207], v[22:23], v[120:121], v[206:207]
	v_pk_mul_f32 v[208:209], v[24:25], v[204:205]
	v_add_f32_e32 v214, v206, v207
	v_pk_fma_f32 v[208:209], v[22:23], v[202:203], v[208:209]
	v_pk_mul_f32 v[210:211], v[132:133], v[28:29] op_sel_hi:[1,0]
	v_add_f32_dpp v214, v214, v214 quad_perm:[1,0,3,2] row_mask:0xf bank_mask:0xf bound_ctrl:1
	v_add_f32_e32 v243, v208, v209
	v_pk_mul_f32 v[212:213], v[134:135], v[28:29] op_sel_hi:[1,0]
	v_add_f32_dpp v214, v214, v214 quad_perm:[2,3,0,1] row_mask:0xf bank_mask:0xf bound_ctrl:1
	v_pk_fma_f32 v[210:211], v[22:23], v[124:125], v[210:211]
	v_pk_fma_f32 v[212:213], v[24:25], v[126:127], v[212:213]
	v_add_f32_dpp v214, v214, v214 row_half_mirror row_mask:0xf bank_mask:0xf bound_ctrl:1
	s_nop 1
	v_add_f32_dpp v214, v214, v214 row_mirror row_mask:0xf bank_mask:0xf bound_ctrl:1
	v_pk_fma_f32 v[22:23], v[128:129], v[214:215], v[210:211] op_sel_hi:[1,0,1]
	v_pk_fma_f32 v[24:25], v[130:131], v[214:215], v[212:213] op_sel_hi:[1,0,1]
	s_waitcnt lgkmcnt(6)
	ds_read_b128 v[186:189], v217 offset:20160
	ds_read_b128 v[190:193], v217 offset:20416
	ds_read_b128 v[194:197], v217 offset:20672
	ds_read_b128 v[198:201], v217 offset:20928
	ds_read_b128 v[202:205], v217 offset:21184
	ds_read_b32 v52, v218 offset:20160
	v_pk_mul_f32 v[206:207], v[24:25], v[148:149]
	v_pk_fma_f32 v[206:207], v[22:23], v[146:147], v[206:207]
	v_pk_mul_f32 v[208:209], v[24:25], v[138:139]
	v_add_f32_e32 v214, v206, v207
	v_pk_fma_f32 v[208:209], v[22:23], v[136:137], v[208:209]
	v_pk_mul_f32 v[210:211], v[158:159], v[30:31] op_sel_hi:[1,0]
	v_add_f32_dpp v214, v214, v214 quad_perm:[1,0,3,2] row_mask:0xf bank_mask:0xf bound_ctrl:1
	v_add_f32_e32 v244, v208, v209
	v_pk_mul_f32 v[212:213], v[160:161], v[30:31] op_sel_hi:[1,0]
	v_add_f32_dpp v214, v214, v214 quad_perm:[2,3,0,1] row_mask:0xf bank_mask:0xf bound_ctrl:1
	v_pk_fma_f32 v[210:211], v[22:23], v[150:151], v[210:211]
	v_pk_fma_f32 v[212:213], v[24:25], v[152:153], v[212:213]
	v_add_f32_dpp v214, v214, v214 row_half_mirror row_mask:0xf bank_mask:0xf bound_ctrl:1
	s_nop 1
	v_add_f32_dpp v214, v214, v214 row_mirror row_mask:0xf bank_mask:0xf bound_ctrl:1
	v_pk_fma_f32 v[22:23], v[154:155], v[214:215], v[210:211] op_sel_hi:[1,0,1]
	v_pk_fma_f32 v[24:25], v[156:157], v[214:215], v[212:213] op_sel_hi:[1,0,1]
	s_waitcnt lgkmcnt(6)
	ds_read_b128 v[120:123], v217 offset:21504
	ds_read_b128 v[124:127], v217 offset:21760
	ds_read_b128 v[128:131], v217 offset:22016
	ds_read_b128 v[132:135], v217 offset:22272
	ds_read_b128 v[136:139], v217 offset:22528
	ds_read_b32 v28, v218 offset:21504
	v_pk_mul_f32 v[206:207], v[24:25], v[34:35]
	v_pk_fma_f32 v[206:207], v[22:23], v[32:33], v[206:207]
	v_pk_mul_f32 v[208:209], v[24:25], v[164:165]
	v_add_f32_e32 v214, v206, v207
	v_pk_fma_f32 v[208:209], v[22:23], v[162:163], v[208:209]
	v_pk_mul_f32 v[210:211], v[44:45], v[92:93] op_sel_hi:[1,0]
	v_add_f32_dpp v214, v214, v214 quad_perm:[1,0,3,2] row_mask:0xf bank_mask:0xf bound_ctrl:1
	v_add_f32_e32 v245, v208, v209
	v_pk_mul_f32 v[212:213], v[46:47], v[92:93] op_sel_hi:[1,0]
	v_add_f32_dpp v214, v214, v214 quad_perm:[2,3,0,1] row_mask:0xf bank_mask:0xf bound_ctrl:1
	v_pk_fma_f32 v[210:211], v[22:23], v[36:37], v[210:211]
	v_pk_fma_f32 v[212:213], v[24:25], v[38:39], v[212:213]
	v_add_f32_dpp v214, v214, v214 row_half_mirror row_mask:0xf bank_mask:0xf bound_ctrl:1
	s_nop 1
	v_add_f32_dpp v214, v214, v214 row_mirror row_mask:0xf bank_mask:0xf bound_ctrl:1
	v_pk_fma_f32 v[22:23], v[40:41], v[214:215], v[210:211] op_sel_hi:[1,0,1]
	v_pk_fma_f32 v[24:25], v[42:43], v[214:215], v[212:213] op_sel_hi:[1,0,1]
	s_waitcnt lgkmcnt(6)
	ds_read_b128 v[146:149], v217 offset:22848
	ds_read_b128 v[150:153], v217 offset:23104
	ds_read_b128 v[154:157], v217 offset:23360
	ds_read_b128 v[158:161], v217 offset:23616
	ds_read_b128 v[162:165], v217 offset:23872
	ds_read_b32 v30, v218 offset:22848
	v_pk_mul_f32 v[206:207], v[24:25], v[188:189]
	v_pk_fma_f32 v[206:207], v[22:23], v[186:187], v[206:207]
	v_pk_mul_f32 v[208:209], v[24:25], v[50:51]
	v_add_f32_e32 v214, v206, v207
	v_pk_fma_f32 v[208:209], v[22:23], v[48:49], v[208:209]
	v_pk_mul_f32 v[210:211], v[198:199], v[52:53] op_sel_hi:[1,0]
	v_add_f32_dpp v214, v214, v214 quad_perm:[1,0,3,2] row_mask:0xf bank_mask:0xf bound_ctrl:1
	v_add_f32_e32 v246, v208, v209
	v_pk_mul_f32 v[212:213], v[200:201], v[52:53] op_sel_hi:[1,0]
	v_add_f32_dpp v214, v214, v214 quad_perm:[2,3,0,1] row_mask:0xf bank_mask:0xf bound_ctrl:1
	v_pk_fma_f32 v[210:211], v[22:23], v[190:191], v[210:211]
	v_pk_fma_f32 v[212:213], v[24:25], v[192:193], v[212:213]
	v_add_f32_dpp v214, v214, v214 row_half_mirror row_mask:0xf bank_mask:0xf bound_ctrl:1
	s_nop 1
	v_add_f32_dpp v214, v214, v214 row_mirror row_mask:0xf bank_mask:0xf bound_ctrl:1
	v_pk_fma_f32 v[22:23], v[194:195], v[214:215], v[210:211] op_sel_hi:[1,0,1]
	v_pk_fma_f32 v[24:25], v[196:197], v[214:215], v[212:213] op_sel_hi:[1,0,1]
	s_waitcnt lgkmcnt(6)
; __device__ void phase_scan(int l, unsigned char* lds) {
;     ...
;                     const f32x4 a = *(const f32x4*)(tb), w = *(const f32x4*)(tb + 256), b = *(const f32x4*)(tb + 512), k = *(const f32x4*)(tb + 768), r = *(const f32x4*)(tb + 1024);
;                     const float v = *(const float*)(buf + tt * SC_TOKB + 1280 + rl * 4);
;                     const f32x2 a01 = (f32x2){a[0], a[1]}, a23 = (f32x2){a[2], a[3]}, w01 = (f32x2){w[0], w[1]}, w23 = (f32x2){w[2], w[3]}, b01 = (f32x2){b[0], b[1]}, b23 = (f32x2){b[2], b[3]};
;                     const f32x2 k01 = (f32x2){k[0], k[1]}, k23 = (f32x2){k[2], k[3]}, r01 = (f32x2){r[0], r[1]}, r23 = (f32x2){r[2], r[3]};
;                     const f32x2 pa = s01 * a01 + s23 * a23;
;                     const float sa = allsum16(pa.x + pa.y);
;                     const f32x2 kv01 = k01 * v, kv23 = k23 * v;
;                     s01 = s01 * w01 + (b01 * sa + kv01); s23 = s23 * w23 + (b23 * sa + kv23);
;                     const f32x2 py = s01 * r01 + s23 * r23;
;                     const float y = allsum16(py.x + py.y);
;                     if ((lane & 15) == (tt & 15)) yreg0 = y;
;                 }
;             }
;             for (int t8 = 16; t8 < (jb.nsteps < 32 ? jb.nsteps : 32); t8 += 4) {
; #pragma unroll
;                 for (int u = 0; u < 4; ++u) {
;                     const int tt = t8 + u;
;                     const unsigned char* tb = buf + tt * SC_TOKB + c0 * 4;
;                     const f32x4 a = *(const f32x4*)(tb), w = *(const f32x4*)(tb + 256), b = *(const f32x4*)(tb + 512), k = *(const f32x4*)(tb + 768), r = *(const f32x4*)(tb + 1024);
;                     const float v = *(const float*)(buf + tt * SC_TOKB + 1280 + rl * 4);
;                     const f32x2 a01 = (f32x2){a[0], a[1]}, a23 = (f32x2){a[2], a[3]}, w01 = (f32x2){w[0], w[1]}, w23 = (f32x2){w[2], w[3]}, b01 = (f32x2){b[0], b[1]}, b23 = (f32x2){b[2], b[3]};
;                     const f32x2 k01 = (f32x2){k[0], k[1]}, k23 = (f32x2){k[2], k[3]}, r01 = (f32x2){r[0], r[1]}, r23 = (f32x2){r[2], r[3]};
;                     const f32x2 pa = s01 * a01 + s23 * a23;
;                     const float sa = allsum16(pa.x + pa.y);
;                     const f32x2 kv01 = k01 * v, kv23 = k23 * v;
;                     s01 = s01 * w01 + (b01 * sa + kv01); s23 = s23 * w23 + (b23 * sa + kv23);
	ds_read_b128 v[32:35], v217 offset:24192
	ds_read_b128 v[36:39], v217 offset:24448
	ds_read_b128 v[40:43], v217 offset:24704
	ds_read_b128 v[44:47], v217 offset:24960
	ds_read_b128 v[48:51], v217 offset:25216
	ds_read_b32 v92, v218 offset:24192
	v_pk_mul_f32 v[206:207], v[24:25], v[122:123]
	v_pk_fma_f32 v[206:207], v[22:23], v[120:121], v[206:207]
	v_pk_mul_f32 v[208:209], v[24:25], v[204:205]
	v_add_f32_e32 v214, v206, v207
	v_pk_fma_f32 v[208:209], v[22:23], v[202:203], v[208:209]
	v_pk_mul_f32 v[210:211], v[132:133], v[28:29] op_sel_hi:[1,0]
	v_add_f32_dpp v214, v214, v214 quad_perm:[1,0,3,2] row_mask:0xf bank_mask:0xf bound_ctrl:1
	v_add_f32_e32 v247, v208, v209
	v_pk_mul_f32 v[212:213], v[134:135], v[28:29] op_sel_hi:[1,0]
	v_add_f32_dpp v214, v214, v214 quad_perm:[2,3,0,1] row_mask:0xf bank_mask:0xf bound_ctrl:1
	v_pk_fma_f32 v[210:211], v[22:23], v[124:125], v[210:211]
	v_pk_fma_f32 v[212:213], v[24:25], v[126:127], v[212:213]
	v_add_f32_dpp v214, v214, v214 row_half_mirror row_mask:0xf bank_mask:0xf bound_ctrl:1
	s_nop 1
	v_add_f32_dpp v214, v214, v214 row_mirror row_mask:0xf bank_mask:0xf bound_ctrl:1
	v_pk_fma_f32 v[22:23], v[128:129], v[214:215], v[210:211] op_sel_hi:[1,0,1]
	v_pk_fma_f32 v[24:25], v[130:131], v[214:215], v[212:213] op_sel_hi:[1,0,1]
	s_mov_b32 s98, 0xaaaaaaaa
	s_mov_b32 s99, 0xaaaaaaaa
	v_cndmask_b32_e64 v249, v233, v232, s[98:99]
	v_cndmask_b32_e64 v232, v232, v233, s[98:99]
	v_cndmask_b32_e64 v251, v235, v234, s[98:99]
	v_cndmask_b32_e64 v234, v234, v235, s[98:99]
	v_add_f32_dpp v232, v249, v232 quad_perm:[1,0,3,2] row_mask:0xf bank_mask:0xf bound_ctrl:1
	v_cndmask_b32_e64 v249, v237, v236, s[98:99]
	v_cndmask_b32_e64 v236, v236, v237, s[98:99]
	v_add_f32_dpp v234, v251, v234 quad_perm:[1,0,3,2] row_mask:0xf bank_mask:0xf bound_ctrl:1
	v_cndmask_b32_e64 v251, v239, v238, s[98:99]
	v_cndmask_b32_e64 v238, v238, v239, s[98:99]
	v_add_f32_dpp v236, v249, v236 quad_perm:[1,0,3,2] row_mask:0xf bank_mask:0xf bound_ctrl:1
	v_cndmask_b32_e64 v249, v241, v240, s[98:99]
	v_cndmask_b32_e64 v240, v240, v241, s[98:99]
	v_add_f32_dpp v238, v251, v238 quad_perm:[1,0,3,2] row_mask:0xf bank_mask:0xf bound_ctrl:1
	v_cndmask_b32_e64 v251, v243, v242, s[98:99]
	v_cndmask_b32_e64 v242, v242, v243, s[98:99]
	v_add_f32_dpp v240, v249, v240 quad_perm:[1,0,3,2] row_mask:0xf bank_mask:0xf bound_ctrl:1
	v_cndmask_b32_e64 v249, v245, v244, s[98:99]
	v_cndmask_b32_e64 v244, v244, v245, s[98:99]
	v_add_f32_dpp v242, v251, v242 quad_perm:[1,0,3,2] row_mask:0xf bank_mask:0xf bound_ctrl:1
	v_cndmask_b32_e64 v251, v247, v246, s[98:99]
	v_cndmask_b32_e64 v246, v246, v247, s[98:99]
	v_add_f32_dpp v244, v249, v244 quad_perm:[1,0,3,2] row_mask:0xf bank_mask:0xf bound_ctrl:1
	s_nop 1
	v_add_f32_dpp v246, v251, v246 quad_perm:[1,0,3,2] row_mask:0xf bank_mask:0xf bound_ctrl:1
	s_mov_b32 s98, 0xcccccccc
	s_mov_b32 s99, 0xcccccccc
	v_cndmask_b32_e64 v249, v234, v232, s[98:99]
	v_cndmask_b32_e64 v232, v232, v234, s[98:99]
	v_cndmask_b32_e64 v251, v238, v236, s[98:99]
	v_cndmask_b32_e64 v236, v236, v238, s[98:99]
	v_add_f32_dpp v232, v249, v232 quad_perm:[2,3,0,1] row_mask:0xf bank_mask:0xf bound_ctrl:1
	v_cndmask_b32_e64 v249, v242, v240, s[98:99]
	v_cndmask_b32_e64 v240, v240, v242, s[98:99]
	v_add_f32_dpp v236, v251, v236 quad_perm:[2,3,0,1] row_mask:0xf bank_mask:0xf bound_ctrl:1
	v_cndmask_b32_e64 v251, v246, v244, s[98:99]
	v_cndmask_b32_e64 v244, v244, v246, s[98:99]
	v_add_f32_dpp v240, v249, v240 quad_perm:[2,3,0,1] row_mask:0xf bank_mask:0xf bound_ctrl:1
	s_nop 1
	v_add_f32_dpp v244, v251, v244 quad_perm:[2,3,0,1] row_mask:0xf bank_mask:0xf bound_ctrl:1
	s_mov_b32 s98, 0xf0f0f0f0
	s_mov_b32 s99, 0xf0f0f0f0
	v_cndmask_b32_e64 v249, v236, v232, s[98:99]
	v_cndmask_b32_e64 v232, v232, v236, s[98:99]
	v_cndmask_b32_e64 v251, v244, v240, s[98:99]
	v_cndmask_b32_e64 v240, v240, v244, s[98:99]
	v_add_f32_dpp v232, v249, v232 row_shr:4 row_mask:0xf bank_mask:0xa
	v_add_f32_dpp v232, v249, v232 row_shl:4 row_mask:0xf bank_mask:0x5
	s_nop 1
	v_add_f32_dpp v240, v251, v240 row_shr:4 row_mask:0xf bank_mask:0xa
	v_add_f32_dpp v240, v251, v240 row_shl:4 row_mask:0xf bank_mask:0x5
	s_mov_b32 s98, 0xff00ff00
	s_mov_b32 s99, 0xff00ff00
	v_cndmask_b32_e64 v249, v240, v232, s[98:99]
	v_cndmask_b32_e64 v232, v232, v240, s[98:99]
	s_nop 1
	v_add_f32_dpp v232, v249, v232 row_ror:8 row_mask:0xf bank_mask:0xf bound_ctrl:1
	v_mov_b32_e32 v18, v232
	s_waitcnt lgkmcnt(6)
	ds_read_b128 v[186:189], v217 offset:25536
	ds_read_b128 v[190:193], v217 offset:25792
	ds_read_b128 v[194:197], v217 offset:26048
	ds_read_b128 v[198:201], v217 offset:26304
	ds_read_b128 v[202:205], v217 offset:26560
	ds_read_b32 v52, v218 offset:25536
	v_pk_mul_f32 v[206:207], v[24:25], v[148:149]
	v_pk_fma_f32 v[206:207], v[22:23], v[146:147], v[206:207]
	v_pk_mul_f32 v[208:209], v[24:25], v[138:139]
	v_add_f32_e32 v214, v206, v207
	v_pk_fma_f32 v[208:209], v[22:23], v[136:137], v[208:209]
	v_pk_mul_f32 v[210:211], v[158:159], v[30:31] op_sel_hi:[1,0]
	v_add_f32_dpp v214, v214, v214 quad_perm:[1,0,3,2] row_mask:0xf bank_mask:0xf bound_ctrl:1
	v_add_f32_e32 v232, v208, v209
	v_pk_mul_f32 v[212:213], v[160:161], v[30:31] op_sel_hi:[1,0]
	v_add_f32_dpp v214, v214, v214 quad_perm:[2,3,0,1] row_mask:0xf bank_mask:0xf bound_ctrl:1
	v_pk_fma_f32 v[210:211], v[22:23], v[150:151], v[210:211]
	v_pk_fma_f32 v[212:213], v[24:25], v[152:153], v[212:213]
	v_add_f32_dpp v214, v214, v214 row_half_mirror row_mask:0xf bank_mask:0xf bound_ctrl:1
	s_nop 1
	v_add_f32_dpp v214, v214, v214 row_mirror row_mask:0xf bank_mask:0xf bound_ctrl:1
	v_pk_fma_f32 v[22:23], v[154:155], v[214:215], v[210:211] op_sel_hi:[1,0,1]
	v_pk_fma_f32 v[24:25], v[156:157], v[214:215], v[212:213] op_sel_hi:[1,0,1]
	s_waitcnt lgkmcnt(6)
; __device__ void phase_scan(int l, unsigned char* lds) {
;     ...
;             for (int t8 = 16; t8 < (jb.nsteps < 32 ? jb.nsteps : 32); t8 += 4) {
; #pragma unroll
;                 for (int u = 0; u < 4; ++u) {
;                     const int tt = t8 + u;
;                     const unsigned char* tb = buf + tt * SC_TOKB + c0 * 4;
;                     const f32x4 a = *(const f32x4*)(tb), w = *(const f32x4*)(tb + 256), b = *(const f32x4*)(tb + 512), k = *(const f32x4*)(tb + 768), r = *(const f32x4*)(tb + 1024);
;                     const float v = *(const float*)(buf + tt * SC_TOKB + 1280 + rl * 4);
;                     const f32x2 a01 = (f32x2){a[0], a[1]}, a23 = (f32x2){a[2], a[3]}, w01 = (f32x2){w[0], w[1]}, w23 = (f32x2){w[2], w[3]}, b01 = (f32x2){b[0], b[1]}, b23 = (f32x2){b[2], b[3]};
;                     const f32x2 k01 = (f32x2){k[0], k[1]}, k23 = (f32x2){k[2], k[3]}, r01 = (f32x2){r[0], r[1]}, r23 = (f32x2){r[2], r[3]};
;                     const f32x2 pa = s01 * a01 + s23 * a23;
;                     const float sa = allsum16(pa.x + pa.y);
;                     const f32x2 kv01 = k01 * v, kv23 = k23 * v;
;                     s01 = s01 * w01 + (b01 * sa + kv01); s23 = s23 * w23 + (b23 * sa + kv23);
;                     const f32x2 py = s01 * r01 + s23 * r23;
;                     const float y = allsum16(py.x + py.y);
;                     if ((lane & 15) == (tt & 15)) yreg1 = y;
;                 }
	ds_read_b128 v[120:123], v217 offset:26880
	ds_read_b128 v[124:127], v217 offset:27136
	ds_read_b128 v[128:131], v217 offset:27392
	ds_read_b128 v[132:135], v217 offset:27648
	ds_read_b128 v[136:139], v217 offset:27904
	ds_read_b32 v28, v218 offset:26880
	v_pk_mul_f32 v[206:207], v[24:25], v[34:35]
	v_pk_fma_f32 v[206:207], v[22:23], v[32:33], v[206:207]
	v_pk_mul_f32 v[208:209], v[24:25], v[164:165]
	v_add_f32_e32 v214, v206, v207
	v_pk_fma_f32 v[208:209], v[22:23], v[162:163], v[208:209]
	v_pk_mul_f32 v[210:211], v[44:45], v[92:93] op_sel_hi:[1,0]
	v_add_f32_dpp v214, v214, v214 quad_perm:[1,0,3,2] row_mask:0xf bank_mask:0xf bound_ctrl:1
	v_add_f32_e32 v233, v208, v209
	v_pk_mul_f32 v[212:213], v[46:47], v[92:93] op_sel_hi:[1,0]
	v_add_f32_dpp v214, v214, v214 quad_perm:[2,3,0,1] row_mask:0xf bank_mask:0xf bound_ctrl:1
	v_pk_fma_f32 v[210:211], v[22:23], v[36:37], v[210:211]
	v_pk_fma_f32 v[212:213], v[24:25], v[38:39], v[212:213]
	v_add_f32_dpp v214, v214, v214 row_half_mirror row_mask:0xf bank_mask:0xf bound_ctrl:1
	s_nop 1
	v_add_f32_dpp v214, v214, v214 row_mirror row_mask:0xf bank_mask:0xf bound_ctrl:1
	v_pk_fma_f32 v[22:23], v[40:41], v[214:215], v[210:211] op_sel_hi:[1,0,1]
	v_pk_fma_f32 v[24:25], v[42:43], v[214:215], v[212:213] op_sel_hi:[1,0,1]
	s_waitcnt lgkmcnt(6)
	ds_read_b128 v[146:149], v217 offset:28224
	ds_read_b128 v[150:153], v217 offset:28480
	ds_read_b128 v[154:157], v217 offset:28736
	ds_read_b128 v[158:161], v217 offset:28992
	ds_read_b128 v[162:165], v217 offset:29248
	ds_read_b32 v30, v218 offset:28224
	v_pk_mul_f32 v[206:207], v[24:25], v[188:189]
	v_pk_fma_f32 v[206:207], v[22:23], v[186:187], v[206:207]
	v_pk_mul_f32 v[208:209], v[24:25], v[50:51]
	v_add_f32_e32 v214, v206, v207
	v_pk_fma_f32 v[208:209], v[22:23], v[48:49], v[208:209]
	v_pk_mul_f32 v[210:211], v[198:199], v[52:53] op_sel_hi:[1,0]
	v_add_f32_dpp v214, v214, v214 quad_perm:[1,0,3,2] row_mask:0xf bank_mask:0xf bound_ctrl:1
	v_add_f32_e32 v234, v208, v209
	v_pk_mul_f32 v[212:213], v[200:201], v[52:53] op_sel_hi:[1,0]
	v_add_f32_dpp v214, v214, v214 quad_perm:[2,3,0,1] row_mask:0xf bank_mask:0xf bound_ctrl:1
	v_pk_fma_f32 v[210:211], v[22:23], v[190:191], v[210:211]
	v_pk_fma_f32 v[212:213], v[24:25], v[192:193], v[212:213]
	v_add_f32_dpp v214, v214, v214 row_half_mirror row_mask:0xf bank_mask:0xf bound_ctrl:1
	s_nop 1
	v_add_f32_dpp v214, v214, v214 row_mirror row_mask:0xf bank_mask:0xf bound_ctrl:1
	v_pk_fma_f32 v[22:23], v[194:195], v[214:215], v[210:211] op_sel_hi:[1,0,1]
	v_pk_fma_f32 v[24:25], v[196:197], v[214:215], v[212:213] op_sel_hi:[1,0,1]
	s_waitcnt lgkmcnt(6)
	ds_read_b128 v[32:35], v217 offset:29568
	ds_read_b128 v[36:39], v217 offset:29824
	ds_read_b128 v[40:43], v217 offset:30080
	ds_read_b128 v[44:47], v217 offset:30336
	ds_read_b128 v[48:51], v217 offset:30592
	ds_read_b32 v92, v218 offset:29568
	v_pk_mul_f32 v[206:207], v[24:25], v[122:123]
	v_pk_fma_f32 v[206:207], v[22:23], v[120:121], v[206:207]
	v_pk_mul_f32 v[208:209], v[24:25], v[204:205]
	v_add_f32_e32 v214, v206, v207
	v_pk_fma_f32 v[208:209], v[22:23], v[202:203], v[208:209]
	v_pk_mul_f32 v[210:211], v[132:133], v[28:29] op_sel_hi:[1,0]
	v_add_f32_dpp v214, v214, v214 quad_perm:[1,0,3,2] row_mask:0xf bank_mask:0xf bound_ctrl:1
	v_add_f32_e32 v235, v208, v209
	v_pk_mul_f32 v[212:213], v[134:135], v[28:29] op_sel_hi:[1,0]
	v_add_f32_dpp v214, v214, v214 quad_perm:[2,3,0,1] row_mask:0xf bank_mask:0xf bound_ctrl:1
	v_pk_fma_f32 v[210:211], v[22:23], v[124:125], v[210:211]
	v_pk_fma_f32 v[212:213], v[24:25], v[126:127], v[212:213]
	v_add_f32_dpp v214, v214, v214 row_half_mirror row_mask:0xf bank_mask:0xf bound_ctrl:1
	s_nop 1
	v_add_f32_dpp v214, v214, v214 row_mirror row_mask:0xf bank_mask:0xf bound_ctrl:1
	v_pk_fma_f32 v[22:23], v[128:129], v[214:215], v[210:211] op_sel_hi:[1,0,1]
	v_pk_fma_f32 v[24:25], v[130:131], v[214:215], v[212:213] op_sel_hi:[1,0,1]
	s_waitcnt lgkmcnt(6)
	ds_read_b128 v[186:189], v217 offset:30912
	ds_read_b128 v[190:193], v217 offset:31168
	ds_read_b128 v[194:197], v217 offset:31424
	ds_read_b128 v[198:201], v217 offset:31680
	ds_read_b128 v[202:205], v217 offset:31936
	ds_read_b32 v52, v218 offset:30912
	v_pk_mul_f32 v[206:207], v[24:25], v[148:149]
	v_pk_fma_f32 v[206:207], v[22:23], v[146:147], v[206:207]
	v_pk_mul_f32 v[208:209], v[24:25], v[138:139]
	v_add_f32_e32 v214, v206, v207
	v_pk_fma_f32 v[208:209], v[22:23], v[136:137], v[208:209]
	v_pk_mul_f32 v[210:211], v[158:159], v[30:31] op_sel_hi:[1,0]
	v_add_f32_dpp v214, v214, v214 quad_perm:[1,0,3,2] row_mask:0xf bank_mask:0xf bound_ctrl:1
	v_add_f32_e32 v236, v208, v209
	v_pk_mul_f32 v[212:213], v[160:161], v[30:31] op_sel_hi:[1,0]
	v_add_f32_dpp v214, v214, v214 quad_perm:[2,3,0,1] row_mask:0xf bank_mask:0xf bound_ctrl:1
	v_pk_fma_f32 v[210:211], v[22:23], v[150:151], v[210:211]
	v_pk_fma_f32 v[212:213], v[24:25], v[152:153], v[212:213]
	v_add_f32_dpp v214, v214, v214 row_half_mirror row_mask:0xf bank_mask:0xf bound_ctrl:1
	s_nop 1
	v_add_f32_dpp v214, v214, v214 row_mirror row_mask:0xf bank_mask:0xf bound_ctrl:1
	v_pk_fma_f32 v[22:23], v[154:155], v[214:215], v[210:211] op_sel_hi:[1,0,1]
	v_pk_fma_f32 v[24:25], v[156:157], v[214:215], v[212:213] op_sel_hi:[1,0,1]
	s_waitcnt lgkmcnt(6)
; __device__ void phase_scan(int l, unsigned char* lds) {
;     ...
;             for (int t8 = 16; t8 < (jb.nsteps < 32 ? jb.nsteps : 32); t8 += 4) {
; #pragma unroll
;                 for (int u = 0; u < 4; ++u) {
;                     const int tt = t8 + u;
;                     const unsigned char* tb = buf + tt * SC_TOKB + c0 * 4;
;                     const f32x4 a = *(const f32x4*)(tb), w = *(const f32x4*)(tb + 256), b = *(const f32x4*)(tb + 512), k = *(const f32x4*)(tb + 768), r = *(const f32x4*)(tb + 1024);
;                     const float v = *(const float*)(buf + tt * SC_TOKB + 1280 + rl * 4);
;                     const f32x2 a01 = (f32x2){a[0], a[1]}, a23 = (f32x2){a[2], a[3]}, w01 = (f32x2){w[0], w[1]}, w23 = (f32x2){w[2], w[3]}, b01 = (f32x2){b[0], b[1]}, b23 = (f32x2){b[2], b[3]};
;                     const f32x2 k01 = (f32x2){k[0], k[1]}, k23 = (f32x2){k[2], k[3]}, r01 = (f32x2){r[0], r[1]}, r23 = (f32x2){r[2], r[3]};
;                     const f32x2 pa = s01 * a01 + s23 * a23;
;                     const float sa = allsum16(pa.x + pa.y);
;                     const f32x2 kv01 = k01 * v, kv23 = k23 * v;
;                     s01 = s01 * w01 + (b01 * sa + kv01); s23 = s23 * w23 + (b23 * sa + kv23);
;                     const f32x2 py = s01 * r01 + s23 * r23;
;                     const float y = allsum16(py.x + py.y);
;                     if ((lane & 15) == (tt & 15)) yreg1 = y;
;                 }
	ds_read_b128 v[120:123], v217 offset:32256
	ds_read_b128 v[124:127], v217 offset:32512
	ds_read_b128 v[128:131], v217 offset:32768
	ds_read_b128 v[132:135], v217 offset:33024
	ds_read_b128 v[136:139], v217 offset:33280
	ds_read_b32 v28, v218 offset:32256
	v_pk_mul_f32 v[206:207], v[24:25], v[34:35]
	v_pk_fma_f32 v[206:207], v[22:23], v[32:33], v[206:207]
	v_pk_mul_f32 v[208:209], v[24:25], v[164:165]
	v_add_f32_e32 v214, v206, v207
	v_pk_fma_f32 v[208:209], v[22:23], v[162:163], v[208:209]
	v_pk_mul_f32 v[210:211], v[44:45], v[92:93] op_sel_hi:[1,0]
	v_add_f32_dpp v214, v214, v214 quad_perm:[1,0,3,2] row_mask:0xf bank_mask:0xf bound_ctrl:1
	v_add_f32_e32 v237, v208, v209
	v_pk_mul_f32 v[212:213], v[46:47], v[92:93] op_sel_hi:[1,0]
	v_add_f32_dpp v214, v214, v214 quad_perm:[2,3,0,1] row_mask:0xf bank_mask:0xf bound_ctrl:1
	v_pk_fma_f32 v[210:211], v[22:23], v[36:37], v[210:211]
	v_pk_fma_f32 v[212:213], v[24:25], v[38:39], v[212:213]
	v_add_f32_dpp v214, v214, v214 row_half_mirror row_mask:0xf bank_mask:0xf bound_ctrl:1
	s_nop 1
	v_add_f32_dpp v214, v214, v214 row_mirror row_mask:0xf bank_mask:0xf bound_ctrl:1
	v_pk_fma_f32 v[22:23], v[40:41], v[214:215], v[210:211] op_sel_hi:[1,0,1]
	v_pk_fma_f32 v[24:25], v[42:43], v[214:215], v[212:213] op_sel_hi:[1,0,1]
	s_waitcnt lgkmcnt(6)
	ds_read_b128 v[146:149], v217 offset:33600
	ds_read_b128 v[150:153], v217 offset:33856
	ds_read_b128 v[154:157], v217 offset:34112
	ds_read_b128 v[158:161], v217 offset:34368
	ds_read_b128 v[162:165], v217 offset:34624
	ds_read_b32 v30, v218 offset:33600
	v_pk_mul_f32 v[206:207], v[24:25], v[188:189]
	v_pk_fma_f32 v[206:207], v[22:23], v[186:187], v[206:207]
	v_pk_mul_f32 v[208:209], v[24:25], v[50:51]
	v_add_f32_e32 v214, v206, v207
	v_pk_fma_f32 v[208:209], v[22:23], v[48:49], v[208:209]
	v_pk_mul_f32 v[210:211], v[198:199], v[52:53] op_sel_hi:[1,0]
	v_add_f32_dpp v214, v214, v214 quad_perm:[1,0,3,2] row_mask:0xf bank_mask:0xf bound_ctrl:1
	v_add_f32_e32 v238, v208, v209
	v_pk_mul_f32 v[212:213], v[200:201], v[52:53] op_sel_hi:[1,0]
	v_add_f32_dpp v214, v214, v214 quad_perm:[2,3,0,1] row_mask:0xf bank_mask:0xf bound_ctrl:1
	v_pk_fma_f32 v[210:211], v[22:23], v[190:191], v[210:211]
	v_pk_fma_f32 v[212:213], v[24:25], v[192:193], v[212:213]
	v_add_f32_dpp v214, v214, v214 row_half_mirror row_mask:0xf bank_mask:0xf bound_ctrl:1
	s_nop 1
	v_add_f32_dpp v214, v214, v214 row_mirror row_mask:0xf bank_mask:0xf bound_ctrl:1
	v_pk_fma_f32 v[22:23], v[194:195], v[214:215], v[210:211] op_sel_hi:[1,0,1]
	v_pk_fma_f32 v[24:25], v[196:197], v[214:215], v[212:213] op_sel_hi:[1,0,1]
	s_waitcnt lgkmcnt(6)
	ds_read_b128 v[32:35], v217 offset:34944
	ds_read_b128 v[36:39], v217 offset:35200
	ds_read_b128 v[40:43], v217 offset:35456
	ds_read_b128 v[44:47], v217 offset:35712
	ds_read_b128 v[48:51], v217 offset:35968
	ds_read_b32 v92, v218 offset:34944
	v_pk_mul_f32 v[206:207], v[24:25], v[122:123]
	v_pk_fma_f32 v[206:207], v[22:23], v[120:121], v[206:207]
	v_pk_mul_f32 v[208:209], v[24:25], v[204:205]
	v_add_f32_e32 v214, v206, v207
	v_pk_fma_f32 v[208:209], v[22:23], v[202:203], v[208:209]
	v_pk_mul_f32 v[210:211], v[132:133], v[28:29] op_sel_hi:[1,0]
	v_add_f32_dpp v214, v214, v214 quad_perm:[1,0,3,2] row_mask:0xf bank_mask:0xf bound_ctrl:1
	v_add_f32_e32 v239, v208, v209
	v_pk_mul_f32 v[212:213], v[134:135], v[28:29] op_sel_hi:[1,0]
	v_add_f32_dpp v214, v214, v214 quad_perm:[2,3,0,1] row_mask:0xf bank_mask:0xf bound_ctrl:1
	v_pk_fma_f32 v[210:211], v[22:23], v[124:125], v[210:211]
	v_pk_fma_f32 v[212:213], v[24:25], v[126:127], v[212:213]
	v_add_f32_dpp v214, v214, v214 row_half_mirror row_mask:0xf bank_mask:0xf bound_ctrl:1
	s_nop 1
	v_add_f32_dpp v214, v214, v214 row_mirror row_mask:0xf bank_mask:0xf bound_ctrl:1
	v_pk_fma_f32 v[22:23], v[128:129], v[214:215], v[210:211] op_sel_hi:[1,0,1]
	v_pk_fma_f32 v[24:25], v[130:131], v[214:215], v[212:213] op_sel_hi:[1,0,1]
	s_waitcnt lgkmcnt(6)
	ds_read_b128 v[186:189], v217 offset:36288
	ds_read_b128 v[190:193], v217 offset:36544
	ds_read_b128 v[194:197], v217 offset:36800
	ds_read_b128 v[198:201], v217 offset:37056
	ds_read_b128 v[202:205], v217 offset:37312
	ds_read_b32 v52, v218 offset:36288
	v_pk_mul_f32 v[206:207], v[24:25], v[148:149]
	v_pk_fma_f32 v[206:207], v[22:23], v[146:147], v[206:207]
	v_pk_mul_f32 v[208:209], v[24:25], v[138:139]
	v_add_f32_e32 v214, v206, v207
	v_pk_fma_f32 v[208:209], v[22:23], v[136:137], v[208:209]
	v_pk_mul_f32 v[210:211], v[158:159], v[30:31] op_sel_hi:[1,0]
	v_add_f32_dpp v214, v214, v214 quad_perm:[1,0,3,2] row_mask:0xf bank_mask:0xf bound_ctrl:1
	v_add_f32_e32 v240, v208, v209
	v_pk_mul_f32 v[212:213], v[160:161], v[30:31] op_sel_hi:[1,0]
	v_add_f32_dpp v214, v214, v214 quad_perm:[2,3,0,1] row_mask:0xf bank_mask:0xf bound_ctrl:1
	v_pk_fma_f32 v[210:211], v[22:23], v[150:151], v[210:211]
	v_pk_fma_f32 v[212:213], v[24:25], v[152:153], v[212:213]
	v_add_f32_dpp v214, v214, v214 row_half_mirror row_mask:0xf bank_mask:0xf bound_ctrl:1
	s_nop 1
	v_add_f32_dpp v214, v214, v214 row_mirror row_mask:0xf bank_mask:0xf bound_ctrl:1
	v_pk_fma_f32 v[22:23], v[154:155], v[214:215], v[210:211] op_sel_hi:[1,0,1]
	v_pk_fma_f32 v[24:25], v[156:157], v[214:215], v[212:213] op_sel_hi:[1,0,1]
	s_waitcnt lgkmcnt(6)
; __device__ void phase_scan(int l, unsigned char* lds) {
;     ...
;             for (int t8 = 16; t8 < (jb.nsteps < 32 ? jb.nsteps : 32); t8 += 4) {
; #pragma unroll
;                 for (int u = 0; u < 4; ++u) {
;                     const int tt = t8 + u;
;                     const unsigned char* tb = buf + tt * SC_TOKB + c0 * 4;
;                     const f32x4 a = *(const f32x4*)(tb), w = *(const f32x4*)(tb + 256), b = *(const f32x4*)(tb + 512), k = *(const f32x4*)(tb + 768), r = *(const f32x4*)(tb + 1024);
;                     const float v = *(const float*)(buf + tt * SC_TOKB + 1280 + rl * 4);
;                     const f32x2 a01 = (f32x2){a[0], a[1]}, a23 = (f32x2){a[2], a[3]}, w01 = (f32x2){w[0], w[1]}, w23 = (f32x2){w[2], w[3]}, b01 = (f32x2){b[0], b[1]}, b23 = (f32x2){b[2], b[3]};
;                     const f32x2 k01 = (f32x2){k[0], k[1]}, k23 = (f32x2){k[2], k[3]}, r01 = (f32x2){r[0], r[1]}, r23 = (f32x2){r[2], r[3]};
;                     const f32x2 pa = s01 * a01 + s23 * a23;
;                     const float sa = allsum16(pa.x + pa.y);
;                     const f32x2 kv01 = k01 * v, kv23 = k23 * v;
;                     s01 = s01 * w01 + (b01 * sa + kv01); s23 = s23 * w23 + (b23 * sa + kv23);
;                     const f32x2 py = s01 * r01 + s23 * r23;
;                     const float y = allsum16(py.x + py.y);
;                     if ((lane & 15) == (tt & 15)) yreg1 = y;
;                 }
	ds_read_b128 v[120:123], v217 offset:37632
	ds_read_b128 v[124:127], v217 offset:37888
	ds_read_b128 v[128:131], v217 offset:38144
	ds_read_b128 v[132:135], v217 offset:38400
	ds_read_b128 v[136:139], v217 offset:38656
	ds_read_b32 v28, v218 offset:37632
	v_pk_mul_f32 v[206:207], v[24:25], v[34:35]
	v_pk_fma_f32 v[206:207], v[22:23], v[32:33], v[206:207]
	v_pk_mul_f32 v[208:209], v[24:25], v[164:165]
	v_add_f32_e32 v214, v206, v207
	v_pk_fma_f32 v[208:209], v[22:23], v[162:163], v[208:209]
	v_pk_mul_f32 v[210:211], v[44:45], v[92:93] op_sel_hi:[1,0]
	v_add_f32_dpp v214, v214, v214 quad_perm:[1,0,3,2] row_mask:0xf bank_mask:0xf bound_ctrl:1
	v_add_f32_e32 v241, v208, v209
	v_pk_mul_f32 v[212:213], v[46:47], v[92:93] op_sel_hi:[1,0]
	v_add_f32_dpp v214, v214, v214 quad_perm:[2,3,0,1] row_mask:0xf bank_mask:0xf bound_ctrl:1
	v_pk_fma_f32 v[210:211], v[22:23], v[36:37], v[210:211]
	v_pk_fma_f32 v[212:213], v[24:25], v[38:39], v[212:213]
	v_add_f32_dpp v214, v214, v214 row_half_mirror row_mask:0xf bank_mask:0xf bound_ctrl:1
	s_nop 1
	v_add_f32_dpp v214, v214, v214 row_mirror row_mask:0xf bank_mask:0xf bound_ctrl:1
	v_pk_fma_f32 v[22:23], v[40:41], v[214:215], v[210:211] op_sel_hi:[1,0,1]
	v_pk_fma_f32 v[24:25], v[42:43], v[214:215], v[212:213] op_sel_hi:[1,0,1]
	s_waitcnt lgkmcnt(6)
	ds_read_b128 v[146:149], v217 offset:38976
	ds_read_b128 v[150:153], v217 offset:39232
	ds_read_b128 v[154:157], v217 offset:39488
	ds_read_b128 v[158:161], v217 offset:39744
	ds_read_b128 v[162:165], v217 offset:40000
	ds_read_b32 v30, v218 offset:38976
	v_pk_mul_f32 v[206:207], v[24:25], v[188:189]
	v_pk_fma_f32 v[206:207], v[22:23], v[186:187], v[206:207]
	v_pk_mul_f32 v[208:209], v[24:25], v[50:51]
	v_add_f32_e32 v214, v206, v207
	v_pk_fma_f32 v[208:209], v[22:23], v[48:49], v[208:209]
	v_pk_mul_f32 v[210:211], v[198:199], v[52:53] op_sel_hi:[1,0]
	v_add_f32_dpp v214, v214, v214 quad_perm:[1,0,3,2] row_mask:0xf bank_mask:0xf bound_ctrl:1
	v_add_f32_e32 v242, v208, v209
	v_pk_mul_f32 v[212:213], v[200:201], v[52:53] op_sel_hi:[1,0]
	v_add_f32_dpp v214, v214, v214 quad_perm:[2,3,0,1] row_mask:0xf bank_mask:0xf bound_ctrl:1
	v_pk_fma_f32 v[210:211], v[22:23], v[190:191], v[210:211]
	v_pk_fma_f32 v[212:213], v[24:25], v[192:193], v[212:213]
	v_add_f32_dpp v214, v214, v214 row_half_mirror row_mask:0xf bank_mask:0xf bound_ctrl:1
	s_nop 1
	v_add_f32_dpp v214, v214, v214 row_mirror row_mask:0xf bank_mask:0xf bound_ctrl:1
	v_pk_fma_f32 v[22:23], v[194:195], v[214:215], v[210:211] op_sel_hi:[1,0,1]
	v_pk_fma_f32 v[24:25], v[196:197], v[214:215], v[212:213] op_sel_hi:[1,0,1]
	s_waitcnt lgkmcnt(6)
	ds_read_b128 v[32:35], v217 offset:40320
	ds_read_b128 v[36:39], v217 offset:40576
	ds_read_b128 v[40:43], v217 offset:40832
	ds_read_b128 v[44:47], v217 offset:41088
	ds_read_b128 v[48:51], v217 offset:41344
	ds_read_b32 v92, v218 offset:40320
	v_pk_mul_f32 v[206:207], v[24:25], v[122:123]
	v_pk_fma_f32 v[206:207], v[22:23], v[120:121], v[206:207]
	v_pk_mul_f32 v[208:209], v[24:25], v[204:205]
	v_add_f32_e32 v214, v206, v207
	v_pk_fma_f32 v[208:209], v[22:23], v[202:203], v[208:209]
	v_pk_mul_f32 v[210:211], v[132:133], v[28:29] op_sel_hi:[1,0]
	v_add_f32_dpp v214, v214, v214 quad_perm:[1,0,3,2] row_mask:0xf bank_mask:0xf bound_ctrl:1
	v_add_f32_e32 v243, v208, v209
	v_pk_mul_f32 v[212:213], v[134:135], v[28:29] op_sel_hi:[1,0]
	v_add_f32_dpp v214, v214, v214 quad_perm:[2,3,0,1] row_mask:0xf bank_mask:0xf bound_ctrl:1
	v_pk_fma_f32 v[210:211], v[22:23], v[124:125], v[210:211]
	v_pk_fma_f32 v[212:213], v[24:25], v[126:127], v[212:213]
	v_add_f32_dpp v214, v214, v214 row_half_mirror row_mask:0xf bank_mask:0xf bound_ctrl:1
	s_nop 1
	v_add_f32_dpp v214, v214, v214 row_mirror row_mask:0xf bank_mask:0xf bound_ctrl:1
	v_pk_fma_f32 v[22:23], v[128:129], v[214:215], v[210:211] op_sel_hi:[1,0,1]
	v_pk_fma_f32 v[24:25], v[130:131], v[214:215], v[212:213] op_sel_hi:[1,0,1]
	s_waitcnt lgkmcnt(6)
	ds_read_b128 v[186:189], v217 offset:41664
	ds_read_b128 v[190:193], v217 offset:41920
	ds_read_b128 v[194:197], v217 offset:42176
	ds_read_b128 v[198:201], v217 offset:42432
	ds_read_b128 v[202:205], v217 offset:42688
	ds_read_b32 v52, v218 offset:41664
	v_pk_mul_f32 v[206:207], v[24:25], v[148:149]
	v_pk_fma_f32 v[206:207], v[22:23], v[146:147], v[206:207]
	v_pk_mul_f32 v[208:209], v[24:25], v[138:139]
	v_add_f32_e32 v214, v206, v207
	v_pk_fma_f32 v[208:209], v[22:23], v[136:137], v[208:209]
	v_pk_mul_f32 v[210:211], v[158:159], v[30:31] op_sel_hi:[1,0]
	v_add_f32_dpp v214, v214, v214 quad_perm:[1,0,3,2] row_mask:0xf bank_mask:0xf bound_ctrl:1
	v_add_f32_e32 v244, v208, v209
	v_pk_mul_f32 v[212:213], v[160:161], v[30:31] op_sel_hi:[1,0]
	v_add_f32_dpp v214, v214, v214 quad_perm:[2,3,0,1] row_mask:0xf bank_mask:0xf bound_ctrl:1
	v_pk_fma_f32 v[210:211], v[22:23], v[150:151], v[210:211]
	v_pk_fma_f32 v[212:213], v[24:25], v[152:153], v[212:213]
	v_add_f32_dpp v214, v214, v214 row_half_mirror row_mask:0xf bank_mask:0xf bound_ctrl:1
	s_nop 1
	v_add_f32_dpp v214, v214, v214 row_mirror row_mask:0xf bank_mask:0xf bound_ctrl:1
	v_pk_fma_f32 v[22:23], v[154:155], v[214:215], v[210:211] op_sel_hi:[1,0,1]
	v_pk_fma_f32 v[24:25], v[156:157], v[214:215], v[212:213] op_sel_hi:[1,0,1]
	s_waitcnt lgkmcnt(6)
; __device__ __forceinline__ bf16_t f2bf(float f) { return (bf16_t)(pk2(f, 0.f) & 0xffffu); }
; __device__ void phase_scan(int l, unsigned char* lds) {
;     ...
;             for (int t8 = 16; t8 < (jb.nsteps < 32 ? jb.nsteps : 32); t8 += 4) {
; #pragma unroll
;                 for (int u = 0; u < 4; ++u) {
;                     const int tt = t8 + u;
;                     const unsigned char* tb = buf + tt * SC_TOKB + c0 * 4;
;                     const f32x4 a = *(const f32x4*)(tb), w = *(const f32x4*)(tb + 256), b = *(const f32x4*)(tb + 512), k = *(const f32x4*)(tb + 768), r = *(const f32x4*)(tb + 1024);
;                     const float v = *(const float*)(buf + tt * SC_TOKB + 1280 + rl * 4);
;                     const f32x2 a01 = (f32x2){a[0], a[1]}, a23 = (f32x2){a[2], a[3]}, w01 = (f32x2){w[0], w[1]}, w23 = (f32x2){w[2], w[3]}, b01 = (f32x2){b[0], b[1]}, b23 = (f32x2){b[2], b[3]};
;                     const f32x2 k01 = (f32x2){k[0], k[1]}, k23 = (f32x2){k[2], k[3]}, r01 = (f32x2){r[0], r[1]}, r23 = (f32x2){r[2], r[3]};
;                     const f32x2 pa = s01 * a01 + s23 * a23;
;                     const float sa = allsum16(pa.x + pa.y);
;                     const f32x2 kv01 = k01 * v, kv23 = k23 * v;
;                     s01 = s01 * w01 + (b01 * sa + kv01); s23 = s23 * w23 + (b23 * sa + kv23);
;                     const f32x2 py = s01 * r01 + s23 * r23;
;                     const float y = allsum16(py.x + py.y);
;                     if ((lane & 15) == (tt & 15)) yreg1 = y;
;                 }
;             }
;             if ((lane & 15) < jb.nsteps) ybuf[(size_t)(jb.tok0 + (lane & 15)) * 512 + jb.h * 64 + row] = f2bf(yreg0);
;             if (16 + (lane & 15) < jb.nsteps) ybuf[(size_t)(jb.tok0 + 16 + (lane & 15)) * 512 + jb.h * 64 + row] = f2bf(yreg1);
	v_pk_mul_f32 v[206:207], v[24:25], v[34:35]
	v_pk_fma_f32 v[206:207], v[22:23], v[32:33], v[206:207]
	v_pk_mul_f32 v[208:209], v[24:25], v[164:165]
	v_add_f32_e32 v214, v206, v207
	v_pk_fma_f32 v[208:209], v[22:23], v[162:163], v[208:209]
	v_pk_mul_f32 v[210:211], v[44:45], v[92:93] op_sel_hi:[1,0]
	v_add_f32_dpp v214, v214, v214 quad_perm:[1,0,3,2] row_mask:0xf bank_mask:0xf bound_ctrl:1
	v_add_f32_e32 v245, v208, v209
	v_pk_mul_f32 v[212:213], v[46:47], v[92:93] op_sel_hi:[1,0]
	v_add_f32_dpp v214, v214, v214 quad_perm:[2,3,0,1] row_mask:0xf bank_mask:0xf bound_ctrl:1
	v_pk_fma_f32 v[210:211], v[22:23], v[36:37], v[210:211]
	v_pk_fma_f32 v[212:213], v[24:25], v[38:39], v[212:213]
	v_add_f32_dpp v214, v214, v214 row_half_mirror row_mask:0xf bank_mask:0xf bound_ctrl:1
	s_nop 1
	v_add_f32_dpp v214, v214, v214 row_mirror row_mask:0xf bank_mask:0xf bound_ctrl:1
	v_pk_fma_f32 v[22:23], v[40:41], v[214:215], v[210:211] op_sel_hi:[1,0,1]
	v_pk_fma_f32 v[24:25], v[42:43], v[214:215], v[212:213] op_sel_hi:[1,0,1]
	s_waitcnt lgkmcnt(0)
	v_pk_mul_f32 v[206:207], v[24:25], v[188:189]
	v_pk_fma_f32 v[206:207], v[22:23], v[186:187], v[206:207]
	v_pk_mul_f32 v[208:209], v[24:25], v[50:51]
	v_add_f32_e32 v214, v206, v207
	v_pk_fma_f32 v[208:209], v[22:23], v[48:49], v[208:209]
	v_pk_mul_f32 v[210:211], v[198:199], v[52:53] op_sel_hi:[1,0]
	v_add_f32_dpp v214, v214, v214 quad_perm:[1,0,3,2] row_mask:0xf bank_mask:0xf bound_ctrl:1
	v_add_f32_e32 v246, v208, v209
	v_pk_mul_f32 v[212:213], v[200:201], v[52:53] op_sel_hi:[1,0]
	v_add_f32_dpp v214, v214, v214 quad_perm:[2,3,0,1] row_mask:0xf bank_mask:0xf bound_ctrl:1
	v_pk_fma_f32 v[210:211], v[22:23], v[190:191], v[210:211]
	v_pk_fma_f32 v[212:213], v[24:25], v[192:193], v[212:213]
	v_add_f32_dpp v214, v214, v214 row_half_mirror row_mask:0xf bank_mask:0xf bound_ctrl:1
	s_nop 1
	v_add_f32_dpp v214, v214, v214 row_mirror row_mask:0xf bank_mask:0xf bound_ctrl:1
	v_pk_fma_f32 v[22:23], v[194:195], v[214:215], v[210:211] op_sel_hi:[1,0,1]
	v_pk_fma_f32 v[24:25], v[196:197], v[214:215], v[212:213] op_sel_hi:[1,0,1]
	v_pk_mul_f32 v[208:209], v[24:25], v[204:205]
	v_pk_fma_f32 v[208:209], v[22:23], v[202:203], v[208:209]
	v_add_f32_e32 v247, v208, v209
	s_mov_b32 s98, 0xaaaaaaaa
	s_mov_b32 s99, 0xaaaaaaaa
	v_cndmask_b32_e64 v249, v233, v232, s[98:99]
	v_cndmask_b32_e64 v232, v232, v233, s[98:99]
	v_cndmask_b32_e64 v251, v235, v234, s[98:99]
	v_cndmask_b32_e64 v234, v234, v235, s[98:99]
	v_add_f32_dpp v232, v249, v232 quad_perm:[1,0,3,2] row_mask:0xf bank_mask:0xf bound_ctrl:1
	v_cndmask_b32_e64 v249, v237, v236, s[98:99]
	v_cndmask_b32_e64 v236, v236, v237, s[98:99]
	v_add_f32_dpp v234, v251, v234 quad_perm:[1,0,3,2] row_mask:0xf bank_mask:0xf bound_ctrl:1
	v_cndmask_b32_e64 v251, v239, v238, s[98:99]
	v_cndmask_b32_e64 v238, v238, v239, s[98:99]
	v_add_f32_dpp v236, v249, v236 quad_perm:[1,0,3,2] row_mask:0xf bank_mask:0xf bound_ctrl:1
	v_cndmask_b32_e64 v249, v241, v240, s[98:99]
	v_cndmask_b32_e64 v240, v240, v241, s[98:99]
	v_add_f32_dpp v238, v251, v238 quad_perm:[1,0,3,2] row_mask:0xf bank_mask:0xf bound_ctrl:1
	v_cndmask_b32_e64 v251, v243, v242, s[98:99]
	v_cndmask_b32_e64 v242, v242, v243, s[98:99]
	v_add_f32_dpp v240, v249, v240 quad_perm:[1,0,3,2] row_mask:0xf bank_mask:0xf bound_ctrl:1
	v_cndmask_b32_e64 v249, v245, v244, s[98:99]
	v_cndmask_b32_e64 v244, v244, v245, s[98:99]
	v_add_f32_dpp v242, v251, v242 quad_perm:[1,0,3,2] row_mask:0xf bank_mask:0xf bound_ctrl:1
	v_cndmask_b32_e64 v251, v247, v246, s[98:99]
	v_cndmask_b32_e64 v246, v246, v247, s[98:99]
	v_add_f32_dpp v244, v249, v244 quad_perm:[1,0,3,2] row_mask:0xf bank_mask:0xf bound_ctrl:1
	s_nop 1
	v_add_f32_dpp v246, v251, v246 quad_perm:[1,0,3,2] row_mask:0xf bank_mask:0xf bound_ctrl:1
	s_mov_b32 s98, 0xcccccccc
	s_mov_b32 s99, 0xcccccccc
	v_cndmask_b32_e64 v249, v234, v232, s[98:99]
	v_cndmask_b32_e64 v232, v232, v234, s[98:99]
	v_cndmask_b32_e64 v251, v238, v236, s[98:99]
	v_cndmask_b32_e64 v236, v236, v238, s[98:99]
	v_add_f32_dpp v232, v249, v232 quad_perm:[2,3,0,1] row_mask:0xf bank_mask:0xf bound_ctrl:1
	v_cndmask_b32_e64 v249, v242, v240, s[98:99]
	v_cndmask_b32_e64 v240, v240, v242, s[98:99]
	v_add_f32_dpp v236, v251, v236 quad_perm:[2,3,0,1] row_mask:0xf bank_mask:0xf bound_ctrl:1
	v_cndmask_b32_e64 v251, v246, v244, s[98:99]
	v_cndmask_b32_e64 v244, v244, v246, s[98:99]
	v_add_f32_dpp v240, v249, v240 quad_perm:[2,3,0,1] row_mask:0xf bank_mask:0xf bound_ctrl:1
	s_nop 1
	v_add_f32_dpp v244, v251, v244 quad_perm:[2,3,0,1] row_mask:0xf bank_mask:0xf bound_ctrl:1
	s_mov_b32 s98, 0xf0f0f0f0
	s_mov_b32 s99, 0xf0f0f0f0
	v_cndmask_b32_e64 v249, v236, v232, s[98:99]
	v_cndmask_b32_e64 v232, v232, v236, s[98:99]
	v_cndmask_b32_e64 v251, v244, v240, s[98:99]
	v_cndmask_b32_e64 v240, v240, v244, s[98:99]
	v_add_f32_dpp v232, v249, v232 row_shr:4 row_mask:0xf bank_mask:0xa
	v_add_f32_dpp v232, v249, v232 row_shl:4 row_mask:0xf bank_mask:0x5
	s_nop 1
	v_add_f32_dpp v240, v251, v240 row_shr:4 row_mask:0xf bank_mask:0xa
	v_add_f32_dpp v240, v251, v240 row_shl:4 row_mask:0xf bank_mask:0x5
	s_mov_b32 s98, 0xff00ff00
	s_mov_b32 s99, 0xff00ff00
	v_cndmask_b32_e64 v249, v240, v232, s[98:99]
	v_cndmask_b32_e64 v232, v232, v240, s[98:99]
	s_nop 1
	v_add_f32_dpp v232, v249, v232 row_ror:8 row_mask:0xf bank_mask:0xf bound_ctrl:1
	v_mov_b32_e32 v26, v232
	s_branch .LBB0_1678

; __global__ __launch_bounds__(512, 2) void mega_kernel(Params P) {
	.amdhsa_kernel _Z11mega_kernel6Params
		.amdhsa_group_segment_fixed_size 0
		.amdhsa_private_segment_fixed_size 0
		.amdhsa_kernarg_size 616
		.amdhsa_user_sgpr_count 2
		.amdhsa_user_sgpr_dispatch_ptr 0
		.amdhsa_user_sgpr_queue_ptr 0
		.amdhsa_user_sgpr_kernarg_segment_ptr 1
		.amdhsa_user_sgpr_dispatch_id 0
		.amdhsa_user_sgpr_kernarg_preload_length 0
		.amdhsa_user_sgpr_kernarg_preload_offset 0
		.amdhsa_user_sgpr_private_segment_size 0
		.amdhsa_uses_dynamic_stack 0
		.amdhsa_enable_private_segment 0
		.amdhsa_system_sgpr_workgroup_id_x 1
		.amdhsa_system_sgpr_workgroup_id_y 0
		.amdhsa_system_sgpr_workgroup_id_z 0
		.amdhsa_system_sgpr_workgroup_info 0
		.amdhsa_system_vgpr_workitem_id 2
		.amdhsa_next_free_vgpr 256
		.amdhsa_next_free_sgpr 100
		.amdhsa_accum_offset 256
		.amdhsa_reserve_vcc 1
		.amdhsa_float_round_mode_32 0
		.amdhsa_float_round_mode_16_64 0
		.amdhsa_float_denorm_mode_32 3
		.amdhsa_float_denorm_mode_16_64 3
		.amdhsa_dx10_clamp 1
		.amdhsa_ieee_mode 1
		.amdhsa_fp16_overflow 0
		.amdhsa_tg_split 0
		.amdhsa_exception_fp_ieee_invalid_op 0
		.amdhsa_exception_fp_denorm_src 0
		.amdhsa_exception_fp_ieee_div_zero 0
		.amdhsa_exception_fp_ieee_overflow 0
		.amdhsa_exception_fp_ieee_underflow 0
		.amdhsa_exception_fp_ieee_inexact 0
		.amdhsa_exception_int_div_zero 0
	.end_amdhsa_kernel

; __global__ __launch_bounds__(512, 2) void mega_kernel(Params P) {
amdhsa.kernels:
  - .agpr_count:     0
    .args:
      - .offset:         0
        .size:           360
        .value_kind:     by_value
      - .offset:         360
        .size:           4
        .value_kind:     hidden_block_count_x
      - .offset:         364
        .size:           4
        .value_kind:     hidden_block_count_y
      - .offset:         368
        .size:           4
        .value_kind:     hidden_block_count_z
      - .offset:         372
        .size:           2
        .value_kind:     hidden_group_size_x
      - .offset:         374
        .size:           2
        .value_kind:     hidden_group_size_y
      - .offset:         376
        .size:           2
        .value_kind:     hidden_group_size_z
      - .offset:         378
        .size:           2
        .value_kind:     hidden_remainder_x
      - .offset:         380
        .size:           2
        .value_kind:     hidden_remainder_y
      - .offset:         382
        .size:           2
        .value_kind:     hidden_remainder_z
      - .offset:         400
        .size:           8
        .value_kind:     hidden_global_offset_x
      - .offset:         408
        .size:           8
        .value_kind:     hidden_global_offset_y
      - .offset:         416
        .size:           8
        .value_kind:     hidden_global_offset_z
      - .offset:         424
        .size:           2
        .value_kind:     hidden_grid_dims
      - .offset:         448
        .size:           8
        .value_kind:     hidden_multigrid_sync_arg
      - .offset:         480
        .size:           4
        .value_kind:     hidden_dynamic_lds_size
    .group_segment_fixed_size: 0
    .kernarg_segment_align: 8
    .kernarg_segment_size: 616
    .language:       OpenCL C
    .language_version:
      - 2
      - 0
    .max_flat_workgroup_size: 512
    .name:           _Z11mega_kernel6Params
    .private_segment_fixed_size: 0
    .sgpr_count:     106
    .sgpr_spill_count: 10
    .symbol:         _Z11mega_kernel6Params.kd
    .uniform_work_group_size: 1
    .uses_dynamic_stack: false
    .vgpr_count:     256
    .vgpr_spill_count: 0
    .wavefront_size: 64
